# v48 + nt (streaming) cache policy on the once-read/once-written traffic of the idle and S5 roles that run beside the GDN/GLA scans, so they stop evicting the warmed scan operands from L2
# speedup vs baseline: 1.0066x; 1.0041x over previous
; __device__ __forceinline__ void ada_gemv(const Ctx& F, const LAS float* sc, int layer, int gw, int NGW) {
;     ...
;     for (int task = gw; task < 192 * 8; task += NGW) {
;         const int kp = task & 7, cb = task >> 3;
;         const float* W = P.in[layer ? 27 : 2] + (size_t)(kp * 256) * 12288 + cb * 64 + F.lane;
;         float acc = 0.f;
; #pragma unroll 16
;         for (int k = 0; k < 256; ++k) acc += sc[kp * 256 + k] * W[(size_t)k * 12288];
;         MODP[(size_t)(kp * 2 + layer) * 12288 + cb * 64 + F.lane] = acc;
;     }
.LBB0_897:
	v_lshl_add_u64 v[8:9], v[4:5], 0, s[0:1]
	v_add_co_u32_e32 v10, vcc, 0xc000, v8
	global_load_dword v7, v[8:9], off nt
	s_nop 0
	v_addc_co_u32_e32 v11, vcc, 0, v9, vcc
	v_add_co_u32_e32 v12, vcc, s5, v8
	global_load_dword v24, v[10:11], off nt
	s_nop 0
	v_addc_co_u32_e32 v13, vcc, 0, v9, vcc
	v_add_co_u32_e32 v10, vcc, 0x24000, v8
	v_mov_b32_e32 v20, s8
	s_nop 0
	v_addc_co_u32_e32 v11, vcc, 0, v9, vcc
	v_add_co_u32_e32 v14, vcc, 0x30000, v8
	global_load_dword v25, v[12:13], off nt
	global_load_dword v26, v[10:11], off nt
	v_addc_co_u32_e32 v15, vcc, 0, v9, vcc
	v_add_co_u32_e32 v10, vcc, 0x3c000, v8
	s_add_u32 s0, s0, 0xc0000
	s_nop 0
	v_addc_co_u32_e32 v11, vcc, 0, v9, vcc
	v_add_co_u32_e32 v12, vcc, 0x48000, v8
	global_load_dword v27, v[14:15], off nt
	global_load_dword v28, v[10:11], off nt
	v_addc_co_u32_e32 v13, vcc, 0, v9, vcc
	v_add_co_u32_e32 v10, vcc, 0x54000, v8
	s_addc_u32 s1, s1, 0
	s_nop 0
	v_addc_co_u32_e32 v11, vcc, 0, v9, vcc
	v_add_co_u32_e32 v14, vcc, 0x60000, v8
	global_load_dword v29, v[12:13], off nt
	global_load_dword v30, v[10:11], off nt
	v_addc_co_u32_e32 v15, vcc, 0, v9, vcc
	v_add_co_u32_e32 v10, vcc, 0x6c000, v8
	s_add_i32 s8, s8, 64
	s_nop 0
	v_addc_co_u32_e32 v11, vcc, 0, v9, vcc
	v_add_co_u32_e32 v12, vcc, 0x78000, v8
	global_load_dword v31, v[14:15], off nt
	global_load_dword v32, v[10:11], off nt
	v_addc_co_u32_e32 v13, vcc, 0, v9, vcc
	v_add_co_u32_e32 v10, vcc, 0x84000, v8
	s_cmp_eq_u32 s0, 0xc00000
	s_nop 0
	v_addc_co_u32_e32 v11, vcc, 0, v9, vcc
	v_add_co_u32_e32 v14, vcc, 0x90000, v8
	global_load_dword v33, v[12:13], off nt
	global_load_dword v34, v[10:11], off nt
	v_addc_co_u32_e32 v15, vcc, 0, v9, vcc
	v_add_co_u32_e32 v10, vcc, 0x9c000, v8
	s_nop 1
	v_addc_co_u32_e32 v11, vcc, 0, v9, vcc
	v_add_co_u32_e32 v12, vcc, 0xa8000, v8
	global_load_dword v35, v[14:15], off nt
	global_load_dword v36, v[10:11], off nt
	v_addc_co_u32_e32 v13, vcc, 0, v9, vcc
	v_add_co_u32_e32 v8, vcc, 0xb4000, v8
	s_nop 1
	v_addc_co_u32_e32 v9, vcc, 0, v9, vcc
	global_load_dword v37, v[12:13], off nt
	global_load_dword v38, v[8:9], off nt
	ds_read_b128 v[8:11], v20
	ds_read_b128 v[12:15], v20 offset:16
	ds_read_b128 v[16:19], v20 offset:32
	ds_read_b128 v[20:23], v20 offset:48
	s_waitcnt vmcnt(15) lgkmcnt(3)
	v_fmac_f32_e32 v6, v8, v7
	s_waitcnt vmcnt(14)
	v_fmac_f32_e32 v6, v9, v24
	s_waitcnt vmcnt(13)
	v_fmac_f32_e32 v6, v10, v25
	s_waitcnt vmcnt(12)
	v_fmac_f32_e32 v6, v11, v26
	s_waitcnt vmcnt(11) lgkmcnt(2)
	v_fmac_f32_e32 v6, v12, v27
	s_waitcnt vmcnt(10)
	v_fmac_f32_e32 v6, v13, v28
	s_waitcnt vmcnt(9)
	v_fmac_f32_e32 v6, v14, v29
	s_waitcnt vmcnt(8)
	v_fmac_f32_e32 v6, v15, v30
	s_waitcnt vmcnt(7) lgkmcnt(1)
	v_fmac_f32_e32 v6, v16, v31
	s_waitcnt vmcnt(6)
	v_fmac_f32_e32 v6, v17, v32
	s_waitcnt vmcnt(5)
	v_fmac_f32_e32 v6, v18, v33
	s_waitcnt vmcnt(4)
	v_fmac_f32_e32 v6, v19, v34
	s_waitcnt vmcnt(3) lgkmcnt(0)
	v_fmac_f32_e32 v6, v20, v35
	s_waitcnt vmcnt(2)
	v_fmac_f32_e32 v6, v21, v36
	s_waitcnt vmcnt(1)
	v_fmac_f32_e32 v6, v22, v37
	s_waitcnt vmcnt(0)
	v_fmac_f32_e32 v6, v23, v38
	s_cbranch_scc0 .LBB0_897
	s_lshl_b32 s0, s3, 3
	s_andn2_b32 s0, s0, 63
	s_ashr_i32 s1, s0, 31
	v_lshl_add_u64 v[4:5], s[0:1], 2, v[0:1]
	s_add_i32 s0, s3, 0x300
	s_addk_i32 s7, 0x1800
	s_cmpk_gt_i32 s3, 0x2ff
	s_mov_b32 s3, s0
	global_store_dword v[4:5], v6, off
	s_cbranch_scc0 .LBB0_896

; __device__ __forceinline__ void transpose_item(const float* W, int K, int Nsrc, int c0, bf16_t* WT, int mode, LAS float* scr, int kb, int nb, int lane) {
;     ...
;     for (int i = 0; i < 32; ++i) { const int kk = 2 * i + (lane >> 5); tv[i] = W[(size_t)(k0 + kk) * Nsrc + c0 + n0 + (lane & 31)]; }
; #pragma unroll
;     for (int i = 0; i < 32; ++i) { const int kk = 2 * i + (lane >> 5); scr[kk * 33 + (lane & 31)] = tv[i]; }
.LBB0_900:
	s_addk_i32 s5, 0x300
	s_and_b32 s12, s5, 0x7fffffc0
	s_and_b32 s9, s6, 0x7e0
	v_or_b32_e32 v2, s12, v70
	v_mov_b32_e32 v11, v3
	v_mov_b32_e32 v13, v3
	v_mov_b32_e32 v15, v3
	v_mov_b32_e32 v17, v3
	v_mov_b32_e32 v19, v3
	v_mov_b32_e32 v21, v3
	v_mov_b32_e32 v23, v3
	v_mov_b32_e32 v25, v3
	v_mov_b32_e32 v33, v3
	v_mov_b32_e32 v35, v3
	v_mov_b32_e32 v37, v3
	v_mov_b32_e32 v39, v3
	v_mov_b32_e32 v41, v3
	v_mov_b32_e32 v43, v3
	v_mov_b32_e32 v45, v3
	v_mov_b32_e32 v47, v3
	s_lshl_b32 s0, s9, 2
	v_or_b32_e32 v10, 2, v2
	v_or_b32_e32 v12, 4, v2
	v_or_b32_e32 v14, 6, v2
	v_or_b32_e32 v16, 8, v2
	v_or_b32_e32 v18, 10, v2
	v_or_b32_e32 v20, 12, v2
	v_or_b32_e32 v22, 14, v2
	v_or_b32_e32 v24, 16, v2
	v_or_b32_e32 v32, 24, v2
	v_or_b32_e32 v34, 26, v2
	v_or_b32_e32 v36, 28, v2
	v_or_b32_e32 v38, 30, v2
	v_or_b32_e32 v40, 32, v2
	v_or_b32_e32 v42, 34, v2
	v_or_b32_e32 v44, 36, v2
	v_or_b32_e32 v46, 38, v2
	v_mov_b32_e32 v27, v3
	v_mov_b32_e32 v29, v3
	v_mov_b32_e32 v31, v3
	v_mov_b32_e32 v49, v3
	v_mov_b32_e32 v51, v3
	v_mov_b32_e32 v53, v3
	v_mov_b32_e32 v55, v3
	v_mov_b32_e32 v57, v3
	v_mov_b32_e32 v59, v3
	v_mov_b32_e32 v61, v3
	v_mov_b32_e32 v63, v3
	v_mov_b32_e32 v65, v3
	v_mov_b32_e32 v79, v3
	v_mov_b32_e32 v81, v3
	v_lshl_add_u64 v[82:83], v[6:7], 0, s[0:1]
	v_lshlrev_b64 v[84:85], 13, v[2:3]
	v_or_b32_e32 v26, 18, v2
	v_or_b32_e32 v28, 20, v2
	v_or_b32_e32 v30, 22, v2
	v_or_b32_e32 v48, 40, v2
	v_or_b32_e32 v50, 42, v2
	v_or_b32_e32 v52, 44, v2
	v_or_b32_e32 v54, 46, v2
	v_or_b32_e32 v56, 48, v2
	v_or_b32_e32 v58, 50, v2
	v_or_b32_e32 v60, 52, v2
	v_or_b32_e32 v62, 54, v2
	v_or_b32_e32 v64, 56, v2
	v_or_b32_e32 v78, 58, v2
	v_or_b32_e32 v80, 60, v2
	v_or_b32_e32 v2, 62, v2
	v_lshlrev_b64 v[10:11], 13, v[10:11]
	v_lshlrev_b64 v[12:13], 13, v[12:13]
	v_lshlrev_b64 v[14:15], 13, v[14:15]
	v_lshlrev_b64 v[16:17], 13, v[16:17]
	v_lshlrev_b64 v[18:19], 13, v[18:19]
	v_lshlrev_b64 v[20:21], 13, v[20:21]
	v_lshlrev_b64 v[22:23], 13, v[22:23]
	v_lshlrev_b64 v[24:25], 13, v[24:25]
	v_lshlrev_b64 v[32:33], 13, v[32:33]
	v_lshlrev_b64 v[34:35], 13, v[34:35]
	v_lshlrev_b64 v[36:37], 13, v[36:37]
	v_lshlrev_b64 v[38:39], 13, v[38:39]
	v_lshlrev_b64 v[40:41], 13, v[40:41]
	v_lshlrev_b64 v[42:43], 13, v[42:43]
	v_lshlrev_b64 v[44:45], 13, v[44:45]
	v_lshlrev_b64 v[46:47], 13, v[46:47]
	v_lshl_add_u64 v[84:85], v[82:83], 0, v[84:85]
	v_lshlrev_b64 v[26:27], 13, v[26:27]
	v_lshlrev_b64 v[28:29], 13, v[28:29]
	v_lshlrev_b64 v[30:31], 13, v[30:31]
	v_lshlrev_b64 v[48:49], 13, v[48:49]
	v_lshlrev_b64 v[50:51], 13, v[50:51]
	v_lshlrev_b64 v[52:53], 13, v[52:53]
	v_lshlrev_b64 v[54:55], 13, v[54:55]
	v_lshlrev_b64 v[56:57], 13, v[56:57]
	v_lshlrev_b64 v[58:59], 13, v[58:59]
	v_lshlrev_b64 v[60:61], 13, v[60:61]
	v_lshlrev_b64 v[62:63], 13, v[62:63]
	v_lshlrev_b64 v[64:65], 13, v[64:65]
	v_lshlrev_b64 v[78:79], 13, v[78:79]
	v_lshlrev_b64 v[80:81], 13, v[80:81]
	v_lshlrev_b64 v[88:89], 13, v[2:3]
	v_lshl_add_u64 v[10:11], v[82:83], 0, v[10:11]
	v_lshl_add_u64 v[12:13], v[82:83], 0, v[12:13]
	v_lshl_add_u64 v[14:15], v[82:83], 0, v[14:15]
	v_lshl_add_u64 v[16:17], v[82:83], 0, v[16:17]
	v_lshl_add_u64 v[18:19], v[82:83], 0, v[18:19]
	v_lshl_add_u64 v[20:21], v[82:83], 0, v[20:21]
	v_lshl_add_u64 v[22:23], v[82:83], 0, v[22:23]
	v_lshl_add_u64 v[24:25], v[82:83], 0, v[24:25]
	v_lshl_add_u64 v[32:33], v[82:83], 0, v[32:33]
	v_lshl_add_u64 v[34:35], v[82:83], 0, v[34:35]
	v_lshl_add_u64 v[36:37], v[82:83], 0, v[36:37]
	v_lshl_add_u64 v[38:39], v[82:83], 0, v[38:39]
	v_lshl_add_u64 v[40:41], v[82:83], 0, v[40:41]
	v_lshl_add_u64 v[42:43], v[82:83], 0, v[42:43]
	v_lshl_add_u64 v[44:45], v[82:83], 0, v[44:45]
	v_lshl_add_u64 v[46:47], v[82:83], 0, v[46:47]
	v_lshl_add_u64 v[26:27], v[82:83], 0, v[26:27]
	v_lshl_add_u64 v[28:29], v[82:83], 0, v[28:29]
	v_lshl_add_u64 v[30:31], v[82:83], 0, v[30:31]
	v_lshl_add_u64 v[48:49], v[82:83], 0, v[48:49]
	v_lshl_add_u64 v[50:51], v[82:83], 0, v[50:51]
	v_lshl_add_u64 v[52:53], v[82:83], 0, v[52:53]
	v_lshl_add_u64 v[54:55], v[82:83], 0, v[54:55]
	v_lshl_add_u64 v[56:57], v[82:83], 0, v[56:57]
	v_lshl_add_u64 v[58:59], v[82:83], 0, v[58:59]
	v_lshl_add_u64 v[60:61], v[82:83], 0, v[60:61]
	v_lshl_add_u64 v[62:63], v[82:83], 0, v[62:63]
	v_lshl_add_u64 v[64:65], v[82:83], 0, v[64:65]
	v_lshl_add_u64 v[78:79], v[82:83], 0, v[78:79]
	v_lshl_add_u64 v[80:81], v[82:83], 0, v[80:81]
	v_lshl_add_u64 v[82:83], v[82:83], 0, v[88:89]
	global_load_dword v84, v[84:85], off nt
	s_nop 0
	global_load_dword v10, v[10:11], off nt
	s_nop 0
	global_load_dword v11, v[12:13], off nt
	s_nop 0
	global_load_dword v12, v[14:15], off nt
	global_load_dword v13, v[16:17], off nt
	s_nop 0
	global_load_dword v14, v[18:19], off nt
	global_load_dword v15, v[20:21], off nt
	global_load_dword v16, v[22:23], off nt
	global_load_dword v17, v[24:25], off nt
	s_nop 0
	global_load_dword v18, v[26:27], off nt
	global_load_dword v19, v[28:29], off nt
	global_load_dword v20, v[30:31], off nt
	global_load_dword v21, v[32:33], off nt
	global_load_dword v22, v[34:35], off nt
	global_load_dword v23, v[36:37], off nt
	global_load_dword v24, v[38:39], off nt
	global_load_dword v25, v[40:41], off nt
	s_nop 0
	global_load_dword v32, v[42:43], off nt
	global_load_dword v33, v[44:45], off nt
	global_load_dword v34, v[46:47], off nt
	global_load_dword v35, v[48:49], off nt
	global_load_dword v36, v[50:51], off nt
	global_load_dword v37, v[52:53], off nt
	global_load_dword v38, v[54:55], off nt
	global_load_dword v39, v[56:57], off nt
	global_load_dword v40, v[58:59], off nt
	global_load_dword v41, v[60:61], off nt
	global_load_dword v42, v[62:63], off nt
	global_load_dword v43, v[64:65], off nt
	global_load_dword v44, v[78:79], off nt
	global_load_dword v45, v[80:81], off nt
	global_load_dword v46, v[82:83], off nt
	v_or_b32_e32 v90, s9, v72
	s_lshl_b32 s0, s12, 1
	s_waitcnt vmcnt(30)
; #define LAS __attribute__((address_space(3)))
; __device__ __forceinline__ unsigned pk2(float lo, float hi) { return f2bf(lo) | (f2bf(hi) << 16); }
; __device__ __forceinline__ void transpose_item(const float* W, int K, int Nsrc, int c0, bf16_t* WT, int mode, LAS float* scr, int kb, int nb, int lane) {
;     ...
;     for (int i = 0; i < 32; ++i) { const int kk = 2 * i + (lane >> 5); scr[kk * 33 + (lane & 31)] = tv[i]; }
;     asm volatile("s_waitcnt lgkmcnt(0)" ::: "memory");
;     const int c = lane & 7;
; #pragma unroll
;     for (int j = 0; j < 4; ++j) { const int n = (lane >> 3) + 8 * j; const LAS float* s = scr + (8 * c) * 33 + n;
;         u32x4 o; o.x = pk2(s[0 * 33], s[1 * 33]); o.y = pk2(s[2 * 33], s[3 * 33]); o.z = pk2(s[4 * 33], s[5 * 33]); o.w = pk2(s[6 * 33], s[7 * 33]);
;         const int nn = n0 + n; const int row = (mode == 0) ? nn : ((nn >> 7) * 256 + (nn & 127) + (mode == 2 ? 128 : 0));
;         *(u32x4*)(WT + (size_t)row * K + k0 + 8 * c) = o; }
;     asm volatile("s_waitcnt lgkmcnt(0)" ::: "memory");
	ds_write2_b32 v71, v84, v10 offset1:66
	s_waitcnt vmcnt(28)
	ds_write2_b32 v71, v11, v12 offset0:132 offset1:198
	s_waitcnt vmcnt(26)
	ds_write2_b32 v1, v13, v14 offset0:8 offset1:74
	s_waitcnt vmcnt(24)
	ds_write2_b32 v1, v15, v16 offset0:140 offset1:206
	s_waitcnt vmcnt(22)
	ds_write2_b32 v5, v17, v18 offset0:16 offset1:82
	s_waitcnt vmcnt(20)
	ds_write2_b32 v5, v19, v20 offset0:148 offset1:214
	s_waitcnt vmcnt(18)
	ds_write2_b32 v66, v21, v22 offset0:24 offset1:90
	s_waitcnt vmcnt(16)
	ds_write2_b32 v66, v23, v24 offset0:156 offset1:222
	s_waitcnt vmcnt(14)
	ds_write2_b32 v67, v25, v32 offset0:32 offset1:98
	s_waitcnt vmcnt(12)
	ds_write2_b32 v67, v33, v34 offset0:164 offset1:230
	s_waitcnt vmcnt(10)
	ds_write2_b32 v68, v35, v36 offset0:40 offset1:106
	s_waitcnt vmcnt(8)
	ds_write2_b32 v68, v37, v38 offset0:172 offset1:238
	s_waitcnt vmcnt(6)
	ds_write2_b32 v69, v39, v40 offset0:48 offset1:114
	s_waitcnt vmcnt(4)
	ds_write2_b32 v69, v41, v42 offset0:180 offset1:246
	s_waitcnt vmcnt(2)
	ds_write2_b32 v77, v43, v44 offset0:56 offset1:122
	s_waitcnt vmcnt(0)
	ds_write2_b32 v77, v45, v46 offset0:188 offset1:254
	v_or_b32_e32 v91, s9, v74
	v_lshl_add_u64 v[86:87], v[8:9], 0, s[0:1]
	v_lshlrev_b32_e32 v2, 12, v90
	s_waitcnt lgkmcnt(0)
	v_or_b32_e32 v92, s9, v75
	v_lshl_add_u64 v[88:89], v[86:87], 0, v[2:3]
	v_lshlrev_b32_e32 v2, 12, v91
	ds_read2_b32 v[10:11], v73 offset0:33 offset1:41
	ds_read2_b32 v[12:13], v73 offset1:8
	ds_read2_b32 v[14:15], v73 offset0:66 offset1:74
	ds_read2_b32 v[16:17], v73 offset0:99 offset1:107
	ds_read2_b32 v[18:19], v73 offset0:132 offset1:140
	ds_read2_b32 v[20:21], v73 offset0:165 offset1:173
	ds_read2_b32 v[22:23], v73 offset0:198 offset1:206
	ds_read2_b32 v[24:25], v73 offset0:231 offset1:239
	ds_read2_b32 v[32:33], v73 offset0:49 offset1:57
	ds_read2_b32 v[34:35], v73 offset0:16 offset1:24
	ds_read2_b32 v[36:37], v73 offset0:82 offset1:90
	ds_read2_b32 v[38:39], v73 offset0:115 offset1:123
	ds_read2_b32 v[40:41], v73 offset0:148 offset1:156
	ds_read2_b32 v[42:43], v73 offset0:181 offset1:189
	ds_read2_b32 v[44:45], v73 offset0:214 offset1:222
	ds_read2_b32 v[46:47], v73 offset0:247 offset1:255
	v_or_b32_e32 v93, s9, v76
	v_lshl_add_u64 v[26:27], v[86:87], 0, v[2:3]
	v_lshlrev_b32_e32 v2, 12, v92
	v_lshl_add_u64 v[28:29], v[86:87], 0, v[2:3]
	v_lshlrev_b32_e32 v2, 12, v93
	v_lshl_add_u64 v[30:31], v[86:87], 0, v[2:3]
	s_waitcnt lgkmcnt(14)
	v_bfe_u32 v2, v12, 16, 1
	s_waitcnt lgkmcnt(13)
	v_bfe_u32 v49, v14, 16, 1
	s_waitcnt lgkmcnt(12)
	v_bfe_u32 v50, v16, 16, 1
	s_waitcnt lgkmcnt(11)
	v_bfe_u32 v51, v18, 16, 1
	s_waitcnt lgkmcnt(10)
	v_bfe_u32 v52, v20, 16, 1
	s_waitcnt lgkmcnt(9)
	v_bfe_u32 v53, v22, 16, 1
	v_bfe_u32 v48, v10, 16, 1
	s_waitcnt lgkmcnt(8)
	v_bfe_u32 v54, v24, 16, 1
	v_bfe_u32 v55, v13, 16, 1
	v_bfe_u32 v56, v11, 16, 1
	v_bfe_u32 v57, v15, 16, 1
	v_bfe_u32 v58, v17, 16, 1
	v_bfe_u32 v59, v19, 16, 1
	v_bfe_u32 v60, v21, 16, 1
	v_bfe_u32 v61, v23, 16, 1
	v_bfe_u32 v62, v25, 16, 1
	s_waitcnt lgkmcnt(6)
	v_bfe_u32 v63, v34, 16, 1
	s_waitcnt lgkmcnt(5)
	v_bfe_u32 v65, v36, 16, 1
	s_waitcnt lgkmcnt(4)
	v_bfe_u32 v78, v38, 16, 1
	s_waitcnt lgkmcnt(3)
	v_bfe_u32 v79, v40, 16, 1
	s_waitcnt lgkmcnt(2)
	v_bfe_u32 v80, v42, 16, 1
	s_waitcnt lgkmcnt(1)
	v_bfe_u32 v81, v44, 16, 1
	v_bfe_u32 v83, v35, 16, 1
	v_bfe_u32 v85, v37, 16, 1
	v_bfe_u32 v87, v41, 16, 1
	v_bfe_u32 v91, v45, 16, 1
	v_add3_u32 v2, v12, v2, s7
	v_add3_u32 v12, v14, v49, s7
	v_add3_u32 v14, v16, v50, s7
	v_add3_u32 v16, v18, v51, s7
	v_add3_u32 v18, v20, v52, s7
	v_add3_u32 v20, v22, v53, s7
	v_bfe_u32 v64, v32, 16, 1
	s_waitcnt lgkmcnt(0)
	v_bfe_u32 v82, v46, 16, 1
	v_bfe_u32 v84, v33, 16, 1
	v_bfe_u32 v86, v39, 16, 1
	v_bfe_u32 v90, v43, 16, 1
	v_bfe_u32 v92, v47, 16, 1
	v_add3_u32 v10, v10, v48, s7
	v_add3_u32 v22, v24, v54, s7
	v_add3_u32 v13, v13, v55, s7
	v_add3_u32 v24, v11, v56, s7
	v_add3_u32 v11, v15, v57, s7
	v_add3_u32 v15, v17, v58, s7
	v_add3_u32 v17, v19, v59, s7
	v_add3_u32 v19, v21, v60, s7
	v_add3_u32 v21, v23, v61, s7
	v_add3_u32 v23, v25, v62, s7
	v_add3_u32 v25, v34, v63, s7
	v_add3_u32 v34, v36, v65, s7
	v_add3_u32 v36, v38, v78, s7
	v_add3_u32 v38, v40, v79, s7
	v_add3_u32 v40, v42, v80, s7
	v_add3_u32 v42, v44, v81, s7
	v_add3_u32 v35, v35, v83, s7
	v_add3_u32 v37, v37, v85, s7
	v_add3_u32 v41, v41, v87, s7
	v_add3_u32 v45, v45, v91, s7
	v_lshrrev_b32_e32 v2, 16, v2
	v_lshrrev_b32_e32 v12, 16, v12
	v_lshrrev_b32_e32 v16, 16, v16
	v_lshrrev_b32_e32 v20, 16, v20
	v_add3_u32 v32, v32, v64, s7
	v_add3_u32 v44, v46, v82, s7
	v_add3_u32 v33, v33, v84, s7
	v_add3_u32 v39, v39, v86, s7
	v_add3_u32 v43, v43, v90, s7
	v_add3_u32 v46, v47, v92, s7
	v_lshrrev_b32_e32 v47, 16, v13
	v_lshrrev_b32_e32 v48, 16, v11
	v_lshrrev_b32_e32 v17, 16, v17
	v_lshrrev_b32_e32 v21, 16, v21
	v_lshrrev_b32_e32 v25, 16, v25
	v_lshrrev_b32_e32 v34, 16, v34
	v_lshrrev_b32_e32 v38, 16, v38
	v_lshrrev_b32_e32 v42, 16, v42
	v_lshrrev_b32_e32 v35, 16, v35
	v_lshrrev_b32_e32 v37, 16, v37
	v_lshrrev_b32_e32 v41, 16, v41
	v_lshrrev_b32_e32 v45, 16, v45
	v_and_or_b32 v10, v10, s8, v2
	v_and_or_b32 v11, v14, s8, v12
	v_and_or_b32 v12, v18, s8, v16
	v_and_or_b32 v13, v22, s8, v20
	v_and_or_b32 v14, v24, s8, v47
	v_and_or_b32 v15, v15, s8, v48
	v_and_or_b32 v16, v19, s8, v17
	v_and_or_b32 v17, v23, s8, v21
	v_and_or_b32 v18, v32, s8, v25
	v_and_or_b32 v19, v36, s8, v34
	v_and_or_b32 v20, v40, s8, v38
	v_and_or_b32 v21, v44, s8, v42
	v_and_or_b32 v22, v33, s8, v35
	v_and_or_b32 v23, v39, s8, v37
	v_and_or_b32 v24, v43, s8, v41
	v_and_or_b32 v25, v46, s8, v45
	global_store_dwordx4 v[88:89], v[10:13], off nt
	global_store_dwordx4 v[26:27], v[14:17], off nt
	global_store_dwordx4 v[28:29], v[18:21], off nt
	global_store_dwordx4 v[30:31], v[22:25], off nt
	s_waitcnt lgkmcnt(0)
	s_addk_i32 s6, 0x6000
	s_cmpk_lt_u32 s5, 0x500
	s_cbranch_scc1 .LBB0_900
	v_mov_b32_e32 v3, 0
	v_lshlrev_b32_e32 v4, 1, v4
	v_mov_b32_e32 v5, v3
	s_add_i32 s5, s4, 0xfffffd00
	v_lshl_add_u64 v[8:9], s[92:93], 0, v[4:5]
	s_mov_b64 s[0:1], 0x5600000
	v_lshl_add_u64 v[8:9], v[8:9], 0, s[0:1]
	s_mul_hi_u32 s0, s5, 0xaaaaaaab
	s_lshr_b32 s0, s0, 9
	v_readlane_b32 s12, v247, 28
	s_mulk_i32 s0, 0x300
	v_lshlrev_b32_e32 v0, 2, v0
	v_mov_b32_e32 v1, v3
	v_readlane_b32 s16, v247, 32
	v_readlane_b32 s17, v247, 33
	s_sub_i32 s1, s5, s0
	s_sub_i32 s0, s4, s0
	v_lshl_add_u64 v[6:7], s[16:17], 0, v[0:1]
	s_add_i32 s4, s0, 0xfffffa00
	s_lshl_b32 s5, s1, 5
	s_mov_b32 s1, 0
	s_movk_i32 s6, 0x7fff
	s_mov_b32 s7, 0xffff0000
	v_readlane_b32 s13, v247, 29
	v_readlane_b32 s14, v247, 30
	v_readlane_b32 s15, v247, 31
	v_readlane_b32 s18, v247, 34
	v_readlane_b32 s19, v247, 35
	v_readlane_b32 s20, v247, 36
	v_readlane_b32 s21, v247, 37
	v_readlane_b32 s22, v247, 38
	v_readlane_b32 s23, v247, 39
	v_readlane_b32 s24, v247, 40
	v_readlane_b32 s25, v247, 41
	v_readlane_b32 s26, v247, 42
	v_readlane_b32 s27, v247, 43
; __device__ __forceinline__ void transpose_item(const float* W, int K, int Nsrc, int c0, bf16_t* WT, int mode, LAS float* scr, int kb, int nb, int lane) {
;     ...
;     for (int i = 0; i < 32; ++i) { const int kk = 2 * i + (lane >> 5); tv[i] = W[(size_t)(k0 + kk) * Nsrc + c0 + n0 + (lane & 31)]; }
; #pragma unroll
;     for (int i = 0; i < 32; ++i) { const int kk = 2 * i + (lane >> 5); scr[kk * 33 + (lane & 31)] = tv[i]; }
.LBB0_902:
	s_addk_i32 s4, 0x300
	s_and_b32 s9, s4, 0x7fffffc0
	s_and_b32 s8, s5, 0x7e0
	v_or_b32_e32 v2, s9, v70
	v_mov_b32_e32 v11, v3
	v_mov_b32_e32 v13, v3
	v_mov_b32_e32 v15, v3
	v_mov_b32_e32 v17, v3
	v_mov_b32_e32 v19, v3
	v_mov_b32_e32 v21, v3
	v_mov_b32_e32 v23, v3
	v_mov_b32_e32 v25, v3
	v_mov_b32_e32 v33, v3
	v_mov_b32_e32 v35, v3
	v_mov_b32_e32 v37, v3
	v_mov_b32_e32 v39, v3
	v_mov_b32_e32 v41, v3
	v_mov_b32_e32 v43, v3
	v_mov_b32_e32 v45, v3
	v_mov_b32_e32 v47, v3
	s_lshl_b32 s0, s8, 2
	v_or_b32_e32 v10, 2, v2
	v_or_b32_e32 v12, 4, v2
	v_or_b32_e32 v14, 6, v2
	v_or_b32_e32 v16, 8, v2
	v_or_b32_e32 v18, 10, v2
	v_or_b32_e32 v20, 12, v2
	v_or_b32_e32 v22, 14, v2
	v_or_b32_e32 v24, 16, v2
	v_or_b32_e32 v32, 24, v2
	v_or_b32_e32 v34, 26, v2
	v_or_b32_e32 v36, 28, v2
	v_or_b32_e32 v38, 30, v2
	v_or_b32_e32 v40, 32, v2
	v_or_b32_e32 v42, 34, v2
	v_or_b32_e32 v44, 36, v2
	v_or_b32_e32 v46, 38, v2
	v_mov_b32_e32 v27, v3
	v_mov_b32_e32 v29, v3
	v_mov_b32_e32 v31, v3
	v_mov_b32_e32 v49, v3
	v_mov_b32_e32 v51, v3
	v_mov_b32_e32 v53, v3
	v_mov_b32_e32 v55, v3
	v_mov_b32_e32 v57, v3
	v_mov_b32_e32 v59, v3
	v_mov_b32_e32 v61, v3
	v_mov_b32_e32 v63, v3
	v_mov_b32_e32 v65, v3
	v_mov_b32_e32 v67, v3
	v_mov_b32_e32 v69, v3
	v_lshl_add_u64 v[78:79], v[6:7], 0, s[0:1]
	v_lshlrev_b64 v[80:81], 13, v[2:3]
	v_or_b32_e32 v26, 18, v2
	v_or_b32_e32 v28, 20, v2
	v_or_b32_e32 v30, 22, v2
	v_or_b32_e32 v48, 40, v2
	v_or_b32_e32 v50, 42, v2
	v_or_b32_e32 v52, 44, v2
	v_or_b32_e32 v54, 46, v2
	v_or_b32_e32 v56, 48, v2
	v_or_b32_e32 v58, 50, v2
	v_or_b32_e32 v60, 52, v2
	v_or_b32_e32 v62, 54, v2
	v_or_b32_e32 v64, 56, v2
	v_or_b32_e32 v66, 58, v2
	v_or_b32_e32 v68, 60, v2
	v_or_b32_e32 v2, 62, v2
	v_lshlrev_b64 v[10:11], 13, v[10:11]
	v_lshlrev_b64 v[12:13], 13, v[12:13]
	v_lshlrev_b64 v[14:15], 13, v[14:15]
	v_lshlrev_b64 v[16:17], 13, v[16:17]
	v_lshlrev_b64 v[18:19], 13, v[18:19]
	v_lshlrev_b64 v[20:21], 13, v[20:21]
	v_lshlrev_b64 v[22:23], 13, v[22:23]
	v_lshlrev_b64 v[24:25], 13, v[24:25]
	v_lshlrev_b64 v[32:33], 13, v[32:33]
	v_lshlrev_b64 v[34:35], 13, v[34:35]
	v_lshlrev_b64 v[36:37], 13, v[36:37]
	v_lshlrev_b64 v[38:39], 13, v[38:39]
	v_lshlrev_b64 v[40:41], 13, v[40:41]
	v_lshlrev_b64 v[42:43], 13, v[42:43]
	v_lshlrev_b64 v[44:45], 13, v[44:45]
	v_lshlrev_b64 v[46:47], 13, v[46:47]
	v_lshl_add_u64 v[80:81], v[78:79], 0, v[80:81]
	v_lshlrev_b64 v[26:27], 13, v[26:27]
	v_lshlrev_b64 v[28:29], 13, v[28:29]
	v_lshlrev_b64 v[30:31], 13, v[30:31]
	v_lshlrev_b64 v[48:49], 13, v[48:49]
	v_lshlrev_b64 v[50:51], 13, v[50:51]
	v_lshlrev_b64 v[52:53], 13, v[52:53]
	v_lshlrev_b64 v[54:55], 13, v[54:55]
	v_lshlrev_b64 v[56:57], 13, v[56:57]
	v_lshlrev_b64 v[58:59], 13, v[58:59]
	v_lshlrev_b64 v[60:61], 13, v[60:61]
	v_lshlrev_b64 v[62:63], 13, v[62:63]
	v_lshlrev_b64 v[64:65], 13, v[64:65]
	v_lshlrev_b64 v[66:67], 13, v[66:67]
	v_lshlrev_b64 v[68:69], 13, v[68:69]
	v_lshlrev_b64 v[84:85], 13, v[2:3]
	v_lshl_add_u64 v[10:11], v[78:79], 0, v[10:11]
	v_lshl_add_u64 v[12:13], v[78:79], 0, v[12:13]
	v_lshl_add_u64 v[14:15], v[78:79], 0, v[14:15]
	v_lshl_add_u64 v[16:17], v[78:79], 0, v[16:17]
	v_lshl_add_u64 v[18:19], v[78:79], 0, v[18:19]
	v_lshl_add_u64 v[20:21], v[78:79], 0, v[20:21]
	v_lshl_add_u64 v[22:23], v[78:79], 0, v[22:23]
	v_lshl_add_u64 v[24:25], v[78:79], 0, v[24:25]
	v_lshl_add_u64 v[32:33], v[78:79], 0, v[32:33]
	v_lshl_add_u64 v[34:35], v[78:79], 0, v[34:35]
	v_lshl_add_u64 v[36:37], v[78:79], 0, v[36:37]
	v_lshl_add_u64 v[38:39], v[78:79], 0, v[38:39]
	v_lshl_add_u64 v[40:41], v[78:79], 0, v[40:41]
	v_lshl_add_u64 v[42:43], v[78:79], 0, v[42:43]
	v_lshl_add_u64 v[44:45], v[78:79], 0, v[44:45]
	v_lshl_add_u64 v[46:47], v[78:79], 0, v[46:47]
	v_lshl_add_u64 v[26:27], v[78:79], 0, v[26:27]
	v_lshl_add_u64 v[28:29], v[78:79], 0, v[28:29]
	v_lshl_add_u64 v[30:31], v[78:79], 0, v[30:31]
	v_lshl_add_u64 v[48:49], v[78:79], 0, v[48:49]
	v_lshl_add_u64 v[50:51], v[78:79], 0, v[50:51]
	v_lshl_add_u64 v[52:53], v[78:79], 0, v[52:53]
	v_lshl_add_u64 v[54:55], v[78:79], 0, v[54:55]
	v_lshl_add_u64 v[56:57], v[78:79], 0, v[56:57]
	v_lshl_add_u64 v[58:59], v[78:79], 0, v[58:59]
	v_lshl_add_u64 v[60:61], v[78:79], 0, v[60:61]
	v_lshl_add_u64 v[62:63], v[78:79], 0, v[62:63]
	v_lshl_add_u64 v[64:65], v[78:79], 0, v[64:65]
	v_lshl_add_u64 v[66:67], v[78:79], 0, v[66:67]
	v_lshl_add_u64 v[68:69], v[78:79], 0, v[68:69]
	v_lshl_add_u64 v[78:79], v[78:79], 0, v[84:85]
	global_load_dword v80, v[80:81], off nt
	s_nop 0
	global_load_dword v10, v[10:11], off nt
	s_nop 0
	global_load_dword v11, v[12:13], off nt
	s_nop 0
	global_load_dword v12, v[14:15], off nt
	global_load_dword v13, v[16:17], off nt
	s_nop 0
	global_load_dword v14, v[18:19], off nt
	global_load_dword v15, v[20:21], off nt
	global_load_dword v16, v[22:23], off nt
	global_load_dword v17, v[24:25], off nt
	s_nop 0
	global_load_dword v18, v[26:27], off nt
	global_load_dword v19, v[28:29], off nt
	global_load_dword v20, v[30:31], off nt
	global_load_dword v21, v[32:33], off nt
	global_load_dword v22, v[34:35], off nt
	global_load_dword v23, v[36:37], off nt
	global_load_dword v24, v[38:39], off nt
	global_load_dword v25, v[40:41], off nt
	s_nop 0
	global_load_dword v32, v[42:43], off nt
	global_load_dword v33, v[44:45], off nt
	global_load_dword v34, v[46:47], off nt
	global_load_dword v35, v[48:49], off nt
	global_load_dword v36, v[50:51], off nt
	global_load_dword v37, v[52:53], off nt
	global_load_dword v38, v[54:55], off nt
	global_load_dword v39, v[56:57], off nt
	global_load_dword v40, v[58:59], off nt
	global_load_dword v41, v[60:61], off nt
	global_load_dword v42, v[62:63], off nt
	global_load_dword v43, v[64:65], off nt
	global_load_dword v44, v[66:67], off nt
	global_load_dword v45, v[68:69], off nt
	global_load_dword v46, v[78:79], off nt
	v_add_u32_e32 v1, 0x400, v71
	v_add_u32_e32 v5, 0x800, v71
	v_add_u32_e32 v77, 0xc00, v71
	v_add_u32_e32 v86, 0x1000, v71
	v_add_u32_e32 v87, 0x1400, v71
	v_add_u32_e32 v88, 0x1800, v71
	v_add_u32_e32 v89, 0x1c00, v71
	v_or_b32_e32 v90, s8, v72
	s_lshl_b32 s0, s9, 1
	s_waitcnt vmcnt(30)
; #define LAS __attribute__((address_space(3)))
; __device__ __forceinline__ unsigned pk2(float lo, float hi) { return f2bf(lo) | (f2bf(hi) << 16); }
; __device__ __forceinline__ void transpose_item(const float* W, int K, int Nsrc, int c0, bf16_t* WT, int mode, LAS float* scr, int kb, int nb, int lane) {
;     ...
;     for (int i = 0; i < 32; ++i) { const int kk = 2 * i + (lane >> 5); scr[kk * 33 + (lane & 31)] = tv[i]; }
;     asm volatile("s_waitcnt lgkmcnt(0)" ::: "memory");
;     const int c = lane & 7;
; #pragma unroll
;     for (int j = 0; j < 4; ++j) { const int n = (lane >> 3) + 8 * j; const LAS float* s = scr + (8 * c) * 33 + n;
;         u32x4 o; o.x = pk2(s[0 * 33], s[1 * 33]); o.y = pk2(s[2 * 33], s[3 * 33]); o.z = pk2(s[4 * 33], s[5 * 33]); o.w = pk2(s[6 * 33], s[7 * 33]);
;         const int nn = n0 + n; const int row = (mode == 0) ? nn : ((nn >> 7) * 256 + (nn & 127) + (mode == 2 ? 128 : 0));
;         *(u32x4*)(WT + (size_t)row * K + k0 + 8 * c) = o; }
;     asm volatile("s_waitcnt lgkmcnt(0)" ::: "memory");
	ds_write2_b32 v71, v80, v10 offset1:66
	s_waitcnt vmcnt(28)
	ds_write2_b32 v71, v11, v12 offset0:132 offset1:198
	s_waitcnt vmcnt(26)
	ds_write2_b32 v1, v13, v14 offset0:8 offset1:74
	s_waitcnt vmcnt(24)
	ds_write2_b32 v1, v15, v16 offset0:140 offset1:206
	s_waitcnt vmcnt(22)
	ds_write2_b32 v5, v17, v18 offset0:16 offset1:82
	s_waitcnt vmcnt(20)
	ds_write2_b32 v5, v19, v20 offset0:148 offset1:214
	s_waitcnt vmcnt(18)
	ds_write2_b32 v77, v21, v22 offset0:24 offset1:90
	s_waitcnt vmcnt(16)
	ds_write2_b32 v77, v23, v24 offset0:156 offset1:222
	s_waitcnt vmcnt(14)
	ds_write2_b32 v86, v25, v32 offset0:32 offset1:98
	s_waitcnt vmcnt(12)
	ds_write2_b32 v86, v33, v34 offset0:164 offset1:230
	s_waitcnt vmcnt(10)
	ds_write2_b32 v87, v35, v36 offset0:40 offset1:106
	s_waitcnt vmcnt(8)
	ds_write2_b32 v87, v37, v38 offset0:172 offset1:238
	s_waitcnt vmcnt(6)
	ds_write2_b32 v88, v39, v40 offset0:48 offset1:114
	s_waitcnt vmcnt(4)
	ds_write2_b32 v88, v41, v42 offset0:180 offset1:246
	s_waitcnt vmcnt(2)
	ds_write2_b32 v89, v43, v44 offset0:56 offset1:122
	s_waitcnt vmcnt(0)
	ds_write2_b32 v89, v45, v46 offset0:188 offset1:254
	v_or_b32_e32 v91, s8, v74
	v_lshl_add_u64 v[82:83], v[8:9], 0, s[0:1]
	v_mul_u32_u24_e32 v2, 0x2c00, v90
	s_waitcnt lgkmcnt(0)
	v_or_b32_e32 v92, s8, v75
	v_lshl_add_u64 v[84:85], v[82:83], 0, v[2:3]
	v_mul_u32_u24_e32 v2, 0x2c00, v91
	ds_read2_b32 v[10:11], v73 offset0:33 offset1:41
	ds_read2_b32 v[12:13], v73 offset1:8
	ds_read2_b32 v[14:15], v73 offset0:66 offset1:74
	ds_read2_b32 v[16:17], v73 offset0:99 offset1:107
	ds_read2_b32 v[18:19], v73 offset0:132 offset1:140
	ds_read2_b32 v[20:21], v73 offset0:165 offset1:173
	ds_read2_b32 v[22:23], v73 offset0:198 offset1:206
	ds_read2_b32 v[24:25], v73 offset0:231 offset1:239
	ds_read2_b32 v[32:33], v73 offset0:16 offset1:24
	ds_read2_b32 v[34:35], v73 offset0:49 offset1:57
	ds_read2_b32 v[36:37], v73 offset0:82 offset1:90
	ds_read2_b32 v[38:39], v73 offset0:115 offset1:123
	ds_read2_b32 v[40:41], v73 offset0:148 offset1:156
	ds_read2_b32 v[42:43], v73 offset0:181 offset1:189
	ds_read2_b32 v[44:45], v73 offset0:214 offset1:222
	ds_read2_b32 v[46:47], v73 offset0:247 offset1:255
	v_or_b32_e32 v93, s8, v76
	v_lshl_add_u64 v[26:27], v[82:83], 0, v[2:3]
	v_mul_u32_u24_e32 v2, 0x2c00, v92
	v_lshl_add_u64 v[28:29], v[82:83], 0, v[2:3]
	v_mul_u32_u24_e32 v2, 0x2c00, v93
	v_lshl_add_u64 v[30:31], v[82:83], 0, v[2:3]
	s_waitcnt lgkmcnt(14)
	v_bfe_u32 v1, v12, 16, 1
	v_bfe_u32 v2, v10, 16, 1
	s_waitcnt lgkmcnt(13)
	v_bfe_u32 v5, v14, 16, 1
	s_waitcnt lgkmcnt(12)
	v_bfe_u32 v48, v16, 16, 1
	s_waitcnt lgkmcnt(11)
	v_bfe_u32 v49, v18, 16, 1
	s_waitcnt lgkmcnt(9)
	v_bfe_u32 v51, v22, 16, 1
	v_bfe_u32 v50, v20, 16, 1
	s_waitcnt lgkmcnt(8)
	v_bfe_u32 v52, v24, 16, 1
	v_bfe_u32 v53, v13, 16, 1
	v_bfe_u32 v54, v11, 16, 1
	v_bfe_u32 v55, v15, 16, 1
	v_bfe_u32 v56, v17, 16, 1
	v_bfe_u32 v57, v19, 16, 1
	v_bfe_u32 v58, v21, 16, 1
	v_bfe_u32 v59, v23, 16, 1
	v_bfe_u32 v60, v25, 16, 1
	s_waitcnt lgkmcnt(7)
	v_bfe_u32 v61, v32, 16, 1
	s_waitcnt lgkmcnt(6)
	v_bfe_u32 v62, v34, 16, 1
	s_waitcnt lgkmcnt(5)
	v_bfe_u32 v63, v36, 16, 1
	s_waitcnt lgkmcnt(4)
	v_bfe_u32 v64, v38, 16, 1
	s_waitcnt lgkmcnt(3)
	v_bfe_u32 v65, v40, 16, 1
	s_waitcnt lgkmcnt(2)
	v_bfe_u32 v66, v42, 16, 1
	s_waitcnt lgkmcnt(1)
	v_bfe_u32 v67, v44, 16, 1
	v_bfe_u32 v69, v33, 16, 1
	v_bfe_u32 v78, v37, 16, 1
	v_bfe_u32 v80, v41, 16, 1
	v_bfe_u32 v81, v43, 16, 1
	v_bfe_u32 v82, v45, 16, 1
	v_add3_u32 v1, v12, v1, s6
	v_add3_u32 v2, v10, v2, s6
	v_add3_u32 v5, v14, v5, s6
	v_add3_u32 v12, v16, v48, s6
	v_add3_u32 v10, v18, v49, s6
	v_add3_u32 v16, v22, v51, s6
	s_waitcnt lgkmcnt(0)
	v_bfe_u32 v68, v46, 16, 1
	v_bfe_u32 v77, v35, 16, 1
	v_bfe_u32 v79, v39, 16, 1
	v_bfe_u32 v83, v47, 16, 1
	v_add3_u32 v14, v20, v50, s6
	v_add3_u32 v18, v24, v52, s6
	v_add3_u32 v13, v13, v53, s6
	v_add3_u32 v20, v11, v54, s6
	v_add3_u32 v11, v15, v55, s6
	v_add3_u32 v15, v17, v56, s6
	v_add3_u32 v17, v19, v57, s6
	v_add3_u32 v19, v21, v58, s6
	v_add3_u32 v21, v23, v59, s6
	v_add3_u32 v22, v25, v60, s6
	v_add3_u32 v23, v32, v61, s6
	v_add3_u32 v24, v34, v62, s6
	v_add3_u32 v25, v36, v63, s6
	v_add3_u32 v32, v38, v64, s6
	v_add3_u32 v34, v40, v65, s6
	v_add3_u32 v36, v42, v66, s6
	v_add3_u32 v38, v44, v67, s6
	v_add3_u32 v33, v33, v69, s6
	v_add3_u32 v37, v37, v78, s6
	v_add3_u32 v41, v41, v80, s6
	v_add3_u32 v42, v43, v81, s6
	v_add3_u32 v43, v45, v82, s6
	v_lshrrev_b32_e32 v1, 16, v1
	v_lshrrev_b32_e32 v5, 16, v5
	v_lshrrev_b32_e32 v45, 16, v10
	v_lshrrev_b32_e32 v16, 16, v16
	v_add3_u32 v40, v46, v68, s6
	v_add3_u32 v35, v35, v77, s6
	v_add3_u32 v39, v39, v79, s6
	v_add3_u32 v44, v47, v83, s6
	v_lshrrev_b32_e32 v46, 16, v13
	v_lshrrev_b32_e32 v47, 16, v11
	v_lshrrev_b32_e32 v17, 16, v17
	v_lshrrev_b32_e32 v21, 16, v21
	v_lshrrev_b32_e32 v23, 16, v23
	v_lshrrev_b32_e32 v25, 16, v25
	v_lshrrev_b32_e32 v34, 16, v34
	v_lshrrev_b32_e32 v38, 16, v38
	v_lshrrev_b32_e32 v33, 16, v33
	v_lshrrev_b32_e32 v37, 16, v37
	v_lshrrev_b32_e32 v41, 16, v41
	v_lshrrev_b32_e32 v43, 16, v43
	v_and_or_b32 v10, v2, s7, v1
	v_and_or_b32 v11, v12, s7, v5
	v_and_or_b32 v12, v14, s7, v45
	v_and_or_b32 v13, v18, s7, v16
	v_and_or_b32 v14, v20, s7, v46
	v_and_or_b32 v15, v15, s7, v47
	v_and_or_b32 v16, v19, s7, v17
	v_and_or_b32 v17, v22, s7, v21
	v_and_or_b32 v18, v24, s7, v23
	v_and_or_b32 v19, v32, s7, v25
	v_and_or_b32 v20, v36, s7, v34
	v_and_or_b32 v21, v40, s7, v38
	v_and_or_b32 v22, v35, s7, v33
	v_and_or_b32 v23, v39, s7, v37
	v_and_or_b32 v24, v42, s7, v41
	v_and_or_b32 v25, v44, s7, v43
	global_store_dwordx4 v[84:85], v[10:13], off nt
	global_store_dwordx4 v[26:27], v[14:17], off nt
	global_store_dwordx4 v[28:29], v[18:21], off nt
	global_store_dwordx4 v[30:31], v[22:25], off nt
	s_waitcnt lgkmcnt(0)
	s_addk_i32 s5, 0x6000
	s_cmpk_lt_u32 s4, 0x1300
	s_cbranch_scc1 .LBB0_902
; __device__ __forceinline__ void transpose_item(const float* W, int K, int Nsrc, int c0, bf16_t* WT, int mode, LAS float* scr, int kb, int nb, int lane) {
;     ...
;     for (int i = 0; i < 32; ++i) { const int kk = 2 * i + (lane >> 5); tv[i] = W[(size_t)(k0 + kk) * Nsrc + c0 + n0 + (lane & 31)]; }
; #pragma unroll
;     for (int i = 0; i < 32; ++i) { const int kk = 2 * i + (lane >> 5); scr[kk * 33 + (lane & 31)] = tv[i]; }
;     ...
;     const int nnb = ncols / 32, items = (K / 64) * nnb;
;     const int first = (gw - base % NGW + NGW) % NGW;
;     for (int it = first; it < items; it += NGW) transpose_item(W, K, Nsrc, c0, WT, mode, scr, it / nnb, it % nnb, F.lane);
	v_mov_b32_e32 v1, 0
	v_readlane_b32 s12, v247, 44
	v_readlane_b32 s13, v247, 45
	v_readlane_b32 s14, v247, 46
	v_readlane_b32 s15, v247, 47
	v_readlane_b32 s16, v247, 48
	v_readlane_b32 s17, v247, 49
	v_readlane_b32 s18, v247, 50
	v_readlane_b32 s19, v247, 51
	v_readlane_b32 s20, v247, 52
	v_readlane_b32 s21, v247, 53
	v_readlane_b32 s22, v247, 54
	v_readlane_b32 s23, v247, 55
	v_readlane_b32 s24, v247, 56
	v_readlane_b32 s25, v247, 57
	v_readlane_b32 s26, v247, 58
	v_readlane_b32 s27, v247, 59
	v_mov_b32_e32 v5, v1
	v_lshl_add_u64 v[2:3], s[14:15], 0, v[0:1]
	v_lshl_add_u64 v[4:5], s[96:97], 0, v[4:5]
	s_mov_b32 s1, 0
	s_mov_b32 s4, 0xc000
	s_mov_b32 s5, 0x18000
	s_mov_b32 s6, 0x24000
	s_mov_b32 s7, 0x30000
	s_mov_b32 s8, 0x3c000
	s_mov_b32 s9, 0x48000
	s_mov_b32 s12, 0x54000
	s_mov_b32 s13, 0x60000
	s_mov_b32 s14, 0x6c000
	s_mov_b32 s15, 0x78000
	s_mov_b32 s16, 0x84000
	s_mov_b32 s17, 0x90000
	s_mov_b32 s18, 0x9c000
	s_mov_b32 s19, 0xa8000
	s_mov_b32 s20, 0xb4000
	s_mov_b32 s21, 0xc0000
	s_mov_b32 s22, 0xcc000
	s_mov_b32 s23, 0xd8000
	s_mov_b32 s24, 0xe4000
	s_mov_b32 s25, 0xf0000
	s_mov_b32 s26, 0xfc000
	s_mov_b32 s27, 0x108000
	s_mov_b32 s28, 0x114000
	s_mov_b32 s29, 0x120000
	s_mov_b32 s30, 0x12c000
	s_mov_b32 s31, 0x138000
	s_mov_b32 s34, 0x144000
	s_mov_b32 s35, 0x150000
	s_mov_b32 s38, 0x15c000
	s_mov_b32 s39, 0x168000
	s_mov_b32 s40, 0x174000
	s_movk_i32 s41, 0x7fff
	s_mov_b32 s44, 0xffff0000
.LBB0_904:
	s_and_b32 s0, s3, 0xffff
	s_mul_i32 s0, s0, 0xaaab
	s_lshr_b32 s45, s0, 23
	s_mul_i32 s0, s45, 0xc0
	s_sub_i32 s0, s3, s0
	s_lshl_b32 s0, s0, 5
	s_and_b32 s52, s0, 0xffe0
	v_lshl_or_b32 v0, s45, 6, v70
	s_lshl_b32 s0, s52, 2
	v_mul_u32_u24_e32 v0, 0x6040, v0
	v_lshl_add_u64 v[6:7], v[2:3], 0, s[0:1]
	v_lshl_add_u64 v[10:11], v[6:7], 0, v[0:1]
	v_or_b32_e32 v8, s52, v72
	s_lshl_b32 s0, s45, 7
	v_add_co_u32_e32 v14, vcc, s4, v10
	v_or_b32_e32 v9, s52, v74
	v_lshl_add_u64 v[12:13], v[4:5], 0, s[0:1]
	v_lshlrev_b32_e32 v0, 12, v8
	v_addc_co_u32_e32 v15, vcc, 0, v11, vcc
	v_or_b32_e32 v17, s52, v75
	v_lshl_add_u64 v[6:7], v[12:13], 0, v[0:1]
	v_lshlrev_b32_e32 v0, 12, v9
	v_add_co_u32_e32 v16, vcc, s5, v10
	v_lshl_add_u64 v[8:9], v[12:13], 0, v[0:1]
	v_lshlrev_b32_e32 v0, 12, v17
	v_addc_co_u32_e32 v17, vcc, 0, v11, vcc
	global_load_dword v31, v[10:11], off nt
	global_load_dword v32, v[14:15], off offset:128 nt
	v_add_co_u32_e32 v14, vcc, s6, v10
	v_or_b32_e32 v18, s52, v76
	s_nop 0
	v_addc_co_u32_e32 v15, vcc, 0, v11, vcc
	v_lshl_add_u64 v[26:27], v[12:13], 0, v[0:1]
	v_lshlrev_b32_e32 v0, 12, v18
	v_add_co_u32_e32 v18, vcc, s7, v10
	v_lshl_add_u64 v[28:29], v[12:13], 0, v[0:1]
	s_nop 0
	v_addc_co_u32_e32 v19, vcc, 0, v11, vcc
	v_add_co_u32_e32 v12, vcc, s8, v10
	global_load_dword v0, v[16:17], off offset:256 nt
	global_load_dword v33, v[14:15], off offset:384 nt
	v_addc_co_u32_e32 v13, vcc, 0, v11, vcc
	v_add_co_u32_e32 v14, vcc, s9, v10
	global_load_dword v18, v[18:19], off offset:512 nt
	s_nop 0
	global_load_dword v19, v[12:13], off offset:640 nt
	v_addc_co_u32_e32 v15, vcc, 0, v11, vcc
	v_add_co_u32_e32 v12, vcc, s12, v10
	v_add_u32_e32 v20, 0x400, v71
	s_nop 0
	v_addc_co_u32_e32 v13, vcc, 0, v11, vcc
	v_add_co_u32_e32 v16, vcc, s13, v10
	global_load_dword v34, v[14:15], off offset:768 nt
	global_load_dword v35, v[12:13], off offset:896 nt
	v_addc_co_u32_e32 v17, vcc, 0, v11, vcc
	v_add_co_u32_e32 v12, vcc, s14, v10
	v_add_u32_e32 v21, 0x800, v71
	s_nop 0
	v_addc_co_u32_e32 v13, vcc, 0, v11, vcc
	v_add_co_u32_e32 v14, vcc, s15, v10
	global_load_dword v36, v[16:17], off offset:1024 nt
	global_load_dword v37, v[12:13], off offset:1152 nt
	v_addc_co_u32_e32 v15, vcc, 0, v11, vcc
	v_add_co_u32_e32 v12, vcc, s16, v10
	v_add_u32_e32 v22, 0xc00, v71
	s_nop 0
	v_addc_co_u32_e32 v13, vcc, 0, v11, vcc
	v_add_co_u32_e32 v16, vcc, s17, v10
	global_load_dword v38, v[14:15], off offset:1280 nt
	global_load_dword v39, v[12:13], off offset:1408 nt
	v_addc_co_u32_e32 v17, vcc, 0, v11, vcc
	v_add_co_u32_e32 v12, vcc, s18, v10
	v_add_u32_e32 v23, 0x1000, v71
	s_nop 0
	v_addc_co_u32_e32 v13, vcc, 0, v11, vcc
	v_add_co_u32_e32 v14, vcc, s19, v10
	global_load_dword v40, v[16:17], off offset:1536 nt
	global_load_dword v41, v[12:13], off offset:1664 nt
	v_addc_co_u32_e32 v15, vcc, 0, v11, vcc
	v_add_co_u32_e32 v12, vcc, s20, v10
	v_add_u32_e32 v24, 0x1400, v71
	s_nop 0
	v_addc_co_u32_e32 v13, vcc, 0, v11, vcc
	v_add_co_u32_e32 v16, vcc, s21, v10
	global_load_dword v42, v[14:15], off offset:1792 nt
	global_load_dword v43, v[12:13], off offset:1920 nt
	v_addc_co_u32_e32 v17, vcc, 0, v11, vcc
	v_add_co_u32_e32 v12, vcc, s22, v10
	v_add_u32_e32 v25, 0x1800, v71
	s_nop 0
	v_addc_co_u32_e32 v13, vcc, 0, v11, vcc
	v_add_co_u32_e32 v14, vcc, s23, v10
	global_load_dword v44, v[16:17], off offset:2048 nt
	global_load_dword v45, v[12:13], off offset:2176 nt
	v_addc_co_u32_e32 v15, vcc, 0, v11, vcc
	v_add_co_u32_e32 v12, vcc, s24, v10
	v_add_u32_e32 v30, 0x1c00, v71
	s_nop 0
	v_addc_co_u32_e32 v13, vcc, 0, v11, vcc
	v_add_co_u32_e32 v16, vcc, s25, v10
	global_load_dword v46, v[14:15], off offset:2304 nt
	global_load_dword v47, v[12:13], off offset:2432 nt
	v_addc_co_u32_e32 v17, vcc, 0, v11, vcc
	v_add_co_u32_e32 v12, vcc, s26, v10
	s_add_i32 s0, s3, 0x300
	s_nop 0
	v_addc_co_u32_e32 v13, vcc, 0, v11, vcc
	v_add_co_u32_e32 v14, vcc, s27, v10
	global_load_dword v48, v[16:17], off offset:2560 nt
	global_load_dword v49, v[12:13], off offset:2688 nt
	v_addc_co_u32_e32 v15, vcc, 0, v11, vcc
	v_add_co_u32_e32 v12, vcc, s28, v10
	s_cmpk_gt_u32 s3, 0x14ff
	s_nop 0
	v_addc_co_u32_e32 v13, vcc, 0, v11, vcc
	v_add_co_u32_e32 v16, vcc, s29, v10
	global_load_dword v50, v[14:15], off offset:2816 nt
	global_load_dword v51, v[12:13], off offset:2944 nt
	v_addc_co_u32_e32 v17, vcc, 0, v11, vcc
	v_add_co_u32_e32 v12, vcc, s30, v10
	s_mov_b32 s3, s0
	s_nop 0
	v_addc_co_u32_e32 v13, vcc, 0, v11, vcc
	v_add_co_u32_e32 v14, vcc, s31, v10
	global_load_dword v52, v[16:17], off offset:3072 nt
	global_load_dword v53, v[12:13], off offset:3200 nt
	v_addc_co_u32_e32 v15, vcc, 0, v11, vcc
	v_add_co_u32_e32 v12, vcc, s34, v10
	s_nop 1
	v_addc_co_u32_e32 v13, vcc, 0, v11, vcc
	v_add_co_u32_e32 v16, vcc, s35, v10
	global_load_dword v54, v[14:15], off offset:3328 nt
	global_load_dword v55, v[12:13], off offset:3456 nt
	v_addc_co_u32_e32 v17, vcc, 0, v11, vcc
	v_add_co_u32_e32 v12, vcc, s38, v10
	s_nop 1
	v_addc_co_u32_e32 v13, vcc, 0, v11, vcc
	v_add_co_u32_e32 v14, vcc, s39, v10
	global_load_dword v16, v[16:17], off offset:3584 nt
	s_nop 0
	global_load_dword v12, v[12:13], off offset:3712 nt
	v_addc_co_u32_e32 v15, vcc, 0, v11, vcc
	v_add_co_u32_e32 v10, vcc, s40, v10
	s_nop 1
	v_addc_co_u32_e32 v11, vcc, 0, v11, vcc
	global_load_dword v13, v[14:15], off offset:3840 nt
	s_nop 0
	global_load_dword v10, v[10:11], off offset:3968 nt
	s_waitcnt vmcnt(30)
; #define LAS __attribute__((address_space(3)))
; __device__ __forceinline__ unsigned pk2(float lo, float hi) { return f2bf(lo) | (f2bf(hi) << 16); }
; __device__ __forceinline__ void transpose_item(const float* W, int K, int Nsrc, int c0, bf16_t* WT, int mode, LAS float* scr, int kb, int nb, int lane) {
;     ...
;     for (int i = 0; i < 32; ++i) { const int kk = 2 * i + (lane >> 5); scr[kk * 33 + (lane & 31)] = tv[i]; }
;     asm volatile("s_waitcnt lgkmcnt(0)" ::: "memory");
;     const int c = lane & 7;
; #pragma unroll
;     for (int j = 0; j < 4; ++j) { const int n = (lane >> 3) + 8 * j; const LAS float* s = scr + (8 * c) * 33 + n;
;         u32x4 o; o.x = pk2(s[0 * 33], s[1 * 33]); o.y = pk2(s[2 * 33], s[3 * 33]); o.z = pk2(s[4 * 33], s[5 * 33]); o.w = pk2(s[6 * 33], s[7 * 33]);
;         const int nn = n0 + n; const int row = (mode == 0) ? nn : ((nn >> 7) * 256 + (nn & 127) + (mode == 2 ? 128 : 0));
;         *(u32x4*)(WT + (size_t)row * K + k0 + 8 * c) = o; }
;     asm volatile("s_waitcnt lgkmcnt(0)" ::: "memory");
	ds_write2_b32 v71, v31, v32 offset1:66
	s_waitcnt vmcnt(28)
	ds_write2_b32 v71, v0, v33 offset0:132 offset1:198
	s_waitcnt vmcnt(26)
	ds_write2_b32 v20, v18, v19 offset0:8 offset1:74
	s_waitcnt vmcnt(24)
	ds_write2_b32 v20, v34, v35 offset0:140 offset1:206
	s_waitcnt vmcnt(22)
	ds_write2_b32 v21, v36, v37 offset0:16 offset1:82
	s_waitcnt vmcnt(20)
	ds_write2_b32 v21, v38, v39 offset0:148 offset1:214
	s_waitcnt vmcnt(18)
	ds_write2_b32 v22, v40, v41 offset0:24 offset1:90
	s_waitcnt vmcnt(16)
	ds_write2_b32 v22, v42, v43 offset0:156 offset1:222
	s_waitcnt vmcnt(14)
	ds_write2_b32 v23, v44, v45 offset0:32 offset1:98
	s_waitcnt vmcnt(12)
	ds_write2_b32 v23, v46, v47 offset0:164 offset1:230
	s_waitcnt vmcnt(10)
	ds_write2_b32 v24, v48, v49 offset0:40 offset1:106
	s_waitcnt vmcnt(8)
	ds_write2_b32 v24, v50, v51 offset0:172 offset1:238
	s_waitcnt vmcnt(6)
	ds_write2_b32 v25, v52, v53 offset0:48 offset1:114
	s_waitcnt vmcnt(4)
	ds_write2_b32 v25, v54, v55 offset0:180 offset1:246
	s_waitcnt vmcnt(2)
	ds_write2_b32 v30, v16, v12 offset0:56 offset1:122
	s_waitcnt vmcnt(0)
	ds_write2_b32 v30, v13, v10 offset0:188 offset1:254
	s_waitcnt lgkmcnt(0)
	ds_read2_b32 v[10:11], v73 offset0:33 offset1:41
	ds_read2_b32 v[12:13], v73 offset1:8
	ds_read2_b32 v[14:15], v73 offset0:66 offset1:74
	ds_read2_b32 v[16:17], v73 offset0:99 offset1:107
	ds_read2_b32 v[18:19], v73 offset0:132 offset1:140
	ds_read2_b32 v[20:21], v73 offset0:165 offset1:173
	ds_read2_b32 v[22:23], v73 offset0:198 offset1:206
	ds_read2_b32 v[24:25], v73 offset0:231 offset1:239
	ds_read2_b32 v[30:31], v73 offset0:49 offset1:57
	ds_read2_b32 v[32:33], v73 offset0:16 offset1:24
	ds_read2_b32 v[34:35], v73 offset0:82 offset1:90
	ds_read2_b32 v[36:37], v73 offset0:115 offset1:123
	ds_read2_b32 v[38:39], v73 offset0:148 offset1:156
	ds_read2_b32 v[40:41], v73 offset0:181 offset1:189
	ds_read2_b32 v[42:43], v73 offset0:214 offset1:222
	ds_read2_b32 v[44:45], v73 offset0:247 offset1:255
	s_waitcnt lgkmcnt(14)
	v_bfe_u32 v0, v12, 16, 1
	s_waitcnt lgkmcnt(13)
	v_bfe_u32 v47, v14, 16, 1
	s_waitcnt lgkmcnt(12)
	v_bfe_u32 v48, v16, 16, 1
	s_waitcnt lgkmcnt(11)
	v_bfe_u32 v49, v18, 16, 1
	s_waitcnt lgkmcnt(10)
	v_bfe_u32 v50, v20, 16, 1
	s_waitcnt lgkmcnt(9)
	v_bfe_u32 v51, v22, 16, 1
	v_bfe_u32 v46, v10, 16, 1
	s_waitcnt lgkmcnt(8)
	v_bfe_u32 v52, v24, 16, 1
	v_bfe_u32 v53, v13, 16, 1
	v_bfe_u32 v54, v11, 16, 1
	v_bfe_u32 v55, v15, 16, 1
	v_bfe_u32 v56, v17, 16, 1
	v_bfe_u32 v57, v19, 16, 1
	v_bfe_u32 v58, v21, 16, 1
	v_bfe_u32 v59, v23, 16, 1
	v_bfe_u32 v60, v25, 16, 1
	s_waitcnt lgkmcnt(6)
	v_bfe_u32 v61, v32, 16, 1
	s_waitcnt lgkmcnt(5)
	v_bfe_u32 v63, v34, 16, 1
	s_waitcnt lgkmcnt(4)
	v_bfe_u32 v64, v36, 16, 1
	s_waitcnt lgkmcnt(3)
	v_bfe_u32 v65, v38, 16, 1
	s_waitcnt lgkmcnt(2)
	v_bfe_u32 v66, v40, 16, 1
	s_waitcnt lgkmcnt(1)
	v_bfe_u32 v67, v42, 16, 1
	v_bfe_u32 v69, v33, 16, 1
	v_bfe_u32 v78, v35, 16, 1
	v_bfe_u32 v80, v39, 16, 1
	v_bfe_u32 v82, v43, 16, 1
	v_add3_u32 v0, v12, v0, s41
	v_add3_u32 v12, v14, v47, s41
	v_add3_u32 v14, v16, v48, s41
	v_add3_u32 v16, v18, v49, s41
	v_add3_u32 v18, v20, v50, s41
	v_add3_u32 v20, v22, v51, s41
	v_bfe_u32 v62, v30, 16, 1
	s_waitcnt lgkmcnt(0)
	v_bfe_u32 v68, v44, 16, 1
	v_bfe_u32 v77, v31, 16, 1
	v_bfe_u32 v79, v37, 16, 1
	v_bfe_u32 v81, v41, 16, 1
	v_bfe_u32 v83, v45, 16, 1
	v_add3_u32 v10, v10, v46, s41
	v_add3_u32 v22, v24, v52, s41
	v_add3_u32 v13, v13, v53, s41
	v_add3_u32 v24, v11, v54, s41
	v_add3_u32 v11, v15, v55, s41
	v_add3_u32 v15, v17, v56, s41
	v_add3_u32 v17, v19, v57, s41
	v_add3_u32 v19, v21, v58, s41
	v_add3_u32 v21, v23, v59, s41
	v_add3_u32 v23, v25, v60, s41
	v_add3_u32 v25, v32, v61, s41
	v_add3_u32 v32, v34, v63, s41
	v_add3_u32 v34, v36, v64, s41
	v_add3_u32 v36, v38, v65, s41
	v_add3_u32 v38, v40, v66, s41
	v_add3_u32 v40, v42, v67, s41
	v_add3_u32 v33, v33, v69, s41
	v_add3_u32 v35, v35, v78, s41
	v_add3_u32 v39, v39, v80, s41
	v_add3_u32 v43, v43, v82, s41
	v_lshrrev_b32_e32 v0, 16, v0
	v_lshrrev_b32_e32 v12, 16, v12
	v_lshrrev_b32_e32 v16, 16, v16
	v_lshrrev_b32_e32 v20, 16, v20
	v_add3_u32 v30, v30, v62, s41
	v_add3_u32 v42, v44, v68, s41
	v_add3_u32 v31, v31, v77, s41
	v_add3_u32 v37, v37, v79, s41
	v_add3_u32 v41, v41, v81, s41
	v_add3_u32 v44, v45, v83, s41
	v_lshrrev_b32_e32 v45, 16, v13
	v_lshrrev_b32_e32 v46, 16, v11
	v_lshrrev_b32_e32 v17, 16, v17
	v_lshrrev_b32_e32 v21, 16, v21
	v_lshrrev_b32_e32 v25, 16, v25
	v_lshrrev_b32_e32 v32, 16, v32
	v_lshrrev_b32_e32 v36, 16, v36
	v_lshrrev_b32_e32 v40, 16, v40
	v_lshrrev_b32_e32 v33, 16, v33
	v_lshrrev_b32_e32 v35, 16, v35
	v_lshrrev_b32_e32 v39, 16, v39
	v_lshrrev_b32_e32 v43, 16, v43
	v_and_or_b32 v10, v10, s44, v0
	v_and_or_b32 v11, v14, s44, v12
	v_and_or_b32 v12, v18, s44, v16
	v_and_or_b32 v13, v22, s44, v20
	v_and_or_b32 v14, v24, s44, v45
	v_and_or_b32 v15, v15, s44, v46
	v_and_or_b32 v16, v19, s44, v17
	v_and_or_b32 v17, v23, s44, v21
	v_and_or_b32 v18, v30, s44, v25
	v_and_or_b32 v19, v34, s44, v32
	v_and_or_b32 v20, v38, s44, v36
	v_and_or_b32 v21, v42, s44, v40
	v_and_or_b32 v22, v31, s44, v33
	v_and_or_b32 v23, v37, s44, v35
	v_and_or_b32 v24, v41, s44, v39
	v_and_or_b32 v25, v44, s44, v43
	global_store_dwordx4 v[6:7], v[10:13], off nt
	global_store_dwordx4 v[8:9], v[14:17], off nt
	global_store_dwordx4 v[26:27], v[18:21], off nt
	global_store_dwordx4 v[28:29], v[22:25], off nt
	s_waitcnt lgkmcnt(0)
	s_cbranch_scc0 .LBB0_904

; #define LAS __attribute__((address_space(3)))
; __device__ __forceinline__ unsigned f2bf(float f) { unsigned u = __float_as_uint(f); return (u + 0x7fffu + ((u >> 16) & 1u)) >> 16; }
; __device__ __forceinline__ void s5_group_phase(const Ctx& F, int g) {
;     ...
;         const float* A16 = WSP(float, WS_SMALL + SM_A16) + g * 128; const float ar = A16[lane], ai = A16[64 + lane]; float cr = 0.f, ci = 0.f;
;         for (int blk = 0; blk < 8; ++blk) {
;             f32x4 t[8];
; #pragma unroll
;             for (int i = 0; i < 8; ++i) t[i] = *(const f32x4*)(WU + (size_t)blk * 16384 + (size_t)(i * 512 + tid) * 4);
; #pragma unroll
;             for (int i = 0; i < 8; ++i) *(LAS f32x4*)(wu + (i * 512 + tid) * 4) = t[i];
;             __syncthreads();
;             if (F.wave == 0) {
; #pragma unroll 8
;                 for (int c = 0; c < 128; ++c) { const float wr_ = wu[c * 128 + lane], wi_ = wu[c * 128 + 64 + lane];
;                     xs[c * 128 + lane] = (bf16_t)f2bf(cr); xs[c * 128 + 64 + lane] = (bf16_t)f2bf(ci);
;                     const float nr = ar * cr - ai * ci + wr_, ni = ar * ci + ai * cr + wi_; cr = nr; ci = ni; }
;             }
;             __syncthreads();
; #pragma unroll
;             for (int i = 0; i < 4; ++i) *(u32x4*)(XC + (size_t)blk * 16384 + (size_t)(i * 512 + tid) * 8) = *(const LAS u32x4*)(xs + (i * 512 + tid) * 8);
;         }
.LBB0_906:
	s_andn2_b64 vcc, exec, s[0:1]
	s_cbranch_vccnz .LBB0_926
	v_readlane_b32 s4, v247, 5
	v_readlane_b32 s6, v247, 7
	s_cmp_eq_u32 s6, 1
	v_readlane_b32 s5, v247, 6
	v_readlane_b32 s7, v247, 8
	s_cbranch_scc1 .LBB0_926
	v_readlane_b32 s0, v247, 10
	s_mov_b32 s15, 0
	s_sub_i32 s8, s0, 64
	s_mov_b32 s9, s15
	s_lshl_b64 s[4:5], s[8:9], 19
	v_readlane_b32 s1, v247, 11
	s_add_u32 s0, s92, s4
	s_addc_u32 s1, s93, s5
	s_add_u32 s3, s0, 0x1fc00000
	s_addc_u32 s16, s1, 0
	s_lshl_b64 s[6:7], s[8:9], 18
	s_add_u32 s0, s92, s6
	s_addc_u32 s1, s93, s7
	s_add_u32 s12, s0, 0x21c00000
	s_addc_u32 s13, s1, 0
	s_lshl_b32 s14, s8, 7
	s_lshl_b64 s[0:1], s[14:15], 2
	s_add_u32 s0, s92, s0
	s_addc_u32 s1, s93, s1
	v_lshlrev_b32_e32 v6, 2, v242
	v_mov_b32_e32 v7, 0
	s_waitcnt lgkmcnt(0)
	v_lshl_add_u64 v[0:1], s[0:1], 0, v[6:7]
	s_mov_b64 s[0:1], 0x500000
	v_lshl_add_u64 v[2:3], v[0:1], 0, s[0:1]
	s_mov_b32 s0, 0x500000
	v_add_co_u32_e32 v0, vcc, s0, v0
	v_readlane_b32 s0, v247, 0
	s_nop 0
	v_addc_co_u32_e32 v1, vcc, 0, v1, vcc
	global_load_dword v0, v[0:1], off nt
	s_nop 0
	global_load_dword v2, v[2:3], off offset:256 nt
	s_cmp_lt_u32 s0, 64
	s_cselect_b64 s[0:1], -1, 0
	v_lshlrev_b32_e32 v106, 4, v212
	v_cndmask_b32_e64 v1, 0, 1, s[0:1]
	v_lshl_add_u32 v8, v242, 1, 0
	s_movk_i32 s9, 0x2000
	s_movk_i32 s17, 0x7fff
	v_mov_b32_e32 v107, v7
	v_or_b32_e32 v4, 0x4000, v106
	v_mov_b32_e32 v5, v7
	v_add_u32_e32 v9, 0, v6
	v_add_u32_e32 v10, 0, v106
	v_mov_b32_e32 v6, v7
	s_add_i32 s18, 0, 0x10000
	v_cmp_ne_u32_e64 s[0:1], 1, v1
	s_mov_b32 s19, 0
	s_waitcnt vmcnt(0)
	v_mov_b32_e32 v1, v0
	v_mov_b32_e32 v3, v2
	s_branch .LBB0_910
.LBB0_909:
	v_add_u32_e32 v11, s18, v106
	s_waitcnt lgkmcnt(0)
	s_barrier
	ds_read_b128 v[12:15], v11
	ds_read_b128 v[16:19], v11 offset:8192
	s_lshl_b32 s14, s14, 1
	s_add_u32 s20, s12, s14
	s_addc_u32 s21, s13, 0
	v_lshl_add_u64 v[20:21], s[20:21], 0, v[106:107]
	s_waitcnt lgkmcnt(1)
	global_store_dwordx4 v[20:21], v[12:15], off nt
	v_add_co_u32_e32 v22, vcc, s9, v20
	s_nop 0
	v_add_u32_e32 v12, s18, v4
	ds_read_b128 v[12:15], v12
	v_addc_co_u32_e32 v23, vcc, 0, v21, vcc
	s_waitcnt lgkmcnt(1)
	global_store_dwordx4 v[22:23], v[16:19], off nt
	ds_read_b128 v[16:19], v11 offset:24576
	v_lshl_add_u64 v[22:23], s[20:21], 0, v[4:5]
	s_waitcnt lgkmcnt(1)
	global_store_dwordx4 v[22:23], v[12:15], off nt
	s_add_i32 s19, s19, 1
	s_cmp_eq_u32 s19, 8
	v_add_co_u32_e32 v12, vcc, 0x6000, v20
	s_nop 1
	v_addc_co_u32_e32 v13, vcc, 0, v21, vcc
	s_waitcnt lgkmcnt(0)
	global_store_dwordx4 v[12:13], v[16:19], off nt
	s_cbranch_scc1 .LBB0_913
.LBB0_910:
	s_lshl_b32 s14, s19, 14
	s_lshl_b64 s[20:21], s[14:15], 2
	s_add_u32 s20, s3, s20
	s_addc_u32 s21, s16, s21
	v_lshl_add_u64 v[36:37], s[20:21], 0, v[106:107]
	v_add_co_u32_e32 v16, vcc, 0x2000, v36
	v_lshl_add_u64 v[20:21], s[20:21], 0, v[4:5]
	s_nop 0
	v_addc_co_u32_e32 v17, vcc, 0, v37, vcc
	v_add_co_u32_e32 v24, vcc, 0x6000, v36
	global_load_dwordx4 v[12:15], v[36:37], off nt
	s_nop 0
	global_load_dwordx4 v[16:19], v[16:17], off nt
	v_addc_co_u32_e32 v25, vcc, 0, v37, vcc
	v_add_co_u32_e32 v28, vcc, 0x8000, v36
	global_load_dwordx4 v[20:23], v[20:21], off nt
	s_nop 0
	global_load_dwordx4 v[24:27], v[24:25], off nt
	v_addc_co_u32_e32 v29, vcc, 0, v37, vcc
	v_add_co_u32_e32 v32, vcc, 0xa000, v36
	s_nop 1
	v_addc_co_u32_e32 v33, vcc, 0, v37, vcc
	v_add_co_u32_e32 v38, vcc, 0xc000, v36
	global_load_dwordx4 v[28:31], v[28:29], off nt
	s_nop 0
	global_load_dwordx4 v[32:35], v[32:33], off nt
	v_addc_co_u32_e32 v39, vcc, 0, v37, vcc
	v_add_co_u32_e32 v40, vcc, 0xe000, v36
	s_nop 1
	v_addc_co_u32_e32 v41, vcc, 0, v37, vcc
	global_load_dwordx4 v[36:39], v[38:39], off nt
	s_nop 0
	global_load_dwordx4 v[40:43], v[40:41], off nt
	s_and_b64 vcc, exec, s[0:1]
	s_waitcnt vmcnt(7)
	ds_write_b128 v10, v[12:15]
	s_waitcnt vmcnt(5)
	ds_write_b128 v10, v[20:23] offset:16384
	ds_write_b128 v10, v[16:19] offset:8192
	s_waitcnt vmcnt(4)
	ds_write_b128 v10, v[24:27] offset:24576
	s_waitcnt vmcnt(3)
	ds_write_b128 v10, v[28:31] offset:32768
	s_waitcnt vmcnt(2)
	ds_write_b128 v10, v[32:35] offset:40960
	s_waitcnt vmcnt(1)
	ds_write_b128 v10, v[36:39] offset:49152
	s_waitcnt vmcnt(0)
	ds_write_b128 v10, v[40:43] offset:57344
	s_waitcnt lgkmcnt(0)
	s_barrier
	s_cbranch_vccnz .LBB0_909
	s_mov_b32 s20, 0
	v_mov_b32_e32 v11, v9

; #define LAS __attribute__((address_space(3)))
; __device__ __forceinline__ void s5_group_phase(const Ctx& F, int g) {
;     ...
;     __threadfence(); __syncthreads();
;     LAS bf16_t* As = (LAS bf16_t*)F.lds;
;     bf16x8 bfr[2][12];
; #pragma unroll
;     for (int t2 = 0; t2 < 2; ++t2)
; #pragma unroll
;         for (int ks = 0; ks < 12; ++ks) bfr[t2][ks] = *(const bf16x8*)(KT + (size_t)((F.wave * 2 + t2) * 16 + fr) * 384 + ks * 32 + fq * 8);
;     u32x4 pu, px; px = (u32x4){0u, 0u, 0u, 0u};
;     pu = *(const u32x4*)(UG + (size_t)tid * 8); if (tid < 256) px = *(const u32x4*)(XC + (size_t)tid * 8);
;     *(LAS u32x4*)(As + (tid >> 5) * 392 + (tid & 31) * 8) = pu; if (tid < 256) *(LAS u32x4*)(As + (tid >> 4) * 392 + 256 + (tid & 15) * 8) = px;
.LBB0_913:
	s_mul_i32 s0, s8, 0x30000
	s_mul_hi_u32 s1, s8, 0x30000
	s_add_u32 s0, s92, s0
	s_addc_u32 s1, s93, s1
	v_and_b32_e32 v96, 48, v242
	v_mov_b32_e32 v97, 0
	v_and_b32_e32 v104, 15, v212
	v_lshl_add_u64 v[0:1], s[0:1], 0, v[96:97]
	s_mov_b64 s[0:1], 0x1f000000
	v_lshl_or_b32 v4, s94, 5, v104
	v_lshl_add_u64 v[0:1], v[0:1], 0, s[0:1]
	s_movk_i32 s3, 0x300
	v_mad_u64_u32 v[2:3], s[0:1], v4, s3, v[0:1]
	buffer_wbl2 sc1
	s_waitcnt vmcnt(0)
	buffer_inv sc1
	s_barrier
	global_load_dwordx4 v[88:91], v[2:3], off nt
	global_load_dwordx4 v[92:95], v[2:3], off offset:64 nt
	global_load_dwordx4 v[80:83], v[2:3], off offset:128 nt
	global_load_dwordx4 v[84:87], v[2:3], off offset:192 nt
	global_load_dwordx4 v[72:75], v[2:3], off offset:256 nt
	global_load_dwordx4 v[76:79], v[2:3], off offset:320 nt
	global_load_dwordx4 v[64:67], v[2:3], off offset:384 nt
	global_load_dwordx4 v[68:71], v[2:3], off offset:448 nt
	global_load_dwordx4 v[60:63], v[2:3], off offset:512 nt
	global_load_dwordx4 v[56:59], v[2:3], off offset:576 nt
	global_load_dwordx4 v[52:55], v[2:3], off offset:640 nt
	global_load_dwordx4 v[44:47], v[2:3], off offset:704 nt
	v_or_b32_e32 v2, 16, v4
	v_mad_u64_u32 v[0:1], s[0:1], v2, s3, v[0:1]
	global_load_dwordx4 v[48:51], v[0:1], off nt
	global_load_dwordx4 v[40:43], v[0:1], off offset:64 nt
	global_load_dwordx4 v[36:39], v[0:1], off offset:128 nt
	global_load_dwordx4 v[32:35], v[0:1], off offset:192 nt
	global_load_dwordx4 v[28:31], v[0:1], off offset:256 nt
	global_load_dwordx4 v[24:27], v[0:1], off offset:320 nt
	global_load_dwordx4 v[20:23], v[0:1], off offset:384 nt
	global_load_dwordx4 v[16:19], v[0:1], off offset:448 nt
	global_load_dwordx4 v[12:15], v[0:1], off offset:512 nt
	global_load_dwordx4 v[8:11], v[0:1], off offset:576 nt
	global_load_dwordx4 v[4:7], v[0:1], off offset:640 nt
	s_nop 0
	global_load_dwordx4 v[0:3], v[0:1], off offset:704 nt
	s_add_u32 s14, s92, s4
	s_addc_u32 s15, s93, s5
	v_lshlrev_b32_e32 v96, 4, v212
	v_lshl_add_u64 v[98:99], s[14:15], 0, v[96:97]
	s_mov_b32 s0, 0x28c00000
	v_add_co_u32_e32 v98, vcc, s0, v98
	s_movk_i32 s0, 0xff
	s_nop 0
	v_addc_co_u32_e32 v99, vcc, 0, v99, vcc
	global_load_dwordx4 v[100:103], v[98:99], off nt
	s_movk_i32 s3, 0x100
	v_cmp_lt_u32_e64 s[0:1], s0, v212
	v_cmp_gt_u32_e32 vcc, s3, v212
	v_mov_b32_e32 v96, v97
	v_mov_b32_e32 v98, v97
	v_mov_b32_e32 v99, v97
	s_and_saveexec_b64 s[14:15], vcc
	s_cbranch_execz .LBB0_915
	v_lshlrev_b32_e32 v96, 3, v212
	v_lshlrev_b32_e32 v96, 1, v96
	global_load_dwordx4 v[96:99], v96, s[12:13] nt

; #define LAS __attribute__((address_space(3)))
; __device__ __forceinline__ unsigned pk2(float lo, float hi) { return f2bf(lo) | (f2bf(hi) << 16); }
; __device__ __forceinline__ f32x4 mfma16(bf16x8 a, bf16x8 b, f32x4 c) { return __builtin_amdgcn_mfma_f32_16x16x32_bf16(a, b, c, 0, 0, 0); }
; __device__ __forceinline__ float gelu_tanh(float x) { const float z = 0.7978845608028654f * (x + 0.044715f * x * x * x); const float e = __expf(2.0f * z); const float th = 1.0f - 2.0f * __builtin_amdgcn_rcpf(e + 1.0f); return 0.5f * x * (1.0f + th); }
; __device__ __forceinline__ void s5_group_phase(const Ctx& F, int g) {
;     ...
;     for (int mt = 0; mt < 64; ++mt) {
;         const int c0 = mt * 16, buf = mt & 1;
;         if (mt + 1 < 64) { pu = *(const u32x4*)(UG + (size_t)(c0 + 16) * 256 + (size_t)tid * 8); if (tid < 256) px = *(const u32x4*)(XC + (size_t)(c0 + 16) * 128 + (size_t)tid * 8); }
;         bf16x8 a[12];
; #pragma unroll
;         for (int ks = 0; ks < 12; ++ks) a[ks] = *(const LAS bf16x8*)(As + buf * 6272 + fr * 392 + ks * 32 + fq * 8);
; #pragma unroll
;         for (int t2 = 0; t2 < 2; ++t2) {
;             f32x4 acc = (f32x4){0.f, 0.f, 0.f, 0.f};
; #pragma unroll
;             for (int ks = 0; ks < 12; ++ks) acc = mfma16(bfr[t2][ks], a[ks], acc);
;             const int t = F.wave * 2 + t2;
;             u32x2 w; w.x = pk2(gelu_tanh(acc[0]), gelu_tanh(acc[1])); w.y = pk2(gelu_tanh(acc[2]), gelu_tanh(acc[3]));
;             *(u32x2*)(YG + (size_t)((c0 + fr) * 16 + t) * 1024 + g * 16 + fq * 4) = w;
.LBB0_921:
	v_lshl_add_u64 v[100:101], s[92:93], 0, v[106:107]
	global_load_dwordx4 v[100:103], v[100:101], off nt
	s_and_saveexec_b64 s[0:1], vcc
	s_cbranch_execz .LBB0_923
	v_lshl_add_u64 v[96:97], s[92:93], 0, v[110:111]
	global_load_dwordx4 v[96:99], v[96:97], off nt
.LBB0_923:
	s_or_b64 exec, exec, s[0:1]
	s_and_b32 s16, s15, 1
	s_mul_i32 s0, s16, 0x3100
	v_add_u32_e32 v166, s0, v114
	ds_read_b128 v[118:121], v166
	ds_read_b128 v[122:125], v166 offset:64
	ds_read_b128 v[130:133], v166 offset:128
	ds_read_b128 v[134:137], v166 offset:192
	ds_read_b128 v[138:141], v166 offset:256
	ds_read_b128 v[142:145], v166 offset:320
	ds_read_b128 v[146:149], v166 offset:384
	ds_read_b128 v[150:153], v166 offset:448
	s_waitcnt lgkmcnt(7)
	v_mfma_f32_16x16x32_bf16 v[126:129], v[88:91], v[118:121], 0
	ds_read_b128 v[154:157], v166 offset:512
	ds_read_b128 v[158:161], v166 offset:576
	ds_read_b128 v[162:165], v166 offset:640
	ds_read_b128 v[166:169], v166 offset:704
	s_waitcnt lgkmcnt(10)
	v_mfma_f32_16x16x32_bf16 v[126:129], v[92:95], v[122:125], v[126:129]
	s_waitcnt lgkmcnt(9)
	v_mfma_f32_16x16x32_bf16 v[126:129], v[80:83], v[130:133], v[126:129]
	s_waitcnt lgkmcnt(8)
	v_mfma_f32_16x16x32_bf16 v[126:129], v[84:87], v[134:137], v[126:129]
	s_waitcnt lgkmcnt(7)
	v_mfma_f32_16x16x32_bf16 v[126:129], v[72:75], v[138:141], v[126:129]
	s_waitcnt lgkmcnt(6)
	v_mfma_f32_16x16x32_bf16 v[126:129], v[76:79], v[142:145], v[126:129]
	v_mfma_f32_16x16x32_bf16 v[118:121], v[48:51], v[118:121], 0
	s_waitcnt lgkmcnt(5)
	v_mfma_f32_16x16x32_bf16 v[126:129], v[64:67], v[146:149], v[126:129]
	v_mfma_f32_16x16x32_bf16 v[118:121], v[40:43], v[122:125], v[118:121]
	s_waitcnt lgkmcnt(4)
	v_mfma_f32_16x16x32_bf16 v[126:129], v[68:71], v[150:153], v[126:129]
	v_mfma_f32_16x16x32_bf16 v[118:121], v[36:39], v[130:133], v[118:121]
	s_waitcnt lgkmcnt(3)
	v_mfma_f32_16x16x32_bf16 v[126:129], v[60:63], v[154:157], v[126:129]
	v_mfma_f32_16x16x32_bf16 v[118:121], v[32:35], v[134:137], v[118:121]
	s_waitcnt lgkmcnt(2)
	v_mfma_f32_16x16x32_bf16 v[126:129], v[56:59], v[158:161], v[126:129]
	v_mfma_f32_16x16x32_bf16 v[118:121], v[28:31], v[138:141], v[118:121]
	s_waitcnt lgkmcnt(1)
	v_mfma_f32_16x16x32_bf16 v[126:129], v[52:55], v[162:165], v[126:129]
	v_mfma_f32_16x16x32_bf16 v[118:121], v[24:27], v[142:145], v[118:121]
	s_waitcnt lgkmcnt(0)
	v_mfma_f32_16x16x32_bf16 v[122:125], v[44:47], v[166:169], v[126:129]
	v_mfma_f32_16x16x32_bf16 v[118:121], v[20:23], v[146:149], v[118:121]
	v_mfma_f32_16x16x32_bf16 v[118:121], v[16:19], v[150:153], v[118:121]
	s_nop 5
	v_mul_f32_e32 v128, 0x3d372713, v122
	v_mul_f32_e32 v170, 0x3d372713, v124
	v_mul_f32_e32 v129, 0x3d372713, v123
	v_mul_f32_e32 v128, v122, v128
	v_mul_f32_e32 v170, v124, v170
	v_mul_f32_e32 v171, 0x3d372713, v125
	v_mov_b32_e32 v126, v122
	v_mov_b32_e32 v127, v124
	v_mul_f32_e32 v129, v123, v129
	v_fma_f32 v122, v122, v128, v122
	v_fma_f32 v124, v124, v170, v124
	v_mul_f32_e32 v171, v125, v171
	v_fma_f32 v128, v123, v129, v123
	v_mul_f32_e32 v122, 0x3f4c422a, v122
	v_mul_f32_e32 v124, 0x3f4c422a, v124
	v_fma_f32 v129, v125, v171, v125
	v_mul_f32_e32 v128, 0x3f4c422a, v128
	v_add_f32_e32 v122, v122, v122
	v_add_f32_e32 v124, v124, v124
	v_mul_f32_e32 v129, 0x3f4c422a, v129
	v_add_f32_e32 v128, v128, v128
	v_mul_f32_e32 v122, 0x3fb8aa3b, v122
	v_mul_f32_e32 v124, 0x3fb8aa3b, v124
	v_mfma_f32_16x16x32_bf16 v[118:121], v[12:15], v[154:157], v[118:121]
	v_add_f32_e32 v129, v129, v129
	v_mul_f32_e32 v128, 0x3fb8aa3b, v128
	v_exp_f32_e32 v122, v122
	v_exp_f32_e32 v124, v124
	v_mul_f32_e32 v129, 0x3fb8aa3b, v129
	v_exp_f32_e32 v128, v128
	v_exp_f32_e32 v130, v129
	v_mfma_f32_16x16x32_bf16 v[118:121], v[8:11], v[158:161], v[118:121]
	v_add_f32_e32 v122, 1.0, v122
	v_add_f32_e32 v124, 1.0, v124
	v_add_f32_e32 v131, 1.0, v128
	v_rcp_f32_e32 v128, v122
	v_rcp_f32_e32 v129, v124
	v_add_f32_e32 v122, 1.0, v130
	v_rcp_f32_e32 v130, v131
	v_rcp_f32_e32 v131, v122
	v_mfma_f32_16x16x32_bf16 v[118:121], v[4:7], v[162:165], v[118:121]
	v_fma_f32 v128, -v128, 2.0, 1.0
	v_fma_f32 v129, -v129, 2.0, 1.0
	v_pk_mul_f32 v[126:127], v[126:127], 0.5 op_sel_hi:[1,0]
	v_pk_add_f32 v[128:129], v[128:129], 1.0 op_sel_hi:[1,0]
	v_mov_b32_e32 v124, v123
	v_pk_mul_f32 v[126:127], v[126:127], v[128:129]
	v_pk_fma_f32 v[128:129], v[130:131], 2.0, 1.0 op_sel_hi:[1,0,0] neg_lo:[1,0,0] neg_hi:[1,0,0]
	v_mfma_f32_16x16x32_bf16 v[118:121], v[0:3], v[166:169], v[118:121]
	v_mul_f32_e64 v122, v124, 0.5
	v_mul_f32_e64 v123, v125, 0.5
	v_pk_add_f32 v[124:125], v[128:129], 1.0 op_sel_hi:[1,0]
	s_nop 0
	v_pk_mul_f32 v[122:123], v[122:123], v[124:125]
	v_and_b32_sdwa v124, v127, v117 dst_sel:DWORD dst_unused:UNUSED_PAD src0_sel:WORD_1 src1_sel:DWORD
	v_and_b32_sdwa v125, v126, v117 dst_sel:DWORD dst_unused:UNUSED_PAD src0_sel:WORD_1 src1_sel:DWORD
	v_add3_u32 v125, v126, v125, s3
	v_add3_u32 v124, v127, v124, s3
	v_and_b32_sdwa v126, v123, v117 dst_sel:DWORD dst_unused:UNUSED_PAD src0_sel:WORD_1 src1_sel:DWORD
	v_and_b32_sdwa v127, v122, v117 dst_sel:DWORD dst_unused:UNUSED_PAD src0_sel:WORD_1 src1_sel:DWORD
	v_add3_u32 v123, v123, v126, s3
	v_add3_u32 v122, v122, v127, s3
	v_mul_f32_e32 v126, 0x3d372713, v118
	v_mul_f32_e32 v127, 0x3d372713, v119
	v_mul_f32_e32 v126, v118, v126
	v_mul_f32_e32 v127, v119, v127
	v_fma_f32 v126, v118, v126, v118
	v_fma_f32 v127, v119, v127, v119
	v_mul_f32_e32 v126, 0x3f4c422a, v126
	v_mul_f32_e32 v127, 0x3f4c422a, v127
	v_add_f32_e32 v126, v126, v126
	v_add_f32_e32 v127, v127, v127
	v_and_b32_e32 v123, 0xffff0000, v123
	v_and_b32_e32 v122, 0xffff0000, v122
	v_mul_f32_e32 v126, 0x3fb8aa3b, v126
	v_mul_f32_e32 v127, 0x3fb8aa3b, v127
; #define LAS __attribute__((address_space(3)))
; __device__ __forceinline__ unsigned pk2(float lo, float hi) { return f2bf(lo) | (f2bf(hi) << 16); }
; __device__ __forceinline__ f32x4 mfma16(bf16x8 a, bf16x8 b, f32x4 c) { return __builtin_amdgcn_mfma_f32_16x16x32_bf16(a, b, c, 0, 0, 0); }
; __device__ __forceinline__ float gelu_tanh(float x) { const float z = 0.7978845608028654f * (x + 0.044715f * x * x * x); const float e = __expf(2.0f * z); const float th = 1.0f - 2.0f * __builtin_amdgcn_rcpf(e + 1.0f); return 0.5f * x * (1.0f + th); }
; __device__ __forceinline__ void s5_group_phase(const Ctx& F, int g) {
;     ...
;         for (int t2 = 0; t2 < 2; ++t2) {
;             f32x4 acc = (f32x4){0.f, 0.f, 0.f, 0.f};
; #pragma unroll
;             for (int ks = 0; ks < 12; ++ks) acc = mfma16(bfr[t2][ks], a[ks], acc);
;             const int t = F.wave * 2 + t2;
;             u32x2 w; w.x = pk2(gelu_tanh(acc[0]), gelu_tanh(acc[1])); w.y = pk2(gelu_tanh(acc[2]), gelu_tanh(acc[3]));
;             *(u32x2*)(YG + (size_t)((c0 + fr) * 16 + t) * 1024 + g * 16 + fq * 4) = w;
;         }
;         if (mt + 1 < 64) { *(LAS u32x4*)(As + (buf ^ 1) * 6272 + (tid >> 5) * 392 + (tid & 31) * 8) = pu; if (tid < 256) *(LAS u32x4*)(As + (buf ^ 1) * 6272 + (tid >> 4) * 392 + 256 + (tid & 15) * 8) = px; }
;         __syncthreads();
	v_or_b32_sdwa v123, v123, v124 dst_sel:DWORD dst_unused:UNUSED_PAD src0_sel:DWORD src1_sel:WORD_1
	v_or_b32_sdwa v122, v122, v125 dst_sel:DWORD dst_unused:UNUSED_PAD src0_sel:DWORD src1_sel:WORD_1
	v_lshl_add_u64 v[124:125], s[92:93], 0, v[108:109]
	v_exp_f32_e32 v126, v126
	v_exp_f32_e32 v127, v127
	v_add_co_u32_e64 v124, s[0:1], s14, v124
	v_mov_b32_e32 v128, v118
	s_nop 0
	v_addc_co_u32_e64 v125, s[0:1], 0, v125, s[0:1]
	global_store_dwordx2 v[124:125], v[122:123], off nt
	v_mul_f32_e32 v123, 0x3d372713, v120
	v_add_f32_e32 v122, 1.0, v126
	v_add_f32_e32 v126, 1.0, v127
	v_mul_f32_e32 v123, v120, v123
	v_mul_f32_e32 v127, 0x3d372713, v121
	v_fma_f32 v123, v120, v123, v120
	v_mul_f32_e32 v127, v121, v127
	v_mul_f32_e32 v123, 0x3f4c422a, v123
	v_fma_f32 v127, v121, v127, v121
	v_add_f32_e32 v123, v123, v123
	v_mul_f32_e32 v127, 0x3f4c422a, v127
	v_mul_f32_e32 v123, 0x3fb8aa3b, v123
	v_add_f32_e32 v127, v127, v127
	v_exp_f32_e32 v123, v123
	v_mul_f32_e32 v127, 0x3fb8aa3b, v127
	v_exp_f32_e32 v127, v127
	v_rcp_f32_e32 v122, v122
	v_add_f32_e32 v123, 1.0, v123
	v_rcp_f32_e32 v123, v123
	v_add_f32_e32 v127, 1.0, v127
	v_rcp_f32_e32 v126, v126
	v_rcp_f32_e32 v127, v127
	v_pk_fma_f32 v[122:123], v[122:123], 2.0, 1.0 op_sel_hi:[1,0,0] neg_lo:[1,0,0] neg_hi:[1,0,0]
	v_mov_b32_e32 v129, v120
	v_pk_mul_f32 v[128:129], v[128:129], 0.5 op_sel_hi:[1,0]
	v_pk_add_f32 v[122:123], v[122:123], 1.0 op_sel_hi:[1,0]
	v_pk_fma_f32 v[126:127], v[126:127], 2.0, 1.0 op_sel_hi:[1,0,0] neg_lo:[1,0,0] neg_hi:[1,0,0]
	v_mov_b32_e32 v120, v119
	v_pk_mul_f32 v[122:123], v[128:129], v[122:123]
	v_pk_mul_f32 v[118:119], v[120:121], 0.5 op_sel_hi:[1,0]
	v_pk_add_f32 v[120:121], v[126:127], 1.0 op_sel_hi:[1,0]
	s_xor_b32 s0, s16, 1
	v_pk_mul_f32 v[118:119], v[118:119], v[120:121]
	v_and_b32_sdwa v120, v123, v117 dst_sel:DWORD dst_unused:UNUSED_PAD src0_sel:WORD_1 src1_sel:DWORD
	v_and_b32_sdwa v121, v122, v117 dst_sel:DWORD dst_unused:UNUSED_PAD src0_sel:WORD_1 src1_sel:DWORD
	v_add3_u32 v121, v122, v121, s3
	v_add3_u32 v120, v123, v120, s3
	v_and_b32_sdwa v122, v119, v117 dst_sel:DWORD dst_unused:UNUSED_PAD src0_sel:WORD_1 src1_sel:DWORD
	v_and_b32_sdwa v123, v118, v117 dst_sel:DWORD dst_unused:UNUSED_PAD src0_sel:WORD_1 src1_sel:DWORD
	v_add3_u32 v119, v119, v122, s3
	v_add3_u32 v118, v118, v123, s3
	v_and_b32_e32 v119, 0xffff0000, v119
	v_and_b32_e32 v118, 0xffff0000, v118
	s_mulk_i32 s0, 0x3100
	v_or_b32_sdwa v119, v119, v120 dst_sel:DWORD dst_unused:UNUSED_PAD src0_sel:DWORD src1_sel:WORD_1
	v_or_b32_sdwa v118, v118, v121 dst_sel:DWORD dst_unused:UNUSED_PAD src0_sel:DWORD src1_sel:WORD_1
	s_add_i32 s16, s0, 0
	global_store_dwordx2 v[124:125], v[118:119], off offset:2048 nt
	v_add3_u32 v118, s16, v113, v115
	s_waitcnt vmcnt(2)
	ds_write_b128 v118, v[100:103]
	s_and_saveexec_b64 s[0:1], vcc
	s_cbranch_execz .LBB0_920
	v_add3_u32 v100, s16, v116, v105
	ds_write_b128 v100, v[96:99] offset:512
	s_branch .LBB0_920
.LBB0_925:
	ds_read_b128 v[96:99], v114 offset:12544
	ds_read_b128 v[100:103], v114 offset:12608
	s_lshl_b64 s[0:1], s[8:9], 1
	s_add_u32 s0, s92, s0
	v_lshlrev_b32_e32 v110, 3, v112
	s_waitcnt lgkmcnt(1)
	v_mfma_f32_16x16x32_bf16 v[88:91], v[88:91], v[96:99], 0
	v_mov_b32_e32 v111, 0
	s_addc_u32 s1, s93, s1
	s_mov_b64 s[4:5], 0x26c00000
	v_mfma_f32_16x16x32_bf16 v[48:51], v[48:51], v[96:99], 0
	s_waitcnt lgkmcnt(0)
	v_mfma_f32_16x16x32_bf16 v[88:91], v[92:95], v[100:103], v[88:91]
	ds_read_b128 v[92:95], v114 offset:12672
	ds_read_b128 v[106:109], v114 offset:12736
	v_mfma_f32_16x16x32_bf16 v[40:43], v[40:43], v[100:103], v[48:51]
	s_waitcnt lgkmcnt(1)
	v_mfma_f32_16x16x32_bf16 v[80:83], v[80:83], v[92:95], v[88:91]
	v_mfma_f32_16x16x32_bf16 v[36:39], v[36:39], v[92:95], v[40:43]
	s_waitcnt lgkmcnt(0)
	v_mfma_f32_16x16x32_bf16 v[80:83], v[84:87], v[106:109], v[80:83]
	ds_read_b128 v[84:87], v114 offset:12800
	ds_read_b128 v[88:91], v114 offset:12864
	v_mfma_f32_16x16x32_bf16 v[32:35], v[32:35], v[106:109], v[36:39]
	s_waitcnt lgkmcnt(1)
	v_mfma_f32_16x16x32_bf16 v[72:75], v[72:75], v[84:87], v[80:83]
	v_mfma_f32_16x16x32_bf16 v[28:31], v[28:31], v[84:87], v[32:35]
	s_waitcnt lgkmcnt(0)
	v_mfma_f32_16x16x32_bf16 v[72:75], v[76:79], v[88:91], v[72:75]
	ds_read_b128 v[76:79], v114 offset:12928
	ds_read_b128 v[80:83], v114 offset:12992
	v_mfma_f32_16x16x32_bf16 v[24:27], v[24:27], v[88:91], v[28:31]
	s_waitcnt lgkmcnt(1)
	v_mfma_f32_16x16x32_bf16 v[64:67], v[64:67], v[76:79], v[72:75]
	s_nop 0
	v_mov_b32_e32 v30, 1
	v_mfma_f32_16x16x32_bf16 v[20:23], v[20:23], v[76:79], v[24:27]
	s_waitcnt lgkmcnt(0)
	v_mfma_f32_16x16x32_bf16 v[64:67], v[68:71], v[80:83], v[64:67]
	ds_read_b128 v[68:71], v114 offset:13056
	ds_read_b128 v[72:75], v114 offset:13120
	v_mfma_f32_16x16x32_bf16 v[16:19], v[16:19], v[80:83], v[20:23]
	s_waitcnt lgkmcnt(1)
	v_mfma_f32_16x16x32_bf16 v[12:15], v[12:15], v[68:71], v[16:19]
	v_mfma_f32_16x16x32_bf16 v[60:63], v[60:63], v[68:71], v[64:67]
	s_nop 2
	ds_read_b128 v[64:67], v114 offset:13184
	s_waitcnt lgkmcnt(1)
	v_mfma_f32_16x16x32_bf16 v[8:11], v[8:11], v[72:75], v[12:15]
	v_mfma_f32_16x16x32_bf16 v[56:59], v[56:59], v[72:75], v[60:63]
	s_nop 2
	ds_read_b128 v[60:63], v114 offset:13248
	s_waitcnt lgkmcnt(1)
	v_mfma_f32_16x16x32_bf16 v[4:7], v[4:7], v[64:67], v[8:11]
	v_mfma_f32_16x16x32_bf16 v[52:55], v[52:55], v[64:67], v[56:59]
	s_waitcnt lgkmcnt(0)
; #define LAS __attribute__((address_space(3)))
; __device__ __forceinline__ unsigned pk2(float lo, float hi) { return f2bf(lo) | (f2bf(hi) << 16); }
; __device__ __forceinline__ f32x4 mfma16(bf16x8 a, bf16x8 b, f32x4 c) { return __builtin_amdgcn_mfma_f32_16x16x32_bf16(a, b, c, 0, 0, 0); }
; __device__ __forceinline__ float gelu_tanh(float x) { const float z = 0.7978845608028654f * (x + 0.044715f * x * x * x); const float e = __expf(2.0f * z); const float th = 1.0f - 2.0f * __builtin_amdgcn_rcpf(e + 1.0f); return 0.5f * x * (1.0f + th); }
; __device__ __forceinline__ void s5_group_phase(const Ctx& F, int g) {
;     ...
;         for (int t2 = 0; t2 < 2; ++t2) {
;             f32x4 acc = (f32x4){0.f, 0.f, 0.f, 0.f};
; #pragma unroll
;             for (int ks = 0; ks < 12; ++ks) acc = mfma16(bfr[t2][ks], a[ks], acc);
;             const int t = F.wave * 2 + t2;
;             u32x2 w; w.x = pk2(gelu_tanh(acc[0]), gelu_tanh(acc[1])); w.y = pk2(gelu_tanh(acc[2]), gelu_tanh(acc[3]));
;             *(u32x2*)(YG + (size_t)((c0 + fr) * 16 + t) * 1024 + g * 16 + fq * 4) = w;
;         }
;         if (mt + 1 < 64) { *(LAS u32x4*)(As + (buf ^ 1) * 6272 + (tid >> 5) * 392 + (tid & 31) * 8) = pu; if (tid < 256) *(LAS u32x4*)(As + (buf ^ 1) * 6272 + (tid >> 4) * 392 + 256 + (tid & 15) * 8) = px; }
;         __syncthreads();
	v_mfma_f32_16x16x32_bf16 v[0:3], v[0:3], v[60:63], v[4:7]
	s_nop 0
	v_lshl_add_u64 v[56:57], s[0:1], 0, v[110:111]
	s_movk_i32 s0, 0x7fff
	v_add_u32_e32 v110, 0x3f00, v104
	v_mfma_f32_16x16x32_bf16 v[44:47], v[44:47], v[60:63], v[52:55]
	v_lshl_add_u64 v[56:57], v[56:57], 0, s[4:5]
	s_nop 1
	v_mul_f32_e32 v5, 0x3d372713, v1
	v_mul_f32_e32 v5, v1, v5
	v_fma_f32 v5, v1, v5, v1
	v_mul_f32_e32 v5, 0x3f4c422a, v5
	s_nop 0
	v_mul_f32_e32 v53, 0x3d372713, v45
	v_mul_f32_e32 v55, 0x3d372713, v47
	v_mul_f32_e32 v52, 0x3d372713, v44
	v_mul_f32_e32 v54, 0x3d372713, v46
	v_mul_f32_e32 v53, v45, v53
	v_mul_f32_e32 v55, v47, v55
	v_add_f32_e32 v5, v5, v5
	v_mul_f32_e32 v52, v44, v52
	v_mul_f32_e32 v54, v46, v54
	v_fma_f32 v53, v45, v53, v45
	v_fma_f32 v55, v47, v55, v47
	v_mul_f32_e32 v5, 0x3fb8aa3b, v5
	v_fma_f32 v52, v44, v52, v44
	v_fma_f32 v54, v46, v54, v46
	v_mul_f32_e32 v53, 0x3f4c422a, v53
	v_mul_f32_e32 v55, 0x3f4c422a, v55
	v_exp_f32_e32 v5, v5
	v_mul_f32_e32 v52, 0x3f4c422a, v52
	v_mul_f32_e32 v54, 0x3f4c422a, v54
	v_add_f32_e32 v53, v53, v53
	v_add_f32_e32 v55, v55, v55
	v_add_f32_e32 v52, v52, v52
	v_add_f32_e32 v54, v54, v54
	v_mul_f32_e32 v53, 0x3fb8aa3b, v53
	v_mul_f32_e32 v55, 0x3fb8aa3b, v55
	v_mul_f32_e32 v52, 0x3fb8aa3b, v52
	v_mul_f32_e32 v54, 0x3fb8aa3b, v54
	v_exp_f32_e32 v53, v53
	v_exp_f32_e32 v55, v55
	v_exp_f32_e32 v52, v52
	v_exp_f32_e32 v58, v54
	v_mul_f32_e32 v4, 0x3d372713, v0
	v_add_f32_e32 v6, 1.0, v5
	v_mul_f32_e32 v5, 0x3d372713, v2
	v_mul_f32_e32 v4, v0, v4
	v_mul_f32_e32 v5, v2, v5
	v_mul_f32_e32 v7, 0x3d372713, v3
	v_fma_f32 v4, v0, v4, v0
	v_fma_f32 v5, v2, v5, v2
	v_mul_f32_e32 v7, v3, v7
	v_add_f32_e32 v53, 1.0, v53
	v_add_f32_e32 v48, 1.0, v55
	v_mul_f32_e32 v4, 0x3f4c422a, v4
	v_mul_f32_e32 v5, 0x3f4c422a, v5
	v_fma_f32 v7, v3, v7, v3
	v_add_f32_e32 v52, 1.0, v52
	v_rcp_f32_e32 v54, v53
	v_add_f32_e32 v53, 1.0, v58
	v_rcp_f32_e32 v55, v48
	v_add_f32_e32 v4, v4, v4
	v_add_f32_e32 v5, v5, v5
	v_mul_f32_e32 v7, 0x3f4c422a, v7
	v_rcp_f32_e32 v52, v52
	v_rcp_f32_e32 v53, v53
	v_mul_f32_e32 v4, 0x3fb8aa3b, v4
	v_mul_f32_e32 v5, 0x3fb8aa3b, v5
	v_add_f32_e32 v7, v7, v7
	v_exp_f32_e32 v4, v4
	v_exp_f32_e32 v5, v5
	v_mul_f32_e32 v7, 0x3fb8aa3b, v7
	v_exp_f32_e32 v7, v7
	v_mov_b32_e32 v41, v46
	v_pk_fma_f32 v[38:39], v[54:55], 2.0, 1.0 op_sel_hi:[1,0,0] neg_lo:[1,0,0] neg_hi:[1,0,0]
	v_mov_b32_e32 v46, v45
	v_pk_fma_f32 v[48:49], v[52:53], 2.0, 1.0 op_sel_hi:[1,0,0] neg_lo:[1,0,0] neg_hi:[1,0,0]
	v_mov_b32_e32 v40, v44
	v_pk_mul_f32 v[32:33], v[46:47], 0.5 op_sel_hi:[1,0]
	v_pk_add_f32 v[34:35], v[38:39], 1.0 op_sel_hi:[1,0]
	v_pk_mul_f32 v[40:41], v[40:41], 0.5 op_sel_hi:[1,0]
	v_pk_add_f32 v[36:37], v[48:49], 1.0 op_sel_hi:[1,0]
	v_pk_mul_f32 v[28:29], v[32:33], v[34:35]
	v_add_f32_e32 v4, 1.0, v4
	v_add_f32_e32 v5, 1.0, v5
	v_pk_mul_f32 v[36:37], v[40:41], v[36:37]
	v_and_b32_sdwa v21, v29, v30 dst_sel:DWORD dst_unused:UNUSED_PAD src0_sel:WORD_1 src1_sel:DWORD
	v_and_b32_sdwa v22, v28, v30 dst_sel:DWORD dst_unused:UNUSED_PAD src0_sel:WORD_1 src1_sel:DWORD
	v_rcp_f32_e32 v4, v4
	v_rcp_f32_e32 v5, v5
	v_add_f32_e32 v7, 1.0, v7
	v_and_b32_sdwa v31, v37, v30 dst_sel:DWORD dst_unused:UNUSED_PAD src0_sel:WORD_1 src1_sel:DWORD
	v_and_b32_sdwa v24, v36, v30 dst_sel:DWORD dst_unused:UNUSED_PAD src0_sel:WORD_1 src1_sel:DWORD
	v_add3_u32 v16, v29, v21, s0
	v_add3_u32 v17, v28, v22, s0
	v_rcp_f32_e32 v6, v6
	v_rcp_f32_e32 v7, v7
	v_add3_u32 v24, v36, v24, s0
	v_add3_u32 v20, v37, v31, s0
	v_and_b32_e32 v16, 0xffff0000, v16
	v_and_b32_e32 v12, 0xffff0000, v17
	v_lshlrev_b64 v[8:9], 11, v[110:111]
	v_or_b32_sdwa v13, v16, v20 dst_sel:DWORD dst_unused:UNUSED_PAD src0_sel:DWORD src1_sel:WORD_1
	v_or_b32_sdwa v12, v12, v24 dst_sel:DWORD dst_unused:UNUSED_PAD src0_sel:DWORD src1_sel:WORD_1
	v_lshl_add_u64 v[8:9], v[56:57], 0, v[8:9]
	global_store_dwordx2 v[8:9], v[12:13], off nt
	v_pk_fma_f32 v[4:5], v[4:5], 2.0, 1.0 op_sel_hi:[1,0,0] neg_lo:[1,0,0] neg_hi:[1,0,0]
	v_mov_b32_e32 v8, v0
	v_mov_b32_e32 v9, v2
	v_pk_mul_f32 v[8:9], v[8:9], 0.5 op_sel_hi:[1,0]
	v_pk_add_f32 v[4:5], v[4:5], 1.0 op_sel_hi:[1,0]
	v_pk_fma_f32 v[6:7], v[6:7], 2.0, 1.0 op_sel_hi:[1,0,0] neg_lo:[1,0,0] neg_hi:[1,0,0]
	v_mov_b32_e32 v2, v1
	v_pk_mul_f32 v[4:5], v[8:9], v[4:5]
	v_pk_mul_f32 v[0:1], v[2:3], 0.5 op_sel_hi:[1,0]
	v_pk_add_f32 v[2:3], v[6:7], 1.0 op_sel_hi:[1,0]
	v_add_u32_e32 v110, 0x3f01, v104
	v_pk_mul_f32 v[0:1], v[0:1], v[2:3]
	v_and_b32_sdwa v2, v5, v30 dst_sel:DWORD dst_unused:UNUSED_PAD src0_sel:WORD_1 src1_sel:DWORD
	v_and_b32_sdwa v3, v4, v30 dst_sel:DWORD dst_unused:UNUSED_PAD src0_sel:WORD_1 src1_sel:DWORD
	v_add3_u32 v3, v4, v3, s0
	v_add3_u32 v2, v5, v2, s0
	v_and_b32_sdwa v4, v1, v30 dst_sel:DWORD dst_unused:UNUSED_PAD src0_sel:WORD_1 src1_sel:DWORD
	v_and_b32_sdwa v5, v0, v30 dst_sel:DWORD dst_unused:UNUSED_PAD src0_sel:WORD_1 src1_sel:DWORD
	v_add3_u32 v1, v1, v4, s0
	v_add3_u32 v0, v0, v5, s0
	v_and_b32_e32 v1, 0xffff0000, v1
	v_and_b32_e32 v0, 0xffff0000, v0
	v_or_b32_sdwa v1, v1, v2 dst_sel:DWORD dst_unused:UNUSED_PAD src0_sel:DWORD src1_sel:WORD_1
	v_or_b32_sdwa v0, v0, v3 dst_sel:DWORD dst_unused:UNUSED_PAD src0_sel:DWORD src1_sel:WORD_1
	v_lshlrev_b64 v[2:3], 11, v[110:111]
	v_lshl_add_u64 v[2:3], v[56:57], 0, v[2:3]
	global_store_dwordx2 v[2:3], v[0:1], off nt
	s_barrier

; #define LAS __attribute__((address_space(3)))
; __device__ __forceinline__ void transpose_item(const float* W, int K, int Nsrc, int c0, bf16_t* WT, int mode, LAS float* scr, int kb, int nb, int lane) {
;     const int k0 = 64 * kb, n0 = 32 * nb;
;     float tv[32];
; #pragma unroll
;     for (int i = 0; i < 32; ++i) { const int kk = 2 * i + (lane >> 5); tv[i] = W[(size_t)(k0 + kk) * Nsrc + c0 + n0 + (lane & 31)]; }
; #pragma unroll
;     for (int i = 0; i < 32; ++i) { const int kk = 2 * i + (lane >> 5); scr[kk * 33 + (lane & 31)] = tv[i]; }
.LBB0_1720:
	s_addk_i32 s4, 0x300
	s_and_b32 s10, s4, 0x7fffffc0
	s_and_b32 s9, s5, 0x7e0
	v_or_b32_e32 v4, s10, v66
	v_mov_b32_e32 v11, v5
	v_mov_b32_e32 v13, v5
	v_mov_b32_e32 v15, v5
	v_mov_b32_e32 v17, v5
	v_mov_b32_e32 v19, v5
	v_mov_b32_e32 v21, v5
	v_mov_b32_e32 v23, v5
	v_mov_b32_e32 v25, v5
	v_mov_b32_e32 v33, v5
	s_lshl_b32 s0, s9, 2
	v_or_b32_e32 v10, 2, v4
	v_or_b32_e32 v12, 4, v4
	v_or_b32_e32 v14, 6, v4
	v_or_b32_e32 v16, 8, v4
	v_or_b32_e32 v18, 10, v4
	v_or_b32_e32 v20, 12, v4
	v_or_b32_e32 v22, 14, v4
	v_or_b32_e32 v24, 16, v4
	v_or_b32_e32 v32, 24, v4
	v_mov_b32_e32 v27, v5
	v_mov_b32_e32 v29, v5
	v_mov_b32_e32 v31, v5
	v_mov_b32_e32 v35, v5
	v_mov_b32_e32 v37, v5
	v_mov_b32_e32 v39, v5
	v_mov_b32_e32 v41, v5
	v_mov_b32_e32 v43, v5
	v_mov_b32_e32 v45, v5
	v_mov_b32_e32 v47, v5
	v_mov_b32_e32 v49, v5
	v_mov_b32_e32 v51, v5
	v_mov_b32_e32 v53, v5
	v_mov_b32_e32 v55, v5
	v_mov_b32_e32 v57, v5
	v_mov_b32_e32 v59, v5
	v_mov_b32_e32 v61, v5
	v_mov_b32_e32 v63, v5
	v_mov_b32_e32 v65, v5
	v_mov_b32_e32 v79, v5
	v_mov_b32_e32 v81, v5
	v_or_b32_e32 v90, s9, v68
	v_lshl_add_u64 v[82:83], v[6:7], 0, s[0:1]
	s_lshl_b32 s0, s10, 1
	v_lshlrev_b64 v[84:85], 13, v[4:5]
	v_or_b32_e32 v26, 18, v4
	v_or_b32_e32 v28, 20, v4
	v_or_b32_e32 v30, 22, v4
	v_or_b32_e32 v34, 26, v4
	v_or_b32_e32 v36, 28, v4
	v_or_b32_e32 v38, 30, v4
	v_or_b32_e32 v40, 32, v4
	v_or_b32_e32 v42, 34, v4
	v_or_b32_e32 v44, 36, v4
	v_or_b32_e32 v46, 38, v4
	v_or_b32_e32 v48, 40, v4
	v_or_b32_e32 v50, 42, v4
	v_or_b32_e32 v52, 44, v4
	v_or_b32_e32 v54, 46, v4
	v_or_b32_e32 v56, 48, v4
	v_or_b32_e32 v58, 50, v4
	v_or_b32_e32 v60, 52, v4
	v_or_b32_e32 v62, 54, v4
	v_or_b32_e32 v64, 56, v4
	v_or_b32_e32 v78, 58, v4
	v_or_b32_e32 v80, 60, v4
	v_or_b32_e32 v4, 62, v4
	v_lshlrev_b64 v[10:11], 13, v[10:11]
	v_lshlrev_b64 v[12:13], 13, v[12:13]
	v_lshlrev_b64 v[14:15], 13, v[14:15]
	v_lshlrev_b64 v[16:17], 13, v[16:17]
	v_lshlrev_b64 v[18:19], 13, v[18:19]
	v_lshlrev_b64 v[20:21], 13, v[20:21]
	v_lshlrev_b64 v[22:23], 13, v[22:23]
	v_lshlrev_b64 v[24:25], 13, v[24:25]
	v_lshlrev_b64 v[32:33], 13, v[32:33]
	v_or_b32_e32 v91, s9, v70
	v_lshl_add_u64 v[86:87], v[8:9], 0, s[0:1]
	v_lshl_add_u64 v[84:85], v[82:83], 0, v[84:85]
	v_lshlrev_b64 v[26:27], 13, v[26:27]
	v_lshlrev_b64 v[28:29], 13, v[28:29]
	v_lshlrev_b64 v[30:31], 13, v[30:31]
	v_lshlrev_b64 v[34:35], 13, v[34:35]
	v_lshlrev_b64 v[36:37], 13, v[36:37]
	v_lshlrev_b64 v[38:39], 13, v[38:39]
	v_lshlrev_b64 v[40:41], 13, v[40:41]
	v_lshlrev_b64 v[42:43], 13, v[42:43]
	v_lshlrev_b64 v[44:45], 13, v[44:45]
	v_lshlrev_b64 v[46:47], 13, v[46:47]
	v_lshlrev_b64 v[48:49], 13, v[48:49]
	v_lshlrev_b64 v[50:51], 13, v[50:51]
	v_lshlrev_b64 v[52:53], 13, v[52:53]
	v_lshlrev_b64 v[54:55], 13, v[54:55]
	v_lshlrev_b64 v[56:57], 13, v[56:57]
	v_lshlrev_b64 v[58:59], 13, v[58:59]
	v_lshlrev_b64 v[60:61], 13, v[60:61]
	v_lshlrev_b64 v[62:63], 13, v[62:63]
	v_lshlrev_b64 v[64:65], 13, v[64:65]
	v_lshlrev_b64 v[78:79], 13, v[78:79]
	v_lshlrev_b64 v[80:81], 13, v[80:81]
	v_lshlrev_b64 v[88:89], 13, v[4:5]
	v_lshlrev_b32_e32 v4, 12, v90
	v_lshl_add_u64 v[10:11], v[82:83], 0, v[10:11]
	v_lshl_add_u64 v[12:13], v[82:83], 0, v[12:13]
	v_lshl_add_u64 v[14:15], v[82:83], 0, v[14:15]
	v_lshl_add_u64 v[16:17], v[82:83], 0, v[16:17]
	v_lshl_add_u64 v[18:19], v[82:83], 0, v[18:19]
	v_lshl_add_u64 v[20:21], v[82:83], 0, v[20:21]
	v_lshl_add_u64 v[22:23], v[82:83], 0, v[22:23]
	v_lshl_add_u64 v[24:25], v[82:83], 0, v[24:25]
	v_lshl_add_u64 v[32:33], v[82:83], 0, v[32:33]
	v_lshl_add_u64 v[26:27], v[82:83], 0, v[26:27]
	v_lshl_add_u64 v[28:29], v[82:83], 0, v[28:29]
	v_lshl_add_u64 v[30:31], v[82:83], 0, v[30:31]
	v_lshl_add_u64 v[34:35], v[82:83], 0, v[34:35]
	v_lshl_add_u64 v[36:37], v[82:83], 0, v[36:37]
	v_lshl_add_u64 v[38:39], v[82:83], 0, v[38:39]
	v_lshl_add_u64 v[40:41], v[82:83], 0, v[40:41]
	v_lshl_add_u64 v[42:43], v[82:83], 0, v[42:43]
	v_lshl_add_u64 v[44:45], v[82:83], 0, v[44:45]
	v_lshl_add_u64 v[46:47], v[82:83], 0, v[46:47]
	v_lshl_add_u64 v[48:49], v[82:83], 0, v[48:49]
	v_lshl_add_u64 v[50:51], v[82:83], 0, v[50:51]
	v_lshl_add_u64 v[52:53], v[82:83], 0, v[52:53]
	v_lshl_add_u64 v[54:55], v[82:83], 0, v[54:55]
	v_lshl_add_u64 v[56:57], v[82:83], 0, v[56:57]
	v_lshl_add_u64 v[58:59], v[82:83], 0, v[58:59]
	v_lshl_add_u64 v[60:61], v[82:83], 0, v[60:61]
	v_lshl_add_u64 v[62:63], v[82:83], 0, v[62:63]
	v_lshl_add_u64 v[64:65], v[82:83], 0, v[64:65]
	v_lshl_add_u64 v[78:79], v[82:83], 0, v[78:79]
	v_lshl_add_u64 v[80:81], v[82:83], 0, v[80:81]
	v_lshl_add_u64 v[82:83], v[82:83], 0, v[88:89]
	v_lshl_add_u64 v[88:89], v[86:87], 0, v[4:5]
	v_lshlrev_b32_e32 v4, 12, v91
	global_load_dword v90, v[84:85], off nt
	global_load_dword v91, v[10:11], off nt
	global_load_dword v94, v[12:13], off nt
	global_load_dword v95, v[14:15], off nt
	global_load_dword v96, v[16:17], off nt
	global_load_dword v97, v[18:19], off nt
	global_load_dword v98, v[20:21], off nt
	global_load_dword v99, v[22:23], off nt
	global_load_dword v100, v[24:25], off nt
	global_load_dword v101, v[26:27], off nt
	global_load_dword v102, v[28:29], off nt
	global_load_dword v103, v[30:31], off nt
	global_load_dword v104, v[32:33], off nt
	global_load_dword v105, v[34:35], off nt
	global_load_dword v106, v[36:37], off nt
	global_load_dword v10, v[38:39], off nt
	global_load_dword v11, v[40:41], off nt
	global_load_dword v12, v[42:43], off nt
	global_load_dword v13, v[44:45], off nt
	global_load_dword v14, v[46:47], off nt
	global_load_dword v15, v[48:49], off nt
	global_load_dword v16, v[50:51], off nt
	global_load_dword v17, v[52:53], off nt
	global_load_dword v18, v[54:55], off nt
	global_load_dword v19, v[56:57], off nt
	global_load_dword v20, v[58:59], off nt
	global_load_dword v21, v[60:61], off nt
	global_load_dword v22, v[62:63], off nt
	global_load_dword v23, v[64:65], off nt
	global_load_dword v24, v[78:79], off nt
	global_load_dword v25, v[80:81], off nt
	global_load_dword v32, v[82:83], off nt
	s_waitcnt vmcnt(30)
; #define LAS __attribute__((address_space(3)))
; __device__ __forceinline__ unsigned pk2(float lo, float hi) { return f2bf(lo) | (f2bf(hi) << 16); }
; __device__ __forceinline__ void transpose_item(const float* W, int K, int Nsrc, int c0, bf16_t* WT, int mode, LAS float* scr, int kb, int nb, int lane) {
;     ...
;     for (int i = 0; i < 32; ++i) { const int kk = 2 * i + (lane >> 5); scr[kk * 33 + (lane & 31)] = tv[i]; }
;     asm volatile("s_waitcnt lgkmcnt(0)" ::: "memory");
;     const int c = lane & 7;
; #pragma unroll
;     for (int j = 0; j < 4; ++j) { const int n = (lane >> 3) + 8 * j; const LAS float* s = scr + (8 * c) * 33 + n;
;         u32x4 o; o.x = pk2(s[0 * 33], s[1 * 33]); o.y = pk2(s[2 * 33], s[3 * 33]); o.z = pk2(s[4 * 33], s[5 * 33]); o.w = pk2(s[6 * 33], s[7 * 33]);
;         const int nn = n0 + n; const int row = (mode == 0) ? nn : ((nn >> 7) * 256 + (nn & 127) + (mode == 2 ? 128 : 0));
;         *(u32x4*)(WT + (size_t)row * K + k0 + 8 * c) = o; }
;     asm volatile("s_waitcnt lgkmcnt(0)" ::: "memory");
	ds_write2_b32 v67, v90, v91 offset1:66
	s_waitcnt vmcnt(28)
	ds_write2_b32 v67, v94, v95 offset0:132 offset1:198
	s_waitcnt vmcnt(26)
	ds_write2_b32 v1, v96, v97 offset0:8 offset1:74
	s_waitcnt vmcnt(24)
	ds_write2_b32 v1, v98, v99 offset0:140 offset1:206
	s_waitcnt vmcnt(22)
	ds_write2_b32 v3, v100, v101 offset0:16 offset1:82
	s_waitcnt vmcnt(20)
	ds_write2_b32 v3, v102, v103 offset0:148 offset1:214
	s_waitcnt vmcnt(18)
	ds_write2_b32 v73, v104, v105 offset0:24 offset1:90
	s_waitcnt vmcnt(16)
	ds_write2_b32 v73, v106, v10 offset0:156 offset1:222
	s_waitcnt vmcnt(14)
	ds_write2_b32 v74, v11, v12 offset0:32 offset1:98
	s_waitcnt vmcnt(12)
	ds_write2_b32 v74, v13, v14 offset0:164 offset1:230
	s_waitcnt vmcnt(10)
	ds_write2_b32 v75, v15, v16 offset0:40 offset1:106
	s_waitcnt vmcnt(8)
	ds_write2_b32 v75, v17, v18 offset0:172 offset1:238
	s_waitcnt vmcnt(6)
	ds_write2_b32 v76, v19, v20 offset0:48 offset1:114
	s_waitcnt vmcnt(4)
	ds_write2_b32 v76, v21, v22 offset0:180 offset1:246
	s_waitcnt vmcnt(2)
	ds_write2_b32 v77, v23, v24 offset0:56 offset1:122
	s_waitcnt vmcnt(0)
	ds_write2_b32 v77, v25, v32 offset0:188 offset1:254
	s_waitcnt lgkmcnt(0)
	v_or_b32_e32 v92, s9, v71
	ds_read2_b32 v[10:11], v69 offset0:33 offset1:41
	ds_read2_b32 v[12:13], v69 offset1:8
	ds_read2_b32 v[14:15], v69 offset0:66 offset1:74
	ds_read2_b32 v[16:17], v69 offset0:99 offset1:107
	ds_read2_b32 v[18:19], v69 offset0:132 offset1:140
	ds_read2_b32 v[20:21], v69 offset0:165 offset1:173
	ds_read2_b32 v[22:23], v69 offset0:198 offset1:206
	ds_read2_b32 v[24:25], v69 offset0:231 offset1:239
	ds_read2_b32 v[32:33], v69 offset0:49 offset1:57
	ds_read2_b32 v[34:35], v69 offset0:16 offset1:24
	ds_read2_b32 v[36:37], v69 offset0:82 offset1:90
	ds_read2_b32 v[38:39], v69 offset0:115 offset1:123
	ds_read2_b32 v[40:41], v69 offset0:148 offset1:156
	ds_read2_b32 v[42:43], v69 offset0:181 offset1:189
	ds_read2_b32 v[44:45], v69 offset0:214 offset1:222
	ds_read2_b32 v[46:47], v69 offset0:247 offset1:255
	v_or_b32_e32 v93, s9, v72
	v_lshl_add_u64 v[26:27], v[86:87], 0, v[4:5]
	v_lshlrev_b32_e32 v4, 12, v92
	v_lshl_add_u64 v[28:29], v[86:87], 0, v[4:5]
	v_lshlrev_b32_e32 v4, 12, v93
	v_lshl_add_u64 v[30:31], v[86:87], 0, v[4:5]
	s_waitcnt lgkmcnt(14)
	v_bfe_u32 v4, v12, 16, 1
	s_waitcnt lgkmcnt(13)
	v_bfe_u32 v49, v14, 16, 1
	s_waitcnt lgkmcnt(12)
	v_bfe_u32 v50, v16, 16, 1
	s_waitcnt lgkmcnt(11)
	v_bfe_u32 v51, v18, 16, 1
	s_waitcnt lgkmcnt(10)
	v_bfe_u32 v52, v20, 16, 1
	s_waitcnt lgkmcnt(9)
	v_bfe_u32 v53, v22, 16, 1
	v_bfe_u32 v48, v10, 16, 1
	s_waitcnt lgkmcnt(8)
	v_bfe_u32 v54, v24, 16, 1
	v_bfe_u32 v55, v13, 16, 1
	v_bfe_u32 v56, v11, 16, 1
	v_bfe_u32 v57, v15, 16, 1
	v_bfe_u32 v58, v17, 16, 1
	v_bfe_u32 v59, v19, 16, 1
	v_bfe_u32 v60, v21, 16, 1
	v_bfe_u32 v61, v23, 16, 1
	v_bfe_u32 v62, v25, 16, 1
	s_waitcnt lgkmcnt(6)
	v_bfe_u32 v63, v34, 16, 1
	s_waitcnt lgkmcnt(5)
	v_bfe_u32 v65, v36, 16, 1
	s_waitcnt lgkmcnt(4)
	v_bfe_u32 v78, v38, 16, 1
	s_waitcnt lgkmcnt(3)
	v_bfe_u32 v79, v40, 16, 1
	s_waitcnt lgkmcnt(2)
	v_bfe_u32 v80, v42, 16, 1
	s_waitcnt lgkmcnt(1)
	v_bfe_u32 v81, v44, 16, 1
	v_bfe_u32 v83, v35, 16, 1
	v_bfe_u32 v85, v37, 16, 1
	v_bfe_u32 v87, v41, 16, 1
	v_bfe_u32 v91, v45, 16, 1
	v_add3_u32 v4, v12, v4, s7
	v_add3_u32 v12, v14, v49, s7
	v_add3_u32 v14, v16, v50, s7
	v_add3_u32 v16, v18, v51, s7
	v_add3_u32 v18, v20, v52, s7
	v_add3_u32 v20, v22, v53, s7
	v_bfe_u32 v64, v32, 16, 1
	s_waitcnt lgkmcnt(0)
	v_bfe_u32 v82, v46, 16, 1
	v_bfe_u32 v84, v33, 16, 1
	v_bfe_u32 v86, v39, 16, 1
	v_bfe_u32 v90, v43, 16, 1
	v_bfe_u32 v92, v47, 16, 1
	v_add3_u32 v10, v10, v48, s7
	v_add3_u32 v22, v24, v54, s7
	v_add3_u32 v13, v13, v55, s7
	v_add3_u32 v24, v11, v56, s7
	v_add3_u32 v11, v15, v57, s7
	v_add3_u32 v15, v17, v58, s7
	v_add3_u32 v17, v19, v59, s7
	v_add3_u32 v19, v21, v60, s7
	v_add3_u32 v21, v23, v61, s7
	v_add3_u32 v23, v25, v62, s7
	v_add3_u32 v25, v34, v63, s7
	v_add3_u32 v34, v36, v65, s7
	v_add3_u32 v36, v38, v78, s7
	v_add3_u32 v38, v40, v79, s7
	v_add3_u32 v40, v42, v80, s7
	v_add3_u32 v42, v44, v81, s7
	v_add3_u32 v35, v35, v83, s7
	v_add3_u32 v37, v37, v85, s7
	v_add3_u32 v41, v41, v87, s7
	v_add3_u32 v45, v45, v91, s7
	v_lshrrev_b32_e32 v4, 16, v4
	v_lshrrev_b32_e32 v12, 16, v12
	v_lshrrev_b32_e32 v16, 16, v16
	v_lshrrev_b32_e32 v20, 16, v20
	v_add3_u32 v32, v32, v64, s7
	v_add3_u32 v44, v46, v82, s7
	v_add3_u32 v33, v33, v84, s7
	v_add3_u32 v39, v39, v86, s7
	v_add3_u32 v43, v43, v90, s7
	v_add3_u32 v46, v47, v92, s7
	v_lshrrev_b32_e32 v47, 16, v13
	v_lshrrev_b32_e32 v48, 16, v11
	v_lshrrev_b32_e32 v17, 16, v17
	v_lshrrev_b32_e32 v21, 16, v21
	v_lshrrev_b32_e32 v25, 16, v25
	v_lshrrev_b32_e32 v34, 16, v34
	v_lshrrev_b32_e32 v38, 16, v38
	v_lshrrev_b32_e32 v42, 16, v42
	v_lshrrev_b32_e32 v35, 16, v35
	v_lshrrev_b32_e32 v37, 16, v37
	v_lshrrev_b32_e32 v41, 16, v41
	v_lshrrev_b32_e32 v45, 16, v45
	v_and_or_b32 v10, v10, s8, v4
	v_and_or_b32 v11, v14, s8, v12
	v_and_or_b32 v12, v18, s8, v16
	v_and_or_b32 v13, v22, s8, v20
	v_and_or_b32 v14, v24, s8, v47
	v_and_or_b32 v15, v15, s8, v48
	v_and_or_b32 v16, v19, s8, v17
	v_and_or_b32 v17, v23, s8, v21
	v_and_or_b32 v18, v32, s8, v25
	v_and_or_b32 v19, v36, s8, v34
	v_and_or_b32 v20, v40, s8, v38
	v_and_or_b32 v21, v44, s8, v42
	v_and_or_b32 v22, v33, s8, v35
	v_and_or_b32 v23, v39, s8, v37
	v_and_or_b32 v24, v43, s8, v41
	v_and_or_b32 v25, v46, s8, v45
	global_store_dwordx4 v[88:89], v[10:13], off nt
	global_store_dwordx4 v[26:27], v[14:17], off nt
	global_store_dwordx4 v[28:29], v[18:21], off nt
	global_store_dwordx4 v[30:31], v[22:25], off nt
	s_waitcnt lgkmcnt(0)
	s_addk_i32 s5, 0x6000
	s_cmpk_lt_u32 s4, 0x500
	s_cbranch_scc1 .LBB0_1720
; __device__ __forceinline__ void transpose_item(const float* W, int K, int Nsrc, int c0, bf16_t* WT, int mode, LAS float* scr, int kb, int nb, int lane) {
;     ...
;     for (int i = 0; i < 32; ++i) { const int kk = 2 * i + (lane >> 5); tv[i] = W[(size_t)(k0 + kk) * Nsrc + c0 + n0 + (lane & 31)]; }
; #pragma unroll
;     for (int i = 0; i < 32; ++i) { const int kk = 2 * i + (lane >> 5); scr[kk * 33 + (lane & 31)] = tv[i]; }
; __device__ __forceinline__ void convert_layer1_rest_idle(const Ctx& F, int first_idle, int end_idle) {
;     ...
;     tr_job(F, base, P.in[38], 2048, 5632, 0, 5632, 1, (bf16_t*)(Wb + W_GU1), scr, gw, NGW);
	s_add_i32 s0, s3, 0xfffffd00
	s_mul_hi_u32 s1, s0, 0xaaaaaaab
	s_lshr_b32 s1, s1, 9
	v_mov_b32_e32 v7, 0
	s_mulk_i32 s1, 0x300
	v_readlane_b32 s8, v247, 44
	v_lshlrev_b32_e32 v2, 1, v2
	v_mov_b32_e32 v3, v7
	s_sub_i32 s4, s0, s1
	v_lshlrev_b32_e32 v0, 2, v0
	v_mov_b32_e32 v1, v7
	v_readlane_b32 s9, v247, 45
	v_readlane_b32 s10, v247, 46
	v_readlane_b32 s11, v247, 47
	v_readlane_b32 s12, v247, 48
	v_readlane_b32 s13, v247, 49
	v_readlane_b32 s14, v247, 50
	v_readlane_b32 s15, v247, 51
	v_readlane_b32 s16, v247, 52
	v_readlane_b32 s17, v247, 53
	v_readlane_b32 s18, v247, 54
	v_readlane_b32 s19, v247, 55
	v_readlane_b32 s20, v247, 56
	v_readlane_b32 s21, v247, 57
	v_readlane_b32 s22, v247, 58
	v_readlane_b32 s23, v247, 59
	v_lshl_add_u64 v[4:5], s[92:93], 0, v[2:3]
	s_mov_b64 s[0:1], 0x2800000
	v_lshl_add_u64 v[8:9], s[20:21], 0, v[0:1]
	v_lshl_add_u64 v[4:5], v[4:5], 0, s[0:1]
	s_mov_b32 s1, 0
	s_mov_b32 s5, 0xb000
	s_mov_b32 s7, 0x16000
	s_mov_b32 s8, 0x21000
	s_mov_b32 s9, 0x2c000
	s_mov_b32 s10, 0x37000
	s_mov_b32 s11, 0x42000
	s_mov_b32 s12, 0x4d000
	s_mov_b32 s13, 0x58000
	s_mov_b32 s14, 0x63000
	s_mov_b32 s15, 0x6e000
	s_mov_b32 s16, 0x79000
	s_mov_b32 s17, 0x84000
	s_mov_b32 s18, 0x8f000
	s_mov_b32 s19, 0x9a000
	s_mov_b32 s20, 0xa5000
	s_mov_b32 s21, 0xb0000
	s_mov_b32 s22, 0xbb000
	s_mov_b32 s23, 0xc6000
	s_mov_b32 s24, 0xd1000
	s_mov_b32 s25, 0xdc000
	s_mov_b32 s26, 0xe7000
	s_mov_b32 s27, 0xf2000
	s_mov_b32 s28, 0xfd000
	s_mov_b32 s29, 0x108000
	s_mov_b32 s30, 0x113000
	s_mov_b32 s31, 0x11e000
	s_mov_b32 s34, 0x129000
	s_mov_b32 s35, 0x134000
	s_mov_b32 s38, 0x13f000
	s_mov_b32 s39, 0x14a000
	s_mov_b32 s40, 0x155000
	s_movk_i32 s41, 0x7fff
	s_mov_b32 s42, 0xffff0000
.LBB0_1722:
	s_and_b32 s0, s4, 0xffff
	s_mul_i32 s0, s0, 0xba2f
	s_lshr_b32 s43, s0, 23
	s_mul_i32 s0, s43, 0xb0
	s_sub_i32 s0, s4, s0
	s_and_b32 s44, s0, 0xffff
	v_lshl_or_b32 v6, s43, 6, v66
	s_lshl_b32 s0, s44, 7
	v_mul_u32_u24_e32 v6, 0x5800, v6
	v_lshl_add_u64 v[10:11], v[8:9], 0, s[0:1]
	v_lshl_add_u64 v[12:13], v[10:11], 0, v[6:7]
	s_lshl_b32 s45, s44, 5
	s_lshl_b32 s44, s44, 6
	v_add_co_u32_e32 v10, vcc, s5, v12
	s_lshl_b32 s0, s43, 7
	s_and_b32 s43, s44, 0x3f00
	s_and_b32 s44, s45, 0x60
	v_addc_co_u32_e32 v11, vcc, 0, v13, vcc
	v_lshl_add_u64 v[14:15], v[4:5], 0, s[0:1]
	s_or_b32 s0, s43, s44
	v_add_co_u32_e32 v16, vcc, s7, v12
	v_or_b32_e32 v6, s0, v68
	s_nop 0
	v_addc_co_u32_e32 v17, vcc, 0, v13, vcc
	v_or_b32_e32 v19, s0, v70
	v_lshlrev_b32_e32 v6, 12, v6
	v_add_co_u32_e32 v18, vcc, s8, v12
	global_load_dword v27, v[12:13], off nt
	global_load_dword v34, v[10:11], off nt
	v_lshl_add_u64 v[10:11], v[14:15], 0, v[6:7]
	v_lshlrev_b32_e32 v6, 12, v19
	v_addc_co_u32_e32 v19, vcc, 0, v13, vcc
	v_or_b32_e32 v21, s0, v71
	v_add_co_u32_e32 v20, vcc, s9, v12
	v_lshl_add_u64 v[28:29], v[14:15], 0, v[6:7]
	v_lshlrev_b32_e32 v6, 12, v21
	v_addc_co_u32_e32 v21, vcc, 0, v13, vcc
	global_load_dword v35, v[16:17], off nt
	global_load_dword v36, v[18:19], off nt
	v_add_co_u32_e32 v16, vcc, s10, v12
	v_or_b32_e32 v32, s0, v72
	s_nop 0
	v_addc_co_u32_e32 v17, vcc, 0, v13, vcc
	v_add_co_u32_e32 v18, vcc, s11, v12
	v_lshl_add_u64 v[30:31], v[14:15], 0, v[6:7]
	v_lshlrev_b32_e32 v6, 12, v32
	v_addc_co_u32_e32 v19, vcc, 0, v13, vcc
	v_lshl_add_u64 v[32:33], v[14:15], 0, v[6:7]
	v_add_co_u32_e32 v14, vcc, s12, v12
	global_load_dword v6, v[20:21], off nt
	s_nop 0
	global_load_dword v20, v[16:17], off nt
	v_addc_co_u32_e32 v15, vcc, 0, v13, vcc
	v_add_co_u32_e32 v16, vcc, s13, v12
	global_load_dword v21, v[18:19], off nt
	global_load_dword v37, v[14:15], off nt
	v_addc_co_u32_e32 v17, vcc, 0, v13, vcc
	v_add_co_u32_e32 v14, vcc, s14, v12
	v_add_u32_e32 v1, 0x400, v67
	s_nop 0
	v_addc_co_u32_e32 v15, vcc, 0, v13, vcc
	v_add_co_u32_e32 v18, vcc, s15, v12
	global_load_dword v38, v[16:17], off nt
	global_load_dword v39, v[14:15], off nt
	v_addc_co_u32_e32 v19, vcc, 0, v13, vcc
	v_add_co_u32_e32 v14, vcc, s16, v12
	v_add_u32_e32 v3, 0x800, v67
	s_nop 0
	v_addc_co_u32_e32 v15, vcc, 0, v13, vcc
	v_add_co_u32_e32 v16, vcc, s17, v12
	global_load_dword v40, v[18:19], off nt
	global_load_dword v41, v[14:15], off nt
	v_addc_co_u32_e32 v17, vcc, 0, v13, vcc
	v_add_co_u32_e32 v14, vcc, s18, v12
	v_add_u32_e32 v22, 0xc00, v67
	s_nop 0
	v_addc_co_u32_e32 v15, vcc, 0, v13, vcc
	v_add_co_u32_e32 v18, vcc, s19, v12
	global_load_dword v42, v[16:17], off nt
	global_load_dword v43, v[14:15], off nt
	v_addc_co_u32_e32 v19, vcc, 0, v13, vcc
	v_add_co_u32_e32 v14, vcc, s20, v12
	v_add_u32_e32 v23, 0x1000, v67
	s_nop 0
	v_addc_co_u32_e32 v15, vcc, 0, v13, vcc
	v_add_co_u32_e32 v16, vcc, s21, v12
	global_load_dword v44, v[18:19], off nt
	global_load_dword v45, v[14:15], off nt
	v_addc_co_u32_e32 v17, vcc, 0, v13, vcc
	v_add_co_u32_e32 v14, vcc, s22, v12
	v_add_u32_e32 v24, 0x1400, v67
	s_nop 0
	v_addc_co_u32_e32 v15, vcc, 0, v13, vcc
	v_add_co_u32_e32 v18, vcc, s23, v12
	global_load_dword v46, v[16:17], off nt
	global_load_dword v47, v[14:15], off nt
	v_addc_co_u32_e32 v19, vcc, 0, v13, vcc
	v_add_co_u32_e32 v14, vcc, s24, v12
	v_add_u32_e32 v25, 0x1800, v67
	s_nop 0
	v_addc_co_u32_e32 v15, vcc, 0, v13, vcc
	v_add_co_u32_e32 v16, vcc, s25, v12
	global_load_dword v48, v[18:19], off nt
	global_load_dword v49, v[14:15], off nt
	v_addc_co_u32_e32 v17, vcc, 0, v13, vcc
	v_add_co_u32_e32 v14, vcc, s26, v12
	v_add_u32_e32 v26, 0x1c00, v67
	s_nop 0
	v_addc_co_u32_e32 v15, vcc, 0, v13, vcc
	v_add_co_u32_e32 v18, vcc, s27, v12
	global_load_dword v50, v[16:17], off nt
	global_load_dword v51, v[14:15], off nt
	v_addc_co_u32_e32 v19, vcc, 0, v13, vcc
	v_add_co_u32_e32 v14, vcc, s28, v12
	s_add_i32 s0, s4, 0x300
	s_nop 0
	v_addc_co_u32_e32 v15, vcc, 0, v13, vcc
	v_add_co_u32_e32 v16, vcc, s29, v12
	global_load_dword v52, v[18:19], off nt
	global_load_dword v53, v[14:15], off nt
	v_addc_co_u32_e32 v17, vcc, 0, v13, vcc
	v_add_co_u32_e32 v14, vcc, s30, v12
	s_cmpk_lt_u32 s4, 0x1300
	s_nop 0
	v_addc_co_u32_e32 v15, vcc, 0, v13, vcc
	v_add_co_u32_e32 v18, vcc, s31, v12
	global_load_dword v54, v[16:17], off nt
	global_load_dword v55, v[14:15], off nt
	v_addc_co_u32_e32 v19, vcc, 0, v13, vcc
	v_add_co_u32_e32 v14, vcc, s34, v12
	s_mov_b32 s4, s0
	s_nop 0
	v_addc_co_u32_e32 v15, vcc, 0, v13, vcc
	v_add_co_u32_e32 v16, vcc, s35, v12
	global_load_dword v56, v[18:19], off nt
	global_load_dword v57, v[14:15], off nt
	v_addc_co_u32_e32 v17, vcc, 0, v13, vcc
	v_add_co_u32_e32 v14, vcc, s38, v12
	s_nop 1
	v_addc_co_u32_e32 v15, vcc, 0, v13, vcc
	v_add_co_u32_e32 v18, vcc, s39, v12
	global_load_dword v16, v[16:17], off nt
	s_nop 0
	global_load_dword v14, v[14:15], off nt
	v_addc_co_u32_e32 v19, vcc, 0, v13, vcc
	v_add_co_u32_e32 v12, vcc, s40, v12
	s_nop 1
	v_addc_co_u32_e32 v13, vcc, 0, v13, vcc
	global_load_dword v15, v[18:19], off nt
	s_nop 0
	global_load_dword v12, v[12:13], off nt
	s_waitcnt vmcnt(30)
; #define LAS __attribute__((address_space(3)))
; __device__ __forceinline__ unsigned pk2(float lo, float hi) { return f2bf(lo) | (f2bf(hi) << 16); }
; __device__ __forceinline__ void transpose_item(const float* W, int K, int Nsrc, int c0, bf16_t* WT, int mode, LAS float* scr, int kb, int nb, int lane) {
;     ...
;     for (int i = 0; i < 32; ++i) { const int kk = 2 * i + (lane >> 5); scr[kk * 33 + (lane & 31)] = tv[i]; }
;     asm volatile("s_waitcnt lgkmcnt(0)" ::: "memory");
;     const int c = lane & 7;
; #pragma unroll
;     for (int j = 0; j < 4; ++j) { const int n = (lane >> 3) + 8 * j; const LAS float* s = scr + (8 * c) * 33 + n;
;         u32x4 o; o.x = pk2(s[0 * 33], s[1 * 33]); o.y = pk2(s[2 * 33], s[3 * 33]); o.z = pk2(s[4 * 33], s[5 * 33]); o.w = pk2(s[6 * 33], s[7 * 33]);
;         const int nn = n0 + n; const int row = (mode == 0) ? nn : ((nn >> 7) * 256 + (nn & 127) + (mode == 2 ? 128 : 0));
;         *(u32x4*)(WT + (size_t)row * K + k0 + 8 * c) = o; }
;     if (gw < 0) { gw = F.bid * 8 + F.wave; NGW = F.G * 8; }
;     const int nnb = ncols / 32, items = (K / 64) * nnb;
;     const int first = (gw - base % NGW + NGW) % NGW;
;     for (int it = first; it < items; it += NGW) transpose_item(W, K, Nsrc, c0, WT, mode, scr, it / nnb, it % nnb, F.lane);
;     base += items;
	ds_write2_b32 v67, v27, v34 offset1:66
	s_waitcnt vmcnt(28)
	ds_write2_b32 v67, v35, v36 offset0:132 offset1:198
	s_waitcnt vmcnt(26)
	ds_write2_b32 v1, v6, v20 offset0:8 offset1:74
	s_waitcnt vmcnt(24)
	ds_write2_b32 v1, v21, v37 offset0:140 offset1:206
	s_waitcnt vmcnt(22)
	ds_write2_b32 v3, v38, v39 offset0:16 offset1:82
	s_waitcnt vmcnt(20)
	ds_write2_b32 v3, v40, v41 offset0:148 offset1:214
	s_waitcnt vmcnt(18)
	ds_write2_b32 v22, v42, v43 offset0:24 offset1:90
	s_waitcnt vmcnt(16)
	ds_write2_b32 v22, v44, v45 offset0:156 offset1:222
	s_waitcnt vmcnt(14)
	ds_write2_b32 v23, v46, v47 offset0:32 offset1:98
	s_waitcnt vmcnt(12)
	ds_write2_b32 v23, v48, v49 offset0:164 offset1:230
	s_waitcnt vmcnt(10)
	ds_write2_b32 v24, v50, v51 offset0:40 offset1:106
	s_waitcnt vmcnt(8)
	ds_write2_b32 v24, v52, v53 offset0:172 offset1:238
	s_waitcnt vmcnt(6)
	ds_write2_b32 v25, v54, v55 offset0:48 offset1:114
	s_waitcnt vmcnt(4)
	ds_write2_b32 v25, v56, v57 offset0:180 offset1:246
	s_waitcnt vmcnt(2)
	ds_write2_b32 v26, v16, v14 offset0:56 offset1:122
	s_waitcnt vmcnt(0)
	ds_write2_b32 v26, v15, v12 offset0:188 offset1:254
	s_waitcnt lgkmcnt(0)
	ds_read2_b32 v[12:13], v69 offset0:33 offset1:41
	ds_read2_b32 v[14:15], v69 offset1:8
	ds_read2_b32 v[16:17], v69 offset0:66 offset1:74
	ds_read2_b32 v[18:19], v69 offset0:99 offset1:107
	ds_read2_b32 v[20:21], v69 offset0:132 offset1:140
	ds_read2_b32 v[22:23], v69 offset0:165 offset1:173
	ds_read2_b32 v[24:25], v69 offset0:198 offset1:206
	ds_read2_b32 v[26:27], v69 offset0:231 offset1:239
	ds_read2_b32 v[34:35], v69 offset0:49 offset1:57
	ds_read2_b32 v[36:37], v69 offset0:16 offset1:24
	ds_read2_b32 v[38:39], v69 offset0:82 offset1:90
	ds_read2_b32 v[40:41], v69 offset0:115 offset1:123
	ds_read2_b32 v[42:43], v69 offset0:148 offset1:156
	ds_read2_b32 v[44:45], v69 offset0:181 offset1:189
	ds_read2_b32 v[46:47], v69 offset0:214 offset1:222
	ds_read2_b32 v[48:49], v69 offset0:247 offset1:255
	s_waitcnt lgkmcnt(14)
	v_bfe_u32 v1, v14, 16, 1
	v_bfe_u32 v3, v12, 16, 1
	s_waitcnt lgkmcnt(13)
	v_bfe_u32 v6, v16, 16, 1
	s_waitcnt lgkmcnt(12)
	v_bfe_u32 v50, v18, 16, 1
	s_waitcnt lgkmcnt(11)
	v_bfe_u32 v51, v20, 16, 1
	s_waitcnt lgkmcnt(9)
	v_bfe_u32 v53, v24, 16, 1
	v_bfe_u32 v52, v22, 16, 1
	s_waitcnt lgkmcnt(8)
	v_bfe_u32 v54, v26, 16, 1
	v_bfe_u32 v55, v15, 16, 1
	v_bfe_u32 v56, v13, 16, 1
	v_bfe_u32 v57, v17, 16, 1
	v_bfe_u32 v58, v19, 16, 1
	v_bfe_u32 v59, v21, 16, 1
	v_bfe_u32 v60, v23, 16, 1
	v_bfe_u32 v61, v25, 16, 1
	v_bfe_u32 v62, v27, 16, 1
	s_waitcnt lgkmcnt(6)
	v_bfe_u32 v63, v36, 16, 1
	v_bfe_u32 v64, v34, 16, 1
	s_waitcnt lgkmcnt(5)
	v_bfe_u32 v65, v38, 16, 1
	s_waitcnt lgkmcnt(4)
	v_bfe_u32 v73, v40, 16, 1
	s_waitcnt lgkmcnt(3)
	v_bfe_u32 v74, v42, 16, 1
	s_waitcnt lgkmcnt(2)
	v_bfe_u32 v75, v44, 16, 1
	s_waitcnt lgkmcnt(1)
	v_bfe_u32 v76, v46, 16, 1
	v_bfe_u32 v78, v37, 16, 1
	v_bfe_u32 v80, v39, 16, 1
	v_bfe_u32 v82, v43, 16, 1
	v_bfe_u32 v83, v45, 16, 1
	v_bfe_u32 v84, v47, 16, 1
	v_add3_u32 v1, v14, v1, s41
	v_add3_u32 v3, v12, v3, s41
	v_add3_u32 v6, v16, v6, s41
	v_add3_u32 v14, v18, v50, s41
	v_add3_u32 v12, v20, v51, s41
	v_add3_u32 v18, v24, v53, s41
	s_waitcnt lgkmcnt(0)
	v_bfe_u32 v77, v48, 16, 1
	v_bfe_u32 v79, v35, 16, 1
	v_bfe_u32 v81, v41, 16, 1
	v_bfe_u32 v85, v49, 16, 1
	v_add3_u32 v16, v22, v52, s41
	v_add3_u32 v20, v26, v54, s41
	v_add3_u32 v15, v15, v55, s41
	v_add3_u32 v22, v13, v56, s41
	v_add3_u32 v13, v17, v57, s41
	v_add3_u32 v17, v19, v58, s41
	v_add3_u32 v19, v21, v59, s41
	v_add3_u32 v21, v23, v60, s41
	v_add3_u32 v23, v25, v61, s41
	v_add3_u32 v24, v27, v62, s41
	v_add3_u32 v25, v36, v63, s41
	v_add3_u32 v26, v34, v64, s41
	v_add3_u32 v27, v38, v65, s41
	v_add3_u32 v34, v40, v73, s41
	v_add3_u32 v36, v42, v74, s41
	v_add3_u32 v38, v44, v75, s41
	v_add3_u32 v40, v46, v76, s41
	v_add3_u32 v37, v37, v78, s41
	v_add3_u32 v39, v39, v80, s41
	v_add3_u32 v43, v43, v82, s41
	v_add3_u32 v44, v45, v83, s41
	v_add3_u32 v45, v47, v84, s41
	v_lshrrev_b32_e32 v1, 16, v1
	v_lshrrev_b32_e32 v6, 16, v6
	v_lshrrev_b32_e32 v47, 16, v12
	v_lshrrev_b32_e32 v18, 16, v18
	v_add3_u32 v42, v48, v77, s41
	v_add3_u32 v35, v35, v79, s41
	v_add3_u32 v41, v41, v81, s41
	v_add3_u32 v46, v49, v85, s41
	v_lshrrev_b32_e32 v48, 16, v15
	v_lshrrev_b32_e32 v49, 16, v13
	v_lshrrev_b32_e32 v19, 16, v19
	v_lshrrev_b32_e32 v23, 16, v23
	v_lshrrev_b32_e32 v25, 16, v25
	v_lshrrev_b32_e32 v27, 16, v27
	v_lshrrev_b32_e32 v36, 16, v36
	v_lshrrev_b32_e32 v40, 16, v40
	v_lshrrev_b32_e32 v37, 16, v37
	v_lshrrev_b32_e32 v39, 16, v39
	v_lshrrev_b32_e32 v43, 16, v43
	v_lshrrev_b32_e32 v45, 16, v45
	v_and_or_b32 v12, v3, s42, v1
	v_and_or_b32 v13, v14, s42, v6
	v_and_or_b32 v14, v16, s42, v47
	v_and_or_b32 v15, v20, s42, v18
	v_and_or_b32 v16, v22, s42, v48
	v_and_or_b32 v17, v17, s42, v49
	v_and_or_b32 v18, v21, s42, v19
	v_and_or_b32 v19, v24, s42, v23
	v_and_or_b32 v20, v26, s42, v25
	v_and_or_b32 v21, v34, s42, v27
	v_and_or_b32 v22, v38, s42, v36
	v_and_or_b32 v23, v42, s42, v40
	v_and_or_b32 v24, v35, s42, v37
	v_and_or_b32 v25, v41, s42, v39
	v_and_or_b32 v26, v44, s42, v43
	v_and_or_b32 v27, v46, s42, v45
	global_store_dwordx4 v[10:11], v[12:15], off nt
	global_store_dwordx4 v[28:29], v[16:19], off nt
	global_store_dwordx4 v[30:31], v[20:23], off nt
	global_store_dwordx4 v[32:33], v[24:27], off nt
	s_waitcnt lgkmcnt(0)
	s_cbranch_scc1 .LBB0_1722
	v_mov_b32_e32 v7, 0
	v_readlane_b32 s8, v247, 44
	v_mov_b32_e32 v1, v7
	v_readlane_b32 s9, v247, 45
	v_readlane_b32 s10, v247, 46
	v_readlane_b32 s11, v247, 47
	v_readlane_b32 s12, v247, 48
	v_readlane_b32 s13, v247, 49
	v_readlane_b32 s14, v247, 50
	v_readlane_b32 s15, v247, 51
	v_readlane_b32 s16, v247, 52
	v_readlane_b32 s17, v247, 53
	v_readlane_b32 s18, v247, 54
	v_readlane_b32 s19, v247, 55
	v_readlane_b32 s20, v247, 56
	v_readlane_b32 s21, v247, 57
	v_readlane_b32 s22, v247, 58
	v_readlane_b32 s23, v247, 59
	s_mov_b32 s5, 0
	s_mov_b32 s7, 0xb000
	v_lshl_add_u64 v[8:9], s[22:23], 0, v[0:1]
	s_mov_b32 s8, 0x16000
	s_mov_b32 s9, 0x21000
	s_mov_b32 s10, 0x2c000
	s_mov_b32 s11, 0x37000
	s_mov_b32 s12, 0x42000
	s_mov_b32 s13, 0x4d000
	s_mov_b32 s14, 0x58000
	s_mov_b32 s15, 0x63000
	s_mov_b32 s16, 0x6e000
	s_mov_b32 s17, 0x79000
	s_mov_b32 s18, 0x84000
	s_mov_b32 s19, 0x8f000
	s_mov_b32 s20, 0x9a000
	s_mov_b32 s21, 0xa5000
	s_mov_b32 s22, 0xb0000
	s_mov_b32 s23, 0xbb000
	s_mov_b32 s24, 0xc6000
	s_mov_b32 s25, 0xd1000
	s_mov_b32 s26, 0xdc000
	s_mov_b32 s27, 0xe7000
	s_mov_b32 s28, 0xf2000
	s_mov_b32 s29, 0xfd000
	s_mov_b32 s30, 0x108000
	s_mov_b32 s31, 0x113000
	s_mov_b32 s34, 0x11e000
	s_mov_b32 s35, 0x129000
	s_mov_b32 s38, 0x134000
	s_mov_b32 s39, 0x13f000
	s_mov_b32 s40, 0x14a000
	s_mov_b32 s41, 0x155000
	s_movk_i32 s42, 0x7fff
	s_mov_b32 s43, 0xffff0000
	s_mov_b32 s44, 0x80000
	s_mov_b32 s45, 0x88000
	s_mov_b32 s46, 0x90000
; #define LAS __attribute__((address_space(3)))
; __device__ __forceinline__ void transpose_item(const float* W, int K, int Nsrc, int c0, bf16_t* WT, int mode, LAS float* scr, int kb, int nb, int lane) {
;     const int k0 = 64 * kb, n0 = 32 * nb;
;     float tv[32];
; #pragma unroll
;     for (int i = 0; i < 32; ++i) { const int kk = 2 * i + (lane >> 5); tv[i] = W[(size_t)(k0 + kk) * Nsrc + c0 + n0 + (lane & 31)]; }
; #pragma unroll
;     for (int i = 0; i < 32; ++i) { const int kk = 2 * i + (lane >> 5); scr[kk * 33 + (lane & 31)] = tv[i]; }
;     ...
;         const int nn = n0 + n; const int row = (mode == 0) ? nn : ((nn >> 7) * 256 + (nn & 127) + (mode == 2 ? 128 : 0));
;         *(u32x4*)(WT + (size_t)row * K + k0 + 8 * c) = o; }
.LBB0_1724:
	s_and_b32 s0, s6, 0xffff
	s_mul_i32 s0, s0, 0xba2f
	s_lshr_b32 s0, s0, 23
	s_mul_i32 s1, s0, 0xb0
	s_sub_i32 s1, s6, s1
	s_and_b32 s1, s1, 0xffff
	v_lshl_or_b32 v6, s0, 6, v66
	s_lshl_b32 s4, s1, 7
	v_mul_u32_u24_e32 v6, 0x5800, v6
	v_lshl_add_u64 v[10:11], v[8:9], 0, s[4:5]
	v_lshl_add_u64 v[16:17], v[10:11], 0, v[6:7]
	v_add_co_u32_e32 v12, vcc, s7, v16
	s_lshl_b32 s47, s1, 5
	s_nop 0
	v_addc_co_u32_e32 v13, vcc, 0, v17, vcc
	v_add_co_u32_e32 v18, vcc, s8, v16
	s_lshl_b32 s1, s1, 6
	s_nop 0
	v_addc_co_u32_e32 v19, vcc, 0, v17, vcc
	s_lshl_b32 s4, s0, 7
	s_and_b32 s0, s1, 0x3f00
	s_and_b32 s1, s47, 0x60
	v_add_co_u32_e32 v20, vcc, s9, v16
	s_or_b32 s0, s0, s1
	s_nop 0
	v_addc_co_u32_e32 v21, vcc, 0, v17, vcc
	v_or_b32_e32 v6, s0, v68
	v_add_co_u32_e32 v24, vcc, s10, v16
	v_lshl_add_u64 v[10:11], v[4:5], 0, s[4:5]
	v_lshlrev_b32_e32 v6, 12, v6
	v_addc_co_u32_e32 v25, vcc, 0, v17, vcc
	global_load_dword v31, v[16:17], off nt
	global_load_dword v34, v[12:13], off nt
	v_lshl_add_u64 v[22:23], v[10:11], 0, v[6:7]
	global_load_dword v6, v[18:19], off nt
	global_load_dword v35, v[20:21], off nt
	v_add_co_u32_e32 v18, vcc, s11, v16
	v_add_co_u32_e64 v10, s[0:1], s44, v22
	s_nop 0
	v_addc_co_u32_e32 v19, vcc, 0, v17, vcc
	v_add_co_u32_e32 v20, vcc, s12, v16
	global_load_dword v36, v[24:25], off nt
	global_load_dword v37, v[18:19], off nt
	v_addc_co_u32_e32 v21, vcc, 0, v17, vcc
	v_add_co_u32_e32 v18, vcc, s13, v16
	v_addc_co_u32_e64 v11, s[0:1], 0, v23, s[0:1]
	s_nop 0
	v_addc_co_u32_e32 v19, vcc, 0, v17, vcc
	v_add_co_u32_e32 v24, vcc, s14, v16
	global_load_dword v38, v[20:21], off nt
	global_load_dword v39, v[18:19], off nt
	v_addc_co_u32_e32 v25, vcc, 0, v17, vcc
	v_add_co_u32_e32 v18, vcc, s15, v16
	v_add_co_u32_e64 v12, s[0:1], s45, v22
	s_nop 0
	v_addc_co_u32_e32 v19, vcc, 0, v17, vcc
	v_add_co_u32_e32 v20, vcc, s16, v16
	global_load_dword v40, v[24:25], off nt
	global_load_dword v41, v[18:19], off nt
	v_addc_co_u32_e32 v21, vcc, 0, v17, vcc
	v_add_co_u32_e32 v18, vcc, s17, v16
	v_add_u32_e32 v1, 0x400, v67
	s_nop 0
	v_addc_co_u32_e32 v19, vcc, 0, v17, vcc
	v_add_co_u32_e32 v24, vcc, s18, v16
	global_load_dword v42, v[20:21], off nt
	global_load_dword v43, v[18:19], off nt
	v_addc_co_u32_e32 v25, vcc, 0, v17, vcc
	v_add_co_u32_e32 v18, vcc, s19, v16
	v_add_u32_e32 v3, 0x800, v67
	s_nop 0
	v_addc_co_u32_e32 v19, vcc, 0, v17, vcc
	v_add_co_u32_e32 v20, vcc, s20, v16
	global_load_dword v44, v[24:25], off nt
	global_load_dword v45, v[18:19], off nt
	v_addc_co_u32_e32 v21, vcc, 0, v17, vcc
	v_add_co_u32_e32 v18, vcc, s21, v16
	v_add_u32_e32 v26, 0xc00, v67
	s_nop 0
	v_addc_co_u32_e32 v19, vcc, 0, v17, vcc
	v_add_co_u32_e32 v24, vcc, s22, v16
	global_load_dword v46, v[20:21], off nt
	global_load_dword v47, v[18:19], off nt
	v_addc_co_u32_e32 v25, vcc, 0, v17, vcc
	v_add_co_u32_e32 v18, vcc, s23, v16
	v_add_u32_e32 v27, 0x1000, v67
	s_nop 0
	v_addc_co_u32_e32 v19, vcc, 0, v17, vcc
	v_add_co_u32_e32 v20, vcc, s24, v16
	global_load_dword v48, v[24:25], off nt
	global_load_dword v49, v[18:19], off nt
	v_addc_co_u32_e32 v21, vcc, 0, v17, vcc
	v_add_co_u32_e32 v18, vcc, s25, v16
	v_add_u32_e32 v28, 0x1400, v67
	s_nop 0
	v_addc_co_u32_e32 v19, vcc, 0, v17, vcc
	v_add_co_u32_e32 v24, vcc, s26, v16
	global_load_dword v50, v[20:21], off nt
	global_load_dword v51, v[18:19], off nt
	v_addc_co_u32_e32 v25, vcc, 0, v17, vcc
	v_add_co_u32_e32 v18, vcc, s27, v16
	v_add_u32_e32 v29, 0x1800, v67
	s_nop 0
	v_addc_co_u32_e32 v19, vcc, 0, v17, vcc
	v_add_co_u32_e32 v20, vcc, s28, v16
	global_load_dword v52, v[24:25], off nt
	global_load_dword v53, v[18:19], off nt
	v_addc_co_u32_e32 v21, vcc, 0, v17, vcc
	v_add_co_u32_e32 v18, vcc, s29, v16
	v_add_u32_e32 v30, 0x1c00, v67
	s_nop 0
	v_addc_co_u32_e32 v19, vcc, 0, v17, vcc
	v_add_co_u32_e32 v24, vcc, s30, v16
	global_load_dword v54, v[20:21], off nt
	global_load_dword v55, v[18:19], off nt
	v_addc_co_u32_e32 v25, vcc, 0, v17, vcc
	v_add_co_u32_e32 v18, vcc, s31, v16
	v_addc_co_u32_e64 v13, s[0:1], 0, v23, s[0:1]
	s_nop 0
	v_addc_co_u32_e32 v19, vcc, 0, v17, vcc
	v_add_co_u32_e32 v20, vcc, s34, v16
	global_load_dword v56, v[24:25], off nt
	global_load_dword v57, v[18:19], off nt
	v_addc_co_u32_e32 v21, vcc, 0, v17, vcc
	v_add_co_u32_e32 v18, vcc, s35, v16
	v_add_co_u32_e64 v14, s[0:1], s46, v22
	s_nop 0
	v_addc_co_u32_e32 v19, vcc, 0, v17, vcc
	v_add_co_u32_e32 v24, vcc, s38, v16
	global_load_dword v58, v[20:21], off nt
	global_load_dword v59, v[18:19], off nt
	v_addc_co_u32_e32 v25, vcc, 0, v17, vcc
	v_add_co_u32_e32 v18, vcc, s39, v16
	v_addc_co_u32_e64 v15, s[0:1], 0, v23, s[0:1]
	s_nop 0
	v_addc_co_u32_e32 v19, vcc, 0, v17, vcc
	v_add_co_u32_e32 v20, vcc, s40, v16
	global_load_dword v24, v[24:25], off nt
	s_nop 0
	global_load_dword v18, v[18:19], off nt
	v_addc_co_u32_e32 v21, vcc, 0, v17, vcc
	v_add_co_u32_e32 v16, vcc, s41, v16
	s_add_i32 s0, s6, 0x300
	s_nop 0
	v_addc_co_u32_e32 v17, vcc, 0, v17, vcc
	global_load_dword v19, v[20:21], off nt
	s_nop 0
	global_load_dword v16, v[16:17], off nt
	s_waitcnt vmcnt(30)
	ds_write2_b32 v67, v31, v34 offset1:66
	s_waitcnt vmcnt(28)
	ds_write2_b32 v67, v6, v35 offset0:132 offset1:198
	s_waitcnt vmcnt(26)
	ds_write2_b32 v1, v36, v37 offset0:8 offset1:74
	s_waitcnt vmcnt(24)
	ds_write2_b32 v1, v38, v39 offset0:140 offset1:206
	s_waitcnt vmcnt(22)
	ds_write2_b32 v3, v40, v41 offset0:16 offset1:82
	s_waitcnt vmcnt(20)
	ds_write2_b32 v3, v42, v43 offset0:148 offset1:214
	s_waitcnt vmcnt(18)
	ds_write2_b32 v26, v44, v45 offset0:24 offset1:90
	s_waitcnt vmcnt(16)
	ds_write2_b32 v26, v46, v47 offset0:156 offset1:222
	s_waitcnt vmcnt(14)
; #define LAS __attribute__((address_space(3)))
; __device__ __forceinline__ unsigned pk2(float lo, float hi) { return f2bf(lo) | (f2bf(hi) << 16); }
; __device__ __forceinline__ void transpose_item(const float* W, int K, int Nsrc, int c0, bf16_t* WT, int mode, LAS float* scr, int kb, int nb, int lane) {
;     ...
;     for (int i = 0; i < 32; ++i) { const int kk = 2 * i + (lane >> 5); scr[kk * 33 + (lane & 31)] = tv[i]; }
;     asm volatile("s_waitcnt lgkmcnt(0)" ::: "memory");
;     const int c = lane & 7;
; #pragma unroll
;     for (int j = 0; j < 4; ++j) { const int n = (lane >> 3) + 8 * j; const LAS float* s = scr + (8 * c) * 33 + n;
;         u32x4 o; o.x = pk2(s[0 * 33], s[1 * 33]); o.y = pk2(s[2 * 33], s[3 * 33]); o.z = pk2(s[4 * 33], s[5 * 33]); o.w = pk2(s[6 * 33], s[7 * 33]);
;         const int nn = n0 + n; const int row = (mode == 0) ? nn : ((nn >> 7) * 256 + (nn & 127) + (mode == 2 ? 128 : 0));
;         *(u32x4*)(WT + (size_t)row * K + k0 + 8 * c) = o; }
	ds_write2_b32 v27, v48, v49 offset0:32 offset1:98
	s_waitcnt vmcnt(12)
	ds_write2_b32 v27, v50, v51 offset0:164 offset1:230
	s_waitcnt vmcnt(10)
	ds_write2_b32 v28, v52, v53 offset0:40 offset1:106
	s_waitcnt vmcnt(8)
	ds_write2_b32 v28, v54, v55 offset0:172 offset1:238
	s_waitcnt vmcnt(6)
	ds_write2_b32 v29, v56, v57 offset0:48 offset1:114
	s_waitcnt vmcnt(4)
	ds_write2_b32 v29, v58, v59 offset0:180 offset1:246
	s_waitcnt vmcnt(2)
	ds_write2_b32 v30, v24, v18 offset0:56 offset1:122
	s_waitcnt vmcnt(0)
	ds_write2_b32 v30, v19, v16 offset0:188 offset1:254
	v_add_co_u32_e32 v32, vcc, 0x98000, v22
	s_waitcnt lgkmcnt(0)
	s_cmpk_lt_u32 s6, 0x1300
	s_nop 0
	v_addc_co_u32_e32 v33, vcc, 0, v23, vcc
	ds_read2_b32 v[16:17], v69 offset0:33 offset1:41
	ds_read2_b32 v[18:19], v69 offset1:8
	ds_read2_b32 v[20:21], v69 offset0:66 offset1:74
	ds_read2_b32 v[22:23], v69 offset0:99 offset1:107
	ds_read2_b32 v[24:25], v69 offset0:132 offset1:140
	ds_read2_b32 v[26:27], v69 offset0:165 offset1:173
	ds_read2_b32 v[28:29], v69 offset0:198 offset1:206
	ds_read2_b32 v[30:31], v69 offset0:231 offset1:239
	ds_read2_b32 v[34:35], v69 offset0:49 offset1:57
	ds_read2_b32 v[36:37], v69 offset0:16 offset1:24
	ds_read2_b32 v[38:39], v69 offset0:82 offset1:90
	ds_read2_b32 v[40:41], v69 offset0:115 offset1:123
	ds_read2_b32 v[42:43], v69 offset0:148 offset1:156
	ds_read2_b32 v[44:45], v69 offset0:181 offset1:189
	ds_read2_b32 v[46:47], v69 offset0:214 offset1:222
	ds_read2_b32 v[48:49], v69 offset0:247 offset1:255
	s_waitcnt lgkmcnt(14)
	v_bfe_u32 v1, v18, 16, 1
	v_bfe_u32 v3, v16, 16, 1
	s_waitcnt lgkmcnt(13)
	v_bfe_u32 v6, v20, 16, 1
	s_waitcnt lgkmcnt(12)
	v_bfe_u32 v50, v22, 16, 1
	s_waitcnt lgkmcnt(11)
	v_bfe_u32 v51, v24, 16, 1
	s_waitcnt lgkmcnt(9)
	v_bfe_u32 v53, v28, 16, 1
	v_bfe_u32 v52, v26, 16, 1
	s_waitcnt lgkmcnt(8)
	v_bfe_u32 v54, v30, 16, 1
	v_bfe_u32 v55, v19, 16, 1
	v_bfe_u32 v56, v17, 16, 1
	v_bfe_u32 v57, v21, 16, 1
	v_bfe_u32 v58, v23, 16, 1
	v_bfe_u32 v59, v25, 16, 1
	v_bfe_u32 v60, v27, 16, 1
	v_bfe_u32 v61, v29, 16, 1
	v_bfe_u32 v62, v31, 16, 1
	s_waitcnt lgkmcnt(6)
	v_bfe_u32 v63, v36, 16, 1
	v_bfe_u32 v64, v34, 16, 1
	s_waitcnt lgkmcnt(5)
	v_bfe_u32 v65, v38, 16, 1
	s_waitcnt lgkmcnt(4)
	v_bfe_u32 v73, v40, 16, 1
	s_waitcnt lgkmcnt(3)
	v_bfe_u32 v74, v42, 16, 1
	s_waitcnt lgkmcnt(2)
	v_bfe_u32 v75, v44, 16, 1
	s_waitcnt lgkmcnt(1)
	v_bfe_u32 v76, v46, 16, 1
	v_bfe_u32 v78, v37, 16, 1
	v_bfe_u32 v80, v39, 16, 1
	v_bfe_u32 v82, v43, 16, 1
	v_bfe_u32 v83, v45, 16, 1
	v_bfe_u32 v84, v47, 16, 1
	v_add3_u32 v1, v18, v1, s42
	v_add3_u32 v3, v16, v3, s42
	v_add3_u32 v6, v20, v6, s42
	v_add3_u32 v18, v22, v50, s42
	v_add3_u32 v16, v24, v51, s42
	v_add3_u32 v22, v28, v53, s42
	s_waitcnt lgkmcnt(0)
	v_bfe_u32 v77, v48, 16, 1
	v_bfe_u32 v79, v35, 16, 1
	v_bfe_u32 v81, v41, 16, 1
	v_bfe_u32 v85, v49, 16, 1
	v_add3_u32 v20, v26, v52, s42
	v_add3_u32 v24, v30, v54, s42
	v_add3_u32 v19, v19, v55, s42
	v_add3_u32 v26, v17, v56, s42
	v_add3_u32 v17, v21, v57, s42
	v_add3_u32 v21, v23, v58, s42
	v_add3_u32 v23, v25, v59, s42
	v_add3_u32 v25, v27, v60, s42
	v_add3_u32 v27, v29, v61, s42
	v_add3_u32 v28, v31, v62, s42
	v_add3_u32 v29, v36, v63, s42
	v_add3_u32 v30, v34, v64, s42
	v_add3_u32 v31, v38, v65, s42
	v_add3_u32 v34, v40, v73, s42
	v_add3_u32 v36, v42, v74, s42
	v_add3_u32 v38, v44, v75, s42
	v_add3_u32 v40, v46, v76, s42
	v_add3_u32 v37, v37, v78, s42
	v_add3_u32 v39, v39, v80, s42
	v_add3_u32 v43, v43, v82, s42
	v_add3_u32 v44, v45, v83, s42
	v_add3_u32 v45, v47, v84, s42
	v_lshrrev_b32_e32 v1, 16, v1
	v_lshrrev_b32_e32 v6, 16, v6
	v_lshrrev_b32_e32 v47, 16, v16
	v_lshrrev_b32_e32 v22, 16, v22
	v_add3_u32 v42, v48, v77, s42
	v_add3_u32 v35, v35, v79, s42
	v_add3_u32 v41, v41, v81, s42
	v_add3_u32 v46, v49, v85, s42
	v_lshrrev_b32_e32 v48, 16, v19
	v_lshrrev_b32_e32 v49, 16, v17
	v_lshrrev_b32_e32 v23, 16, v23
	v_lshrrev_b32_e32 v27, 16, v27
	v_lshrrev_b32_e32 v29, 16, v29
	v_lshrrev_b32_e32 v31, 16, v31
	v_lshrrev_b32_e32 v36, 16, v36
	v_lshrrev_b32_e32 v40, 16, v40
	v_lshrrev_b32_e32 v37, 16, v37
	v_lshrrev_b32_e32 v39, 16, v39
	v_lshrrev_b32_e32 v43, 16, v43
	v_lshrrev_b32_e32 v45, 16, v45
	v_and_or_b32 v16, v3, s43, v1
	v_and_or_b32 v17, v18, s43, v6
	v_and_or_b32 v18, v20, s43, v47
	v_and_or_b32 v19, v24, s43, v22
	v_and_or_b32 v20, v26, s43, v48
	v_and_or_b32 v21, v21, s43, v49
	v_and_or_b32 v22, v25, s43, v23
	v_and_or_b32 v23, v28, s43, v27
	v_and_or_b32 v24, v30, s43, v29
	v_and_or_b32 v25, v34, s43, v31
	v_and_or_b32 v26, v38, s43, v36
	v_and_or_b32 v27, v42, s43, v40
	v_and_or_b32 v28, v35, s43, v37
	v_and_or_b32 v29, v41, s43, v39
	v_and_or_b32 v30, v44, s43, v43
	v_and_or_b32 v31, v46, s43, v45
	global_store_dwordx4 v[10:11], v[16:19], off nt
	global_store_dwordx4 v[12:13], v[20:23], off nt
	global_store_dwordx4 v[14:15], v[24:27], off nt
	global_store_dwordx4 v[32:33], v[28:31], off nt
	s_waitcnt lgkmcnt(0)
	s_mov_b32 s6, s0
	s_cbranch_scc1 .LBB0_1724
	v_mov_b32_e32 v1, 0
	v_mov_b32_e32 v3, v1
	s_add_i32 s4, s3, 0xfffffe00
	v_lshl_add_u64 v[2:3], s[92:93], 0, v[2:3]
	s_mov_b64 s[0:1], 0x5400000
	v_lshl_add_u64 v[2:3], v[2:3], 0, s[0:1]
	s_mul_hi_u32 s0, s4, 0xaaaaaaab
	s_lshr_b32 s0, s0, 9
	s_mulk_i32 s0, 0x300
	s_sub_i32 s1, s4, s0
	s_sub_i32 s0, s3, s0
	v_lshl_add_u64 v[4:5], s[72:73], 0, v[0:1]
	s_add_i32 s3, s0, 0xfffffb00
	s_lshl_b32 s4, s1, 5
	s_mov_b32 s1, 0
	s_movk_i32 s5, 0x7fff
	s_mov_b32 s6, 0xffff0000
; #define LAS __attribute__((address_space(3)))
; __device__ __forceinline__ void transpose_item(const float* W, int K, int Nsrc, int c0, bf16_t* WT, int mode, LAS float* scr, int kb, int nb, int lane) {
;     const int k0 = 64 * kb, n0 = 32 * nb;
;     float tv[32];
; #pragma unroll
;     for (int i = 0; i < 32; ++i) { const int kk = 2 * i + (lane >> 5); tv[i] = W[(size_t)(k0 + kk) * Nsrc + c0 + n0 + (lane & 31)]; }
; __device__ __forceinline__ void convert_layer1_rest_idle(const Ctx& F, int first_idle, int end_idle) {
;     ...
;     tr_job(F, base, P.in[40], 5632, 2048, 0, 2048, 0, (bf16_t*)(Wb + W_DN1), scr, gw, NGW);
.LBB0_1726:
	s_addk_i32 s3, 0x300
	s_and_b32 s8, s3, 0x7fffffc0
	s_and_b32 s7, s4, 0x7e0
	v_or_b32_e32 v0, s8, v66
	v_mov_b32_e32 v7, v1
	v_mov_b32_e32 v9, v1
	v_mov_b32_e32 v11, v1
	v_mov_b32_e32 v13, v1
	v_mov_b32_e32 v15, v1
	v_mov_b32_e32 v17, v1
	v_mov_b32_e32 v19, v1
	v_mov_b32_e32 v21, v1
	v_mov_b32_e32 v29, v1
	s_lshl_b32 s0, s7, 2
	v_or_b32_e32 v6, 2, v0
	v_or_b32_e32 v8, 4, v0
	v_or_b32_e32 v10, 6, v0
	v_or_b32_e32 v12, 8, v0
	v_or_b32_e32 v14, 10, v0
	v_or_b32_e32 v16, 12, v0
	v_or_b32_e32 v18, 14, v0
	v_or_b32_e32 v20, 16, v0
	v_or_b32_e32 v28, 24, v0
	v_mov_b32_e32 v23, v1
	v_mov_b32_e32 v25, v1
	v_mov_b32_e32 v27, v1
	v_mov_b32_e32 v31, v1
	v_mov_b32_e32 v33, v1
	v_mov_b32_e32 v35, v1
	v_mov_b32_e32 v37, v1
	v_mov_b32_e32 v39, v1
	v_mov_b32_e32 v41, v1
	v_mov_b32_e32 v43, v1
	v_mov_b32_e32 v45, v1
	v_mov_b32_e32 v47, v1
	v_mov_b32_e32 v49, v1
	v_mov_b32_e32 v51, v1
	v_mov_b32_e32 v53, v1
	v_mov_b32_e32 v55, v1
	v_mov_b32_e32 v57, v1
	v_mov_b32_e32 v59, v1
	v_mov_b32_e32 v61, v1
	v_mov_b32_e32 v63, v1
	v_mov_b32_e32 v65, v1
	v_or_b32_e32 v88, s7, v68
	v_lshl_add_u64 v[74:75], v[4:5], 0, s[0:1]
	s_lshl_b32 s0, s8, 1
	v_lshlrev_b64 v[76:77], 13, v[0:1]
	v_or_b32_e32 v22, 18, v0
	v_or_b32_e32 v24, 20, v0
	v_or_b32_e32 v26, 22, v0
	v_or_b32_e32 v30, 26, v0
	v_or_b32_e32 v32, 28, v0
	v_or_b32_e32 v34, 30, v0
	v_or_b32_e32 v36, 32, v0
	v_or_b32_e32 v38, 34, v0
	v_or_b32_e32 v40, 36, v0
	v_or_b32_e32 v42, 38, v0
	v_or_b32_e32 v44, 40, v0
	v_or_b32_e32 v46, 42, v0
	v_or_b32_e32 v48, 44, v0
	v_or_b32_e32 v50, 46, v0
	v_or_b32_e32 v52, 48, v0
	v_or_b32_e32 v54, 50, v0
	v_or_b32_e32 v56, 52, v0
	v_or_b32_e32 v58, 54, v0
	v_or_b32_e32 v60, 56, v0
	v_or_b32_e32 v62, 58, v0
	v_or_b32_e32 v64, 60, v0
	v_or_b32_e32 v0, 62, v0
	v_lshlrev_b64 v[6:7], 13, v[6:7]
	v_lshlrev_b64 v[8:9], 13, v[8:9]
	v_lshlrev_b64 v[10:11], 13, v[10:11]
	v_lshlrev_b64 v[12:13], 13, v[12:13]
	v_lshlrev_b64 v[14:15], 13, v[14:15]
	v_lshlrev_b64 v[16:17], 13, v[16:17]
	v_lshlrev_b64 v[18:19], 13, v[18:19]
	v_lshlrev_b64 v[20:21], 13, v[20:21]
	v_lshlrev_b64 v[28:29], 13, v[28:29]
	v_or_b32_e32 v89, s7, v70
	v_lshl_add_u64 v[78:79], v[2:3], 0, s[0:1]
	v_lshl_add_u64 v[76:77], v[74:75], 0, v[76:77]
	v_lshlrev_b64 v[22:23], 13, v[22:23]
	v_lshlrev_b64 v[24:25], 13, v[24:25]
	v_lshlrev_b64 v[26:27], 13, v[26:27]
	v_lshlrev_b64 v[30:31], 13, v[30:31]
	v_lshlrev_b64 v[32:33], 13, v[32:33]
	v_lshlrev_b64 v[34:35], 13, v[34:35]
	v_lshlrev_b64 v[36:37], 13, v[36:37]
	v_lshlrev_b64 v[38:39], 13, v[38:39]
	v_lshlrev_b64 v[40:41], 13, v[40:41]
	v_lshlrev_b64 v[42:43], 13, v[42:43]
	v_lshlrev_b64 v[44:45], 13, v[44:45]
	v_lshlrev_b64 v[46:47], 13, v[46:47]
	v_lshlrev_b64 v[48:49], 13, v[48:49]
	v_lshlrev_b64 v[50:51], 13, v[50:51]
	v_lshlrev_b64 v[52:53], 13, v[52:53]
	v_lshlrev_b64 v[54:55], 13, v[54:55]
	v_lshlrev_b64 v[56:57], 13, v[56:57]
	v_lshlrev_b64 v[58:59], 13, v[58:59]
	v_lshlrev_b64 v[60:61], 13, v[60:61]
	v_lshlrev_b64 v[62:63], 13, v[62:63]
	v_lshlrev_b64 v[64:65], 13, v[64:65]
	v_lshlrev_b64 v[80:81], 13, v[0:1]
	v_mul_u32_u24_e32 v0, 0x2c00, v88
	v_lshl_add_u64 v[6:7], v[74:75], 0, v[6:7]
	v_lshl_add_u64 v[8:9], v[74:75], 0, v[8:9]
	v_lshl_add_u64 v[10:11], v[74:75], 0, v[10:11]
	v_lshl_add_u64 v[12:13], v[74:75], 0, v[12:13]
	v_lshl_add_u64 v[14:15], v[74:75], 0, v[14:15]
	v_lshl_add_u64 v[16:17], v[74:75], 0, v[16:17]
	v_lshl_add_u64 v[18:19], v[74:75], 0, v[18:19]
	v_lshl_add_u64 v[20:21], v[74:75], 0, v[20:21]
	v_lshl_add_u64 v[28:29], v[74:75], 0, v[28:29]
	v_lshl_add_u64 v[22:23], v[74:75], 0, v[22:23]
	v_lshl_add_u64 v[24:25], v[74:75], 0, v[24:25]
	v_lshl_add_u64 v[26:27], v[74:75], 0, v[26:27]
	v_lshl_add_u64 v[30:31], v[74:75], 0, v[30:31]
	v_lshl_add_u64 v[32:33], v[74:75], 0, v[32:33]
	v_lshl_add_u64 v[34:35], v[74:75], 0, v[34:35]
	v_lshl_add_u64 v[36:37], v[74:75], 0, v[36:37]
	v_lshl_add_u64 v[38:39], v[74:75], 0, v[38:39]
	v_lshl_add_u64 v[40:41], v[74:75], 0, v[40:41]
	v_lshl_add_u64 v[42:43], v[74:75], 0, v[42:43]
	v_lshl_add_u64 v[44:45], v[74:75], 0, v[44:45]
	v_lshl_add_u64 v[46:47], v[74:75], 0, v[46:47]
	v_lshl_add_u64 v[48:49], v[74:75], 0, v[48:49]
	v_lshl_add_u64 v[50:51], v[74:75], 0, v[50:51]
	v_lshl_add_u64 v[52:53], v[74:75], 0, v[52:53]
	v_lshl_add_u64 v[54:55], v[74:75], 0, v[54:55]
	v_lshl_add_u64 v[56:57], v[74:75], 0, v[56:57]
	v_lshl_add_u64 v[58:59], v[74:75], 0, v[58:59]
	v_lshl_add_u64 v[60:61], v[74:75], 0, v[60:61]
	v_lshl_add_u64 v[62:63], v[74:75], 0, v[62:63]
	v_lshl_add_u64 v[64:65], v[74:75], 0, v[64:65]
	v_lshl_add_u64 v[74:75], v[74:75], 0, v[80:81]
	v_lshl_add_u64 v[80:81], v[78:79], 0, v[0:1]
	v_mul_u32_u24_e32 v0, 0x2c00, v89
	global_load_dword v88, v[76:77], off nt
	global_load_dword v89, v[6:7], off nt
	global_load_dword v92, v[8:9], off nt
	global_load_dword v93, v[10:11], off nt
	global_load_dword v94, v[12:13], off nt
	global_load_dword v95, v[14:15], off nt
	global_load_dword v96, v[16:17], off nt
	global_load_dword v97, v[18:19], off nt
	global_load_dword v98, v[20:21], off nt
	global_load_dword v99, v[22:23], off nt
	global_load_dword v100, v[24:25], off nt
	global_load_dword v101, v[26:27], off nt
	global_load_dword v102, v[28:29], off nt
	global_load_dword v103, v[30:31], off nt
	global_load_dword v104, v[32:33], off nt
	global_load_dword v6, v[34:35], off nt
	global_load_dword v7, v[36:37], off nt
	global_load_dword v8, v[38:39], off nt
	global_load_dword v9, v[40:41], off nt
	global_load_dword v10, v[42:43], off nt
	global_load_dword v11, v[44:45], off nt
	global_load_dword v12, v[46:47], off nt
	global_load_dword v13, v[48:49], off nt
	global_load_dword v14, v[50:51], off nt
	global_load_dword v15, v[52:53], off nt
	global_load_dword v16, v[54:55], off nt
	global_load_dword v17, v[56:57], off nt
	global_load_dword v18, v[58:59], off nt
	global_load_dword v19, v[60:61], off nt
	global_load_dword v20, v[62:63], off nt
	global_load_dword v21, v[64:65], off nt
	global_load_dword v28, v[74:75], off nt
	v_add_u32_e32 v73, 0x400, v67
	v_add_u32_e32 v82, 0x800, v67
	v_add_u32_e32 v83, 0xc00, v67
	v_add_u32_e32 v84, 0x1000, v67
	v_add_u32_e32 v85, 0x1400, v67
	v_add_u32_e32 v86, 0x1800, v67
	v_add_u32_e32 v87, 0x1c00, v67
	s_waitcnt vmcnt(30)
; #define LAS __attribute__((address_space(3)))
; __device__ __forceinline__ unsigned pk2(float lo, float hi) { return f2bf(lo) | (f2bf(hi) << 16); }
; __device__ __forceinline__ void transpose_item(const float* W, int K, int Nsrc, int c0, bf16_t* WT, int mode, LAS float* scr, int kb, int nb, int lane) {
;     ...
;     for (int i = 0; i < 32; ++i) { const int kk = 2 * i + (lane >> 5); scr[kk * 33 + (lane & 31)] = tv[i]; }
;     asm volatile("s_waitcnt lgkmcnt(0)" ::: "memory");
;     const int c = lane & 7;
; #pragma unroll
;     for (int j = 0; j < 4; ++j) { const int n = (lane >> 3) + 8 * j; const LAS float* s = scr + (8 * c) * 33 + n;
;         u32x4 o; o.x = pk2(s[0 * 33], s[1 * 33]); o.y = pk2(s[2 * 33], s[3 * 33]); o.z = pk2(s[4 * 33], s[5 * 33]); o.w = pk2(s[6 * 33], s[7 * 33]);
;         const int nn = n0 + n; const int row = (mode == 0) ? nn : ((nn >> 7) * 256 + (nn & 127) + (mode == 2 ? 128 : 0));
;         *(u32x4*)(WT + (size_t)row * K + k0 + 8 * c) = o; }
	ds_write2_b32 v67, v88, v89 offset1:66
	s_waitcnt vmcnt(28)
	ds_write2_b32 v67, v92, v93 offset0:132 offset1:198
	s_waitcnt vmcnt(26)
	ds_write2_b32 v73, v94, v95 offset0:8 offset1:74
	s_waitcnt vmcnt(24)
	ds_write2_b32 v73, v96, v97 offset0:140 offset1:206
	s_waitcnt vmcnt(22)
	ds_write2_b32 v82, v98, v99 offset0:16 offset1:82
	s_waitcnt vmcnt(20)
	ds_write2_b32 v82, v100, v101 offset0:148 offset1:214
	s_waitcnt vmcnt(18)
	ds_write2_b32 v83, v102, v103 offset0:24 offset1:90
	s_waitcnt vmcnt(16)
	ds_write2_b32 v83, v104, v6 offset0:156 offset1:222
	s_waitcnt vmcnt(14)
	ds_write2_b32 v84, v7, v8 offset0:32 offset1:98
	s_waitcnt vmcnt(12)
	ds_write2_b32 v84, v9, v10 offset0:164 offset1:230
	s_waitcnt vmcnt(10)
	ds_write2_b32 v85, v11, v12 offset0:40 offset1:106
	s_waitcnt vmcnt(8)
	ds_write2_b32 v85, v13, v14 offset0:172 offset1:238
	s_waitcnt vmcnt(6)
	ds_write2_b32 v86, v15, v16 offset0:48 offset1:114
	s_waitcnt vmcnt(4)
	ds_write2_b32 v86, v17, v18 offset0:180 offset1:246
	s_waitcnt vmcnt(2)
	ds_write2_b32 v87, v19, v20 offset0:56 offset1:122
	s_waitcnt vmcnt(0)
	ds_write2_b32 v87, v21, v28 offset0:188 offset1:254
	s_waitcnt lgkmcnt(0)
	v_or_b32_e32 v90, s7, v71
	ds_read2_b32 v[6:7], v69 offset0:33 offset1:41
	ds_read2_b32 v[8:9], v69 offset1:8
	ds_read2_b32 v[10:11], v69 offset0:66 offset1:74
	ds_read2_b32 v[12:13], v69 offset0:99 offset1:107
	ds_read2_b32 v[14:15], v69 offset0:132 offset1:140
	ds_read2_b32 v[16:17], v69 offset0:165 offset1:173
	ds_read2_b32 v[18:19], v69 offset0:198 offset1:206
	ds_read2_b32 v[20:21], v69 offset0:231 offset1:239
	ds_read2_b32 v[28:29], v69 offset0:16 offset1:24
	ds_read2_b32 v[30:31], v69 offset0:49 offset1:57
	ds_read2_b32 v[32:33], v69 offset0:82 offset1:90
	ds_read2_b32 v[34:35], v69 offset0:115 offset1:123
	ds_read2_b32 v[36:37], v69 offset0:148 offset1:156
	ds_read2_b32 v[38:39], v69 offset0:181 offset1:189
	ds_read2_b32 v[40:41], v69 offset0:214 offset1:222
	ds_read2_b32 v[42:43], v69 offset0:247 offset1:255
	v_or_b32_e32 v91, s7, v72
	v_lshl_add_u64 v[22:23], v[78:79], 0, v[0:1]
	v_mul_u32_u24_e32 v0, 0x2c00, v90
	v_lshl_add_u64 v[24:25], v[78:79], 0, v[0:1]
	v_mul_u32_u24_e32 v0, 0x2c00, v91
	v_lshl_add_u64 v[26:27], v[78:79], 0, v[0:1]
	s_waitcnt lgkmcnt(14)
	v_bfe_u32 v0, v8, 16, 1
	s_waitcnt lgkmcnt(13)
	v_bfe_u32 v45, v10, 16, 1
	s_waitcnt lgkmcnt(12)
	v_bfe_u32 v46, v12, 16, 1
	s_waitcnt lgkmcnt(11)
	v_bfe_u32 v47, v14, 16, 1
	s_waitcnt lgkmcnt(10)
	v_bfe_u32 v48, v16, 16, 1
	s_waitcnt lgkmcnt(9)
	v_bfe_u32 v49, v18, 16, 1
	v_bfe_u32 v44, v6, 16, 1
	s_waitcnt lgkmcnt(8)
	v_bfe_u32 v50, v20, 16, 1
	v_bfe_u32 v51, v9, 16, 1
	v_bfe_u32 v52, v7, 16, 1
	v_bfe_u32 v53, v11, 16, 1
	v_bfe_u32 v54, v13, 16, 1
	v_bfe_u32 v55, v15, 16, 1
	v_bfe_u32 v56, v17, 16, 1
	v_bfe_u32 v57, v19, 16, 1
	v_bfe_u32 v58, v21, 16, 1
	s_waitcnt lgkmcnt(7)
	v_bfe_u32 v59, v28, 16, 1
	s_waitcnt lgkmcnt(6)
	v_bfe_u32 v60, v30, 16, 1
	s_waitcnt lgkmcnt(5)
	v_bfe_u32 v61, v32, 16, 1
	s_waitcnt lgkmcnt(4)
	v_bfe_u32 v62, v34, 16, 1
	s_waitcnt lgkmcnt(3)
	v_bfe_u32 v63, v36, 16, 1
	s_waitcnt lgkmcnt(2)
	v_bfe_u32 v64, v38, 16, 1
	s_waitcnt lgkmcnt(1)
	v_bfe_u32 v65, v40, 16, 1
	v_bfe_u32 v74, v29, 16, 1
	v_bfe_u32 v76, v33, 16, 1
	v_bfe_u32 v78, v37, 16, 1
	v_bfe_u32 v82, v41, 16, 1
	v_add3_u32 v0, v8, v0, s5
	v_add3_u32 v8, v10, v45, s5
	v_add3_u32 v10, v12, v46, s5
	v_add3_u32 v12, v14, v47, s5
	v_add3_u32 v14, v16, v48, s5
	v_add3_u32 v16, v18, v49, s5
	s_waitcnt lgkmcnt(0)
	v_bfe_u32 v73, v42, 16, 1
	v_bfe_u32 v75, v31, 16, 1
	v_bfe_u32 v77, v35, 16, 1
	v_bfe_u32 v79, v39, 16, 1
	v_bfe_u32 v83, v43, 16, 1
	v_add3_u32 v6, v6, v44, s5
	v_add3_u32 v18, v20, v50, s5
	v_add3_u32 v9, v9, v51, s5
	v_add3_u32 v20, v7, v52, s5
	v_add3_u32 v7, v11, v53, s5
	v_add3_u32 v11, v13, v54, s5
	v_add3_u32 v13, v15, v55, s5
	v_add3_u32 v15, v17, v56, s5
	v_add3_u32 v17, v19, v57, s5
	v_add3_u32 v19, v21, v58, s5
	v_add3_u32 v21, v28, v59, s5
	v_add3_u32 v28, v30, v60, s5
	v_add3_u32 v30, v32, v61, s5
	v_add3_u32 v32, v34, v62, s5
	v_add3_u32 v34, v36, v63, s5
	v_add3_u32 v36, v38, v64, s5
	v_add3_u32 v38, v40, v65, s5
	v_add3_u32 v29, v29, v74, s5
	v_add3_u32 v33, v33, v76, s5
	v_add3_u32 v37, v37, v78, s5
	v_add3_u32 v41, v41, v82, s5
	v_lshrrev_b32_e32 v0, 16, v0
	v_lshrrev_b32_e32 v8, 16, v8
	v_lshrrev_b32_e32 v12, 16, v12
	v_lshrrev_b32_e32 v16, 16, v16
	v_add3_u32 v40, v42, v73, s5
	v_add3_u32 v31, v31, v75, s5
	v_add3_u32 v35, v35, v77, s5
	v_add3_u32 v39, v39, v79, s5
	v_add3_u32 v42, v43, v83, s5
	v_lshrrev_b32_e32 v43, 16, v9
	v_lshrrev_b32_e32 v44, 16, v7
	v_lshrrev_b32_e32 v13, 16, v13
	v_lshrrev_b32_e32 v17, 16, v17
	v_lshrrev_b32_e32 v21, 16, v21
	v_lshrrev_b32_e32 v30, 16, v30
	v_lshrrev_b32_e32 v34, 16, v34
	v_lshrrev_b32_e32 v38, 16, v38
	v_lshrrev_b32_e32 v29, 16, v29
	v_lshrrev_b32_e32 v33, 16, v33
	v_lshrrev_b32_e32 v37, 16, v37
	v_lshrrev_b32_e32 v41, 16, v41
	v_and_or_b32 v6, v6, s6, v0
	v_and_or_b32 v7, v10, s6, v8
	v_and_or_b32 v8, v14, s6, v12
	v_and_or_b32 v9, v18, s6, v16
	v_and_or_b32 v10, v20, s6, v43
	v_and_or_b32 v11, v11, s6, v44
	v_and_or_b32 v12, v15, s6, v13
	v_and_or_b32 v13, v19, s6, v17
	v_and_or_b32 v14, v28, s6, v21
	v_and_or_b32 v15, v32, s6, v30
	v_and_or_b32 v16, v36, s6, v34
	v_and_or_b32 v17, v40, s6, v38
	v_and_or_b32 v18, v31, s6, v29
	v_and_or_b32 v19, v35, s6, v33
	v_and_or_b32 v20, v39, s6, v37
	v_and_or_b32 v21, v42, s6, v41
	global_store_dwordx4 v[80:81], v[6:9], off nt
	global_store_dwordx4 v[22:23], v[10:13], off nt
	global_store_dwordx4 v[24:25], v[14:17], off nt
	global_store_dwordx4 v[26:27], v[18:21], off nt
	s_waitcnt lgkmcnt(0)
	s_addk_i32 s4, 0x6000
	s_cmpk_gt_u32 s3, 0x12ff
	s_cbranch_scc0 .LBB0_1726
